# v19: v17 + in every K-loop load segment the LDS-DMA loads are issued before the ds_reads
# speedup vs baseline: 1.0022x; 1.0022x over previous
; #define PG8_WAIT_V(n) asm volatile("s_waitcnt vmcnt(" #n ")" ::: "memory")
; #define PG8_WAIT_L(n) asm volatile("s_waitcnt lgkmcnt(" #n ")" ::: "memory")
; #define PG8_BAR __builtin_amdgcn_s_barrier()
; #define PG8_SCHED __builtin_amdgcn_sched_barrier(0)
;     ...
;             const char* a1 = cA + (size_t)(t + 1) * kstep;
;             const char* a2 = last ? nA : cA + (size_t)(t + 2) * kstep; const char* b2 = last ? nB : cB + (size_t)(t + 2) * kstep;
;             const char* a3 = a2 + kstep; const char* b3 = b2 + kstep;
;             if (last && has_next) S.a_ready(nxt);
;             if constexpr (SP2) {
;             PG8_LDB(B0, 0, 0); PG8_LDB(B1, 0, 1); PG8_SCHED; PG8_LDA(At, 0, 0); PG8_STAGE(PG8_SA(1, 1), a1 + hstepA, voffA);
;             PG8_WAIT_V(8); PG8_WAIT_L(0); PG8_BAR; PG8_MMA(0, 0, At, B0); PG8_MMA(0, 1, At, B1); PG8_BAR; PG8_SCHED;
;             if constexpr (!HALFU) PG8_LDA(At, 0, 1); PG8_STAGE(PG8_SB(0, 0), b2, voffB); PG8_STAGE(PG8_SB(0, 1), b2 + hstep, voffB); PG8_STAGE(PG8_SA(0, 0), a2, voffA);
;             PG8_WAIT_V(8); PG8_WAIT_L(0); PG8_BAR; if constexpr (!HALFU) { PG8_MMA(1, 0, At, B0); PG8_MMA(1, 1, At, B1); } PG8_BAR; PG8_SCHED;
.LBB0_317:
	s_add_u32 s98, s14, 0x80
	s_addc_u32 s99, s15, 0
	s_mov_b32 m0, s49
	s_nop 0
	global_load_lds_dwordx4 v252, s[98:99]
	s_mov_b32 m0, s50
	s_nop 0
	global_load_lds_dwordx4 v146, s[98:99]
	s_add_u32 s30, s14, 0x100
	s_addc_u32 s31, s15, 0
	s_cmp_eq_u32 s58, 28
	s_cselect_b32 s38, s23, s30
	s_cselect_b32 s39, s7, s31
	s_cselect_b32 s36, s55, s56
	s_cselect_b32 s37, s21, s57
	s_add_u32 s34, s38, 0x80
	s_addc_u32 s35, s39, 0
	s_add_u32 s14, s14, 0x80080
	s_addc_u32 s15, s15, 0
	s_add_i32 m0, s29, 0xc000
	s_nop 0
	global_load_lds_dwordx4 v252, s[14:15]
	s_add_i32 m0, s29, 0xe000
	s_nop 0
	global_load_lds_dwordx4 v146, s[14:15]
	ds_read_b128 v[128:131], v155
	ds_read_b128 v[132:135], v155 offset:1024
	ds_read_b128 v[164:167], v155 offset:2048
	ds_read_b128 v[168:171], v155 offset:3072
	ds_read_b128 v[172:175], v156
	ds_read_b128 v[176:179], v156 offset:1024
	ds_read_b128 v[180:183], v156 offset:2048
	ds_read_b128 v[184:187], v156 offset:3072
	ds_read_b128 v[188:191], v157
	ds_read_b128 v[192:195], v157 offset:1024
	ds_read_b128 v[196:199], v157 offset:2048
	ds_read_b128 v[200:203], v157 offset:3072
	ds_read_b128 v[204:207], v157 offset:4096
	ds_read_b128 v[208:211], v157 offset:5120
	ds_read_b128 v[212:215], v157 offset:6144
	ds_read_b128 v[216:219], v157 offset:7168
	s_waitcnt vmcnt(8)
	s_waitcnt lgkmcnt(0)
	s_barrier
	s_setprio 1
	s_waitcnt lgkmcnt(0)
	v_mfma_scale_f32_16x16x128_f8f6f4 v[124:127], v[128:135], v[188:195], v[124:127], v158, v158 op_sel_hi:[0,0,0]
	v_mfma_scale_f32_16x16x128_f8f6f4 v[120:123], v[164:171], v[188:195], v[120:123], v158, v158 op_sel_hi:[0,0,0]
	v_mfma_scale_f32_16x16x128_f8f6f4 v[108:111], v[128:135], v[196:203], v[108:111], v158, v158 op_sel_hi:[0,0,0]
	v_mfma_scale_f32_16x16x128_f8f6f4 v[104:107], v[164:171], v[196:203], v[104:107], v158, v158 op_sel_hi:[0,0,0]
	v_mfma_scale_f32_16x16x128_f8f6f4 v[136:139], v[128:135], v[204:211], v[92:95], v158, v158 op_sel_hi:[0,0,0]
	v_mfma_scale_f32_16x16x128_f8f6f4 v[220:223], v[164:171], v[204:211], v[88:91], v158, v158 op_sel_hi:[0,0,0]
	v_mfma_scale_f32_16x16x128_f8f6f4 v[224:227], v[128:135], v[212:219], v[76:79], v158, v158 op_sel_hi:[0,0,0]
	v_mfma_scale_f32_16x16x128_f8f6f4 v[228:231], v[164:171], v[212:219], v[72:75], v158, v158 op_sel_hi:[0,0,0]
	s_setprio 0
	s_setprio 1
	v_mfma_scale_f32_16x16x128_f8f6f4 v[116:119], v[172:179], v[188:195], v[116:119], v158, v158 op_sel_hi:[0,0,0]
	v_mfma_scale_f32_16x16x128_f8f6f4 v[112:115], v[180:187], v[188:195], v[112:115], v158, v158 op_sel_hi:[0,0,0]
	v_mfma_scale_f32_16x16x128_f8f6f4 v[100:103], v[172:179], v[196:203], v[100:103], v158, v158 op_sel_hi:[0,0,0]
	v_mfma_scale_f32_16x16x128_f8f6f4 v[96:99], v[180:187], v[196:203], v[96:99], v158, v158 op_sel_hi:[0,0,0]
	v_mfma_scale_f32_16x16x128_f8f6f4 v[188:191], v[172:179], v[204:211], v[84:87], v158, v158 op_sel_hi:[0,0,0]
	v_mfma_scale_f32_16x16x128_f8f6f4 v[192:195], v[180:187], v[204:211], v[80:83], v158, v158 op_sel_hi:[0,0,0]
	v_mfma_scale_f32_16x16x128_f8f6f4 v[196:199], v[172:179], v[212:219], v[68:71], v158, v158 op_sel_hi:[0,0,0]
	v_mfma_scale_f32_16x16x128_f8f6f4 v[200:203], v[180:187], v[212:219], v[64:67], v158, v158 op_sel_hi:[0,0,0]
	s_setprio 0
	s_barrier
	s_add_i32 s14, s53, s40
	s_mov_b32 m0, s14
	s_nop 1
	global_load_lds_dwordx4 v144, s[36:37]
	s_add_i32 m0, s14, 0x2000
	s_add_u32 s14, s36, 0x80000
	s_addc_u32 s15, s37, 0
	s_add_i32 s59, s54, s40
	global_load_lds_dwordx4 v148, s[36:37]
	s_mov_b32 m0, s59
	s_nop 0
	global_load_lds_dwordx4 v144, s[14:15]
	s_add_i32 m0, s59, 0x2000
	s_nop 0
	global_load_lds_dwordx4 v148, s[14:15]
	ds_read_b128 v[64:67], v157 offset:16384
	ds_read_b128 v[68:71], v157 offset:17408
	ds_read_b128 v[72:75], v157 offset:18432
	ds_read_b128 v[76:79], v157 offset:19456
	ds_read_b128 v[80:83], v157 offset:20480
	ds_read_b128 v[84:87], v157 offset:21504
	ds_read_b128 v[88:91], v157 offset:22528
	ds_read_b128 v[92:95], v157 offset:23552
	s_waitcnt vmcnt(4)
	s_waitcnt lgkmcnt(0)
	s_barrier
	s_setprio 1
	s_waitcnt lgkmcnt(0)
	v_mfma_scale_f32_16x16x128_f8f6f4 v[60:63], v[128:135], v[64:71], v[60:63], v158, v158 op_sel_hi:[0,0,0]
	v_mfma_scale_f32_16x16x128_f8f6f4 v[56:59], v[164:171], v[64:71], v[56:59], v158, v158 op_sel_hi:[0,0,0]
	v_mfma_scale_f32_16x16x128_f8f6f4 v[204:207], v[128:135], v[72:79], v[44:47], v158, v158 op_sel_hi:[0,0,0]
	v_mfma_scale_f32_16x16x128_f8f6f4 v[208:211], v[164:171], v[72:79], v[40:43], v158, v158 op_sel_hi:[0,0,0]
	v_mfma_scale_f32_16x16x128_f8f6f4 v[212:215], v[128:135], v[80:87], v[28:31], v158, v158 op_sel_hi:[0,0,0]
	v_mfma_scale_f32_16x16x128_f8f6f4 v[216:219], v[164:171], v[80:87], v[24:27], v158, v158 op_sel_hi:[0,0,0]
	v_mfma_scale_f32_16x16x128_f8f6f4 v[232:235], v[128:135], v[88:95], v[12:15], v158, v158 op_sel_hi:[0,0,0]
	v_mfma_scale_f32_16x16x128_f8f6f4 v[236:239], v[164:171], v[88:95], v[8:11], v158, v158 op_sel_hi:[0,0,0]
	s_setprio 0
	s_setprio 1
	v_mfma_scale_f32_16x16x128_f8f6f4 v[52:55], v[172:179], v[64:71], v[52:55], v158, v158 op_sel_hi:[0,0,0]
	v_mfma_scale_f32_16x16x128_f8f6f4 v[48:51], v[180:187], v[64:71], v[48:51], v158, v158 op_sel_hi:[0,0,0]
	v_mfma_scale_f32_16x16x128_f8f6f4 v[240:243], v[172:179], v[72:79], v[36:39], v158, v158 op_sel_hi:[0,0,0]
	v_mfma_scale_f32_16x16x128_f8f6f4 v[244:247], v[180:187], v[72:79], v[32:35], v158, v158 op_sel_hi:[0,0,0]
	v_mfma_scale_f32_16x16x128_f8f6f4 v[248:251], v[172:179], v[80:87], v[20:23], v158, v158 op_sel_hi:[0,0,0]
	v_mfma_scale_f32_16x16x128_f8f6f4 v[150:153], v[180:187], v[80:87], v[16:19], v158, v158 op_sel_hi:[0,0,0]
	v_mfma_scale_f32_16x16x128_f8f6f4 v[160:163], v[172:179], v[88:95], v[4:7], v158, v158 op_sel_hi:[0,0,0]
	v_mfma_scale_f32_16x16x128_f8f6f4 v[140:143], v[180:187], v[88:95], v[0:3], v158, v158 op_sel_hi:[0,0,0]
	s_setprio 0
	s_barrier
; #define PG8_WAIT_V(n) asm volatile("s_waitcnt vmcnt(" #n ")" ::: "memory")
; #define PG8_WAIT_L(n) asm volatile("s_waitcnt lgkmcnt(" #n ")" ::: "memory")
; #define PG8_BAR __builtin_amdgcn_s_barrier()
; #define PG8_SCHED __builtin_amdgcn_sched_barrier(0)
;     ...
;             PG8_LDB(B0, 1, 0); PG8_LDB(B1, 1, 1); PG8_SCHED; PG8_LDA(At, 1, 0); PG8_STAGE(PG8_SA(0, 1), a2 + hstepA, voffA);
;             PG8_WAIT_V(8); PG8_WAIT_L(0); PG8_BAR; PG8_MMA(0, 0, At, B0); PG8_MMA(0, 1, At, B1); PG8_BAR; PG8_SCHED;
;             if constexpr (!HALFU) PG8_LDA(At, 1, 1); PG8_STAGE(PG8_SB(1, 0), b3, voffB); PG8_STAGE(PG8_SB(1, 1), b3 + hstep, voffB); PG8_STAGE(PG8_SA(1, 0), a3, voffA);
;             PG8_WAIT_V(8); PG8_WAIT_L(0); PG8_BAR; if constexpr (!HALFU) { PG8_MMA(1, 0, At, B0); PG8_MMA(1, 1, At, B1); } PG8_BAR; PG8_SCHED;
	s_mov_b32 m0, s29
	s_nop 0
	global_load_lds_dwordx4 v252, s[38:39]
	s_mov_b32 m0, s41
	s_nop 0
	global_load_lds_dwordx4 v146, s[38:39]
	s_add_i32 s59, 0, 0x18000
	s_add_i32 s60, 0, 0x1c000
	s_nop 1
	s_add_u32 s14, s38, 0x80000
	s_addc_u32 s15, s39, 0
	s_mov_b32 m0, s42
	s_nop 0
	global_load_lds_dwordx4 v252, s[14:15]
	s_mov_b32 m0, s43
	s_nop 0
	global_load_lds_dwordx4 v146, s[14:15]
	v_add_u32_e32 v8, s59, v154
	ds_read_b128 v[0:3], v8
	ds_read_b128 v[4:7], v8 offset:1024
	ds_read_b128 v[16:19], v8 offset:2048
	ds_read_b128 v[20:23], v8 offset:3072
	v_add_u32_e32 v8, s60, v154
	ds_read_b128 v[128:131], v8
	ds_read_b128 v[132:135], v8 offset:1024
	ds_read_b128 v[164:167], v8 offset:2048
	ds_read_b128 v[168:171], v8 offset:3072
	ds_read_b128 v[8:11], v157 offset:32768
	ds_read_b128 v[12:15], v157 offset:33792
	ds_read_b128 v[24:27], v157 offset:34816
	ds_read_b128 v[28:31], v157 offset:35840
	ds_read_b128 v[32:35], v157 offset:36864
	ds_read_b128 v[36:39], v157 offset:37888
	ds_read_b128 v[40:43], v157 offset:38912
	ds_read_b128 v[44:47], v157 offset:39936
	s_waitcnt vmcnt(8)
	s_waitcnt lgkmcnt(0)
	s_barrier
	s_setprio 1
	s_waitcnt lgkmcnt(0)
	v_mfma_scale_f32_16x16x128_f8f6f4 v[124:127], v[0:7], v[8:15], v[124:127], v158, v158 op_sel_hi:[0,0,0]
	v_mfma_scale_f32_16x16x128_f8f6f4 v[120:123], v[16:23], v[8:15], v[120:123], v158, v158 op_sel_hi:[0,0,0]
	v_mfma_scale_f32_16x16x128_f8f6f4 v[108:111], v[0:7], v[24:31], v[108:111], v158, v158 op_sel_hi:[0,0,0]
	v_mfma_scale_f32_16x16x128_f8f6f4 v[104:107], v[16:23], v[24:31], v[104:107], v158, v158 op_sel_hi:[0,0,0]
	v_mfma_scale_f32_16x16x128_f8f6f4 v[92:95], v[0:7], v[32:39], v[136:139], v158, v158 op_sel_hi:[0,0,0]
	v_mfma_scale_f32_16x16x128_f8f6f4 v[88:91], v[16:23], v[32:39], v[220:223], v158, v158 op_sel_hi:[0,0,0]
	v_mfma_scale_f32_16x16x128_f8f6f4 v[76:79], v[0:7], v[40:47], v[224:227], v158, v158 op_sel_hi:[0,0,0]
	v_mfma_scale_f32_16x16x128_f8f6f4 v[72:75], v[16:23], v[40:47], v[228:231], v158, v158 op_sel_hi:[0,0,0]
	s_setprio 0
	s_setprio 1
	v_mfma_scale_f32_16x16x128_f8f6f4 v[116:119], v[128:135], v[8:15], v[116:119], v158, v158 op_sel_hi:[0,0,0]
	v_mfma_scale_f32_16x16x128_f8f6f4 v[112:115], v[164:171], v[8:15], v[112:115], v158, v158 op_sel_hi:[0,0,0]
	v_mfma_scale_f32_16x16x128_f8f6f4 v[100:103], v[128:135], v[24:31], v[100:103], v158, v158 op_sel_hi:[0,0,0]
	v_mfma_scale_f32_16x16x128_f8f6f4 v[96:99], v[164:171], v[24:31], v[96:99], v158, v158 op_sel_hi:[0,0,0]
	v_mfma_scale_f32_16x16x128_f8f6f4 v[84:87], v[128:135], v[32:39], v[188:191], v158, v158 op_sel_hi:[0,0,0]
	v_mfma_scale_f32_16x16x128_f8f6f4 v[80:83], v[164:171], v[32:39], v[192:195], v158, v158 op_sel_hi:[0,0,0]
	v_mfma_scale_f32_16x16x128_f8f6f4 v[68:71], v[128:135], v[40:47], v[196:199], v158, v158 op_sel_hi:[0,0,0]
	v_mfma_scale_f32_16x16x128_f8f6f4 v[64:67], v[164:171], v[40:47], v[200:203], v158, v158 op_sel_hi:[0,0,0]
	s_setprio 0
	s_barrier
	s_add_u32 s14, s36, 0x80
	s_addc_u32 s15, s37, 0
	s_add_i32 s38, s59, s40
	s_mov_b32 m0, s38
	ds_read_b128 v[32:35], v157 offset:49152
	ds_read_b128 v[36:39], v157 offset:50176
	ds_read_b128 v[172:175], v157 offset:51200
	ds_read_b128 v[176:179], v157 offset:52224
	ds_read_b128 v[180:183], v157 offset:53248
	ds_read_b128 v[184:187], v157 offset:54272
	ds_read_b128 v[188:191], v157 offset:55296
	ds_read_b128 v[192:195], v157 offset:56320
	global_load_lds_dwordx4 v144, s[14:15]
	s_add_i32 m0, s38, 0x2000
	v_lshl_add_u64 v[8:9], s[14:15], 0, v[148:149]
	s_add_u32 s14, s36, 0x80080
	s_addc_u32 s15, s37, 0
	s_add_i32 s36, s60, s40
	global_load_lds_dwordx4 v[8:9], off
	s_mov_b32 m0, s36
	s_nop 0
	global_load_lds_dwordx4 v144, s[14:15]
	s_add_i32 m0, s36, 0x2000
	s_nop 0
	global_load_lds_dwordx4 v148, s[14:15]
	s_waitcnt vmcnt(4)
	s_waitcnt lgkmcnt(0)
	s_barrier
	s_setprio 1
	s_waitcnt lgkmcnt(0)
	v_mfma_scale_f32_16x16x128_f8f6f4 v[60:63], v[0:7], v[32:39], v[60:63], v158, v158 op_sel_hi:[0,0,0]
	v_mfma_scale_f32_16x16x128_f8f6f4 v[56:59], v[16:23], v[32:39], v[56:59], v158, v158 op_sel_hi:[0,0,0]
	v_mfma_scale_f32_16x16x128_f8f6f4 v[44:47], v[0:7], v[172:179], v[204:207], v158, v158 op_sel_hi:[0,0,0]
	v_mfma_scale_f32_16x16x128_f8f6f4 v[40:43], v[16:23], v[172:179], v[208:211], v158, v158 op_sel_hi:[0,0,0]
	v_mfma_scale_f32_16x16x128_f8f6f4 v[28:31], v[0:7], v[180:187], v[212:215], v158, v158 op_sel_hi:[0,0,0]
	v_mfma_scale_f32_16x16x128_f8f6f4 v[24:27], v[16:23], v[180:187], v[216:219], v158, v158 op_sel_hi:[0,0,0]
	v_mfma_scale_f32_16x16x128_f8f6f4 v[12:15], v[0:7], v[188:195], v[232:235], v158, v158 op_sel_hi:[0,0,0]
	v_mfma_scale_f32_16x16x128_f8f6f4 v[8:11], v[16:23], v[188:195], v[236:239], v158, v158 op_sel_hi:[0,0,0]
	s_setprio 0
	s_setprio 1
	v_mfma_scale_f32_16x16x128_f8f6f4 v[52:55], v[128:135], v[32:39], v[52:55], v158, v158 op_sel_hi:[0,0,0]
	v_mfma_scale_f32_16x16x128_f8f6f4 v[48:51], v[164:171], v[32:39], v[48:51], v158, v158 op_sel_hi:[0,0,0]
	v_mfma_scale_f32_16x16x128_f8f6f4 v[36:39], v[128:135], v[172:179], v[240:243], v158, v158 op_sel_hi:[0,0,0]
	v_mfma_scale_f32_16x16x128_f8f6f4 v[32:35], v[164:171], v[172:179], v[244:247], v158, v158 op_sel_hi:[0,0,0]
	v_mfma_scale_f32_16x16x128_f8f6f4 v[20:23], v[128:135], v[180:187], v[248:251], v158, v158 op_sel_hi:[0,0,0]
	v_mfma_scale_f32_16x16x128_f8f6f4 v[16:19], v[164:171], v[180:187], v[150:153], v158, v158 op_sel_hi:[0,0,0]
	v_mfma_scale_f32_16x16x128_f8f6f4 v[4:7], v[128:135], v[188:195], v[160:163], v158, v158 op_sel_hi:[0,0,0]
	v_mfma_scale_f32_16x16x128_f8f6f4 v[0:3], v[164:171], v[188:195], v[140:143], v158, v158 op_sel_hi:[0,0,0]
	s_setprio 0
	s_barrier
	s_add_i32 s58, s58, 2
	s_add_u32 s56, s56, 0x100
	s_addc_u32 s57, s57, 0
	s_cmp_gt_u32 s58, 29
	s_mov_b64 s[14:15], s[30:31]
	s_cbranch_scc0 .LBB0_317
	s_and_b64 vcc, exec, s[16:17]
	s_cbranch_vccz .LBB0_320
	s_barrier

; #define PG8_WAIT_V(n) asm volatile("s_waitcnt vmcnt(" #n ")" ::: "memory")
; #define PG8_WAIT_L(n) asm volatile("s_waitcnt lgkmcnt(" #n ")" ::: "memory")
; #define PG8_BAR __builtin_amdgcn_s_barrier()
; #define PG8_SCHED __builtin_amdgcn_sched_barrier(0)
;     ...
;             const char* a1 = cA + (size_t)(t + 1) * kstep;
;             const char* a2 = last ? nA : cA + (size_t)(t + 2) * kstep; const char* b2 = last ? nB : cB + (size_t)(t + 2) * kstep;
;             const char* a3 = a2 + kstep; const char* b3 = b2 + kstep;
;             if (last && has_next) S.a_ready(nxt);
;             if constexpr (SP2) {
;             PG8_LDB(B0, 0, 0); PG8_LDB(B1, 0, 1); PG8_SCHED; PG8_LDA(At, 0, 0); PG8_STAGE(PG8_SA(1, 1), a1 + hstepA, voffA);
;             PG8_WAIT_V(8); PG8_WAIT_L(0); PG8_BAR; PG8_MMA(0, 0, At, B0); PG8_MMA(0, 1, At, B1); PG8_BAR; PG8_SCHED;
;             if constexpr (!HALFU) PG8_LDA(At, 0, 1); PG8_STAGE(PG8_SB(0, 0), b2, voffB); PG8_STAGE(PG8_SB(0, 1), b2 + hstep, voffB); PG8_STAGE(PG8_SA(0, 0), a2, voffA);
;             PG8_WAIT_V(8); PG8_WAIT_L(0); PG8_BAR; if constexpr (!HALFU) { PG8_MMA(1, 0, At, B0); PG8_MMA(1, 1, At, B1); } PG8_BAR; PG8_SCHED;
.LBB0_542:
	s_add_u32 s98, s28, 0x80
	s_addc_u32 s99, s29, 0
	s_mov_b32 m0, s53
	s_nop 0
	global_load_lds_dwordx4 v128, s[98:99]
	s_mov_b32 m0, s54
	s_nop 0
	global_load_lds_dwordx4 v130, s[98:99]
	s_add_u32 s30, s28, 0x100
	s_addc_u32 s31, s29, 0
	s_cmp_eq_u32 s61, 12
	s_cselect_b32 s40, s57, s30
	s_cselect_b32 s41, s23, s31
	s_cselect_b32 s38, s58, s59
	s_cselect_b32 s39, s21, s60
	s_add_u32 s36, s40, 0x80
	s_addc_u32 s37, s41, 0
	s_add_u32 s28, s28, 0x40080
	s_addc_u32 s29, s29, 0
	s_add_i32 m0, s45, 0xc000
	s_nop 0
	global_load_lds_dwordx4 v128, s[28:29]
	s_add_i32 m0, s45, 0xe000
	s_nop 0
	global_load_lds_dwordx4 v130, s[28:29]
	ds_read_b128 v[142:145], v137
	ds_read_b128 v[146:149], v137 offset:1024
	ds_read_b128 v[150:153], v137 offset:2048
	ds_read_b128 v[154:157], v137 offset:3072
	ds_read_b128 v[158:161], v138
	ds_read_b128 v[162:165], v138 offset:1024
	ds_read_b128 v[166:169], v138 offset:2048
	ds_read_b128 v[170:173], v138 offset:3072
	ds_read_b128 v[174:177], v139
	ds_read_b128 v[178:181], v139 offset:1024
	ds_read_b128 v[182:185], v139 offset:2048
	ds_read_b128 v[186:189], v139 offset:3072
	ds_read_b128 v[190:193], v139 offset:4096
	ds_read_b128 v[194:197], v139 offset:5120
	ds_read_b128 v[198:201], v139 offset:6144
	ds_read_b128 v[202:205], v139 offset:7168
	s_waitcnt vmcnt(8)
	s_waitcnt lgkmcnt(0)
	s_barrier
	s_setprio 1
	s_waitcnt lgkmcnt(0)
	v_mfma_scale_f32_16x16x128_f8f6f4 v[124:127], v[142:149], v[174:181], v[124:127], v140, v140 op_sel_hi:[0,0,0]
	v_mfma_scale_f32_16x16x128_f8f6f4 v[120:123], v[150:157], v[174:181], v[120:123], v140, v140 op_sel_hi:[0,0,0]
	v_mfma_scale_f32_16x16x128_f8f6f4 v[108:111], v[142:149], v[182:189], v[108:111], v140, v140 op_sel_hi:[0,0,0]
	v_mfma_scale_f32_16x16x128_f8f6f4 v[104:107], v[150:157], v[182:189], v[104:107], v140, v140 op_sel_hi:[0,0,0]
	v_mfma_scale_f32_16x16x128_f8f6f4 v[96:99], v[142:149], v[190:197], v[96:99], v140, v140 op_sel_hi:[0,0,0]
	v_mfma_scale_f32_16x16x128_f8f6f4 v[206:209], v[150:157], v[190:197], v[88:91], v140, v140 op_sel_hi:[0,0,0]
	v_mfma_scale_f32_16x16x128_f8f6f4 v[210:213], v[142:149], v[198:205], v[80:83], v140, v140 op_sel_hi:[0,0,0]
	v_mfma_scale_f32_16x16x128_f8f6f4 v[214:217], v[150:157], v[198:205], v[72:75], v140, v140 op_sel_hi:[0,0,0]
	s_setprio 0
	s_setprio 1
	v_mfma_scale_f32_16x16x128_f8f6f4 v[116:119], v[158:165], v[174:181], v[116:119], v140, v140 op_sel_hi:[0,0,0]
	v_mfma_scale_f32_16x16x128_f8f6f4 v[112:115], v[166:173], v[174:181], v[112:115], v140, v140 op_sel_hi:[0,0,0]
	v_mfma_scale_f32_16x16x128_f8f6f4 v[100:103], v[158:165], v[182:189], v[100:103], v140, v140 op_sel_hi:[0,0,0]
	v_mfma_scale_f32_16x16x128_f8f6f4 v[174:177], v[166:173], v[182:189], v[92:95], v140, v140 op_sel_hi:[0,0,0]
	v_mfma_scale_f32_16x16x128_f8f6f4 v[178:181], v[158:165], v[190:197], v[84:87], v140, v140 op_sel_hi:[0,0,0]
	v_mfma_scale_f32_16x16x128_f8f6f4 v[182:185], v[166:173], v[190:197], v[76:79], v140, v140 op_sel_hi:[0,0,0]
	v_mfma_scale_f32_16x16x128_f8f6f4 v[186:189], v[158:165], v[198:205], v[68:71], v140, v140 op_sel_hi:[0,0,0]
	v_mfma_scale_f32_16x16x128_f8f6f4 v[190:193], v[166:173], v[198:205], v[64:67], v140, v140 op_sel_hi:[0,0,0]
	s_setprio 0
	s_barrier
	s_add_i32 s28, s55, s43
	s_mov_b32 m0, s28
	s_nop 1
	global_load_lds_dwordx4 v128, s[38:39]
	s_add_i32 m0, s28, 0x2000
	s_add_u32 s28, s38, 0x40000
	s_addc_u32 s29, s39, 0
	s_add_i32 s62, s56, s43
	global_load_lds_dwordx4 v130, s[38:39]
	s_mov_b32 m0, s62
	s_nop 0
	global_load_lds_dwordx4 v128, s[28:29]
	s_add_i32 m0, s62, 0x2000
	s_nop 0
	global_load_lds_dwordx4 v130, s[28:29]
	ds_read_b128 v[64:67], v139 offset:16384
	ds_read_b128 v[68:71], v139 offset:17408
	ds_read_b128 v[72:75], v139 offset:18432
	ds_read_b128 v[76:79], v139 offset:19456
	ds_read_b128 v[80:83], v139 offset:20480
	ds_read_b128 v[84:87], v139 offset:21504
	ds_read_b128 v[88:91], v139 offset:22528
	ds_read_b128 v[92:95], v139 offset:23552
	s_waitcnt vmcnt(4)
	s_waitcnt lgkmcnt(0)
	s_barrier
	s_setprio 1
	s_waitcnt lgkmcnt(0)
	v_mfma_scale_f32_16x16x128_f8f6f4 v[60:63], v[142:149], v[64:71], v[60:63], v140, v140 op_sel_hi:[0,0,0]
	v_mfma_scale_f32_16x16x128_f8f6f4 v[56:59], v[150:157], v[64:71], v[56:59], v140, v140 op_sel_hi:[0,0,0]
	v_mfma_scale_f32_16x16x128_f8f6f4 v[48:51], v[142:149], v[72:79], v[48:51], v140, v140 op_sel_hi:[0,0,0]
	v_mfma_scale_f32_16x16x128_f8f6f4 v[194:197], v[150:157], v[72:79], v[40:43], v140, v140 op_sel_hi:[0,0,0]
	v_mfma_scale_f32_16x16x128_f8f6f4 v[198:201], v[142:149], v[80:87], v[32:35], v140, v140 op_sel_hi:[0,0,0]
	v_mfma_scale_f32_16x16x128_f8f6f4 v[202:205], v[150:157], v[80:87], v[24:27], v140, v140 op_sel_hi:[0,0,0]
	v_mfma_scale_f32_16x16x128_f8f6f4 v[218:221], v[142:149], v[88:95], v[16:19], v140, v140 op_sel_hi:[0,0,0]
	v_mfma_scale_f32_16x16x128_f8f6f4 v[222:225], v[150:157], v[88:95], v[8:11], v140, v140 op_sel_hi:[0,0,0]
	s_setprio 0
	s_setprio 1
	v_mfma_scale_f32_16x16x128_f8f6f4 v[52:55], v[158:165], v[64:71], v[52:55], v140, v140 op_sel_hi:[0,0,0]
	v_mfma_scale_f32_16x16x128_f8f6f4 v[226:229], v[166:173], v[64:71], v[44:47], v140, v140 op_sel_hi:[0,0,0]
	v_mfma_scale_f32_16x16x128_f8f6f4 v[230:233], v[158:165], v[72:79], v[36:39], v140, v140 op_sel_hi:[0,0,0]
	v_mfma_scale_f32_16x16x128_f8f6f4 v[234:237], v[166:173], v[72:79], v[28:31], v140, v140 op_sel_hi:[0,0,0]
	v_mfma_scale_f32_16x16x128_f8f6f4 v[238:241], v[158:165], v[80:87], v[20:23], v140, v140 op_sel_hi:[0,0,0]
	v_mfma_scale_f32_16x16x128_f8f6f4 v[242:245], v[166:173], v[80:87], v[12:15], v140, v140 op_sel_hi:[0,0,0]
	v_mfma_scale_f32_16x16x128_f8f6f4 v[246:249], v[158:165], v[88:95], v[4:7], v140, v140 op_sel_hi:[0,0,0]
	v_mfma_scale_f32_16x16x128_f8f6f4 v[250:253], v[166:173], v[88:95], v[0:3], v140, v140 op_sel_hi:[0,0,0]
	s_setprio 0
	s_barrier
; #define PG8_WAIT_V(n) asm volatile("s_waitcnt vmcnt(" #n ")" ::: "memory")
; #define PG8_WAIT_L(n) asm volatile("s_waitcnt lgkmcnt(" #n ")" ::: "memory")
; #define PG8_BAR __builtin_amdgcn_s_barrier()
; #define PG8_SCHED __builtin_amdgcn_sched_barrier(0)
;     ...
;             PG8_LDB(B0, 1, 0); PG8_LDB(B1, 1, 1); PG8_SCHED; PG8_LDA(At, 1, 0); PG8_STAGE(PG8_SA(0, 1), a2 + hstepA, voffA);
;             PG8_WAIT_V(8); PG8_WAIT_L(0); PG8_BAR; PG8_MMA(0, 0, At, B0); PG8_MMA(0, 1, At, B1); PG8_BAR; PG8_SCHED;
;             if constexpr (!HALFU) PG8_LDA(At, 1, 1); PG8_STAGE(PG8_SB(1, 0), b3, voffB); PG8_STAGE(PG8_SB(1, 1), b3 + hstep, voffB); PG8_STAGE(PG8_SA(1, 0), a3, voffA);
;             PG8_WAIT_V(8); PG8_WAIT_L(0); PG8_BAR; if constexpr (!HALFU) { PG8_MMA(1, 0, At, B0); PG8_MMA(1, 1, At, B1); } PG8_BAR; PG8_SCHED;
	s_mov_b32 m0, s45
	s_nop 0
	global_load_lds_dwordx4 v128, s[40:41]
	s_mov_b32 m0, s46
	s_nop 0
	global_load_lds_dwordx4 v130, s[40:41]
	s_add_i32 s62, 0, 0x18000
	s_add_i32 s63, 0, 0x1c000
	s_nop 0
	s_add_u32 s28, s40, 0x40000
	s_addc_u32 s29, s41, 0
	s_mov_b32 m0, s47
	s_nop 0
	global_load_lds_dwordx4 v128, s[28:29]
	s_mov_b32 m0, s48
	s_nop 0
	global_load_lds_dwordx4 v130, s[28:29]
	v_add_u32_e32 v12, s62, v136
	v_add_u32_e32 v16, s63, v136
	ds_read_b128 v[0:3], v12
	ds_read_b128 v[4:7], v12 offset:1024
	ds_read_b128 v[8:11], v12 offset:2048
	ds_read_b128 v[12:15], v12 offset:3072
	ds_read_b128 v[142:145], v16
	ds_read_b128 v[146:149], v16 offset:1024
	ds_read_b128 v[150:153], v16 offset:2048
	ds_read_b128 v[154:157], v16 offset:3072
	ds_read_b128 v[16:19], v139 offset:32768
	ds_read_b128 v[20:23], v139 offset:33792
	ds_read_b128 v[24:27], v139 offset:34816
	ds_read_b128 v[28:31], v139 offset:35840
	ds_read_b128 v[32:35], v139 offset:36864
	ds_read_b128 v[36:39], v139 offset:37888
	ds_read_b128 v[40:43], v139 offset:38912
	ds_read_b128 v[44:47], v139 offset:39936
	s_waitcnt vmcnt(8)
	s_waitcnt lgkmcnt(0)
	s_barrier
	s_setprio 1
	s_waitcnt lgkmcnt(0)
	v_mfma_scale_f32_16x16x128_f8f6f4 v[124:127], v[0:7], v[16:23], v[124:127], v140, v140 op_sel_hi:[0,0,0]
	v_mfma_scale_f32_16x16x128_f8f6f4 v[120:123], v[8:15], v[16:23], v[120:123], v140, v140 op_sel_hi:[0,0,0]
	v_mfma_scale_f32_16x16x128_f8f6f4 v[108:111], v[0:7], v[24:31], v[108:111], v140, v140 op_sel_hi:[0,0,0]
	v_mfma_scale_f32_16x16x128_f8f6f4 v[104:107], v[8:15], v[24:31], v[104:107], v140, v140 op_sel_hi:[0,0,0]
	v_mfma_scale_f32_16x16x128_f8f6f4 v[96:99], v[0:7], v[32:39], v[96:99], v140, v140 op_sel_hi:[0,0,0]
	v_mfma_scale_f32_16x16x128_f8f6f4 v[88:91], v[8:15], v[32:39], v[206:209], v140, v140 op_sel_hi:[0,0,0]
	v_mfma_scale_f32_16x16x128_f8f6f4 v[80:83], v[0:7], v[40:47], v[210:213], v140, v140 op_sel_hi:[0,0,0]
	v_mfma_scale_f32_16x16x128_f8f6f4 v[72:75], v[8:15], v[40:47], v[214:217], v140, v140 op_sel_hi:[0,0,0]
	s_setprio 0
	s_setprio 1
	v_mfma_scale_f32_16x16x128_f8f6f4 v[116:119], v[142:149], v[16:23], v[116:119], v140, v140 op_sel_hi:[0,0,0]
	v_mfma_scale_f32_16x16x128_f8f6f4 v[112:115], v[150:157], v[16:23], v[112:115], v140, v140 op_sel_hi:[0,0,0]
	v_mfma_scale_f32_16x16x128_f8f6f4 v[100:103], v[142:149], v[24:31], v[100:103], v140, v140 op_sel_hi:[0,0,0]
	v_mfma_scale_f32_16x16x128_f8f6f4 v[92:95], v[150:157], v[24:31], v[174:177], v140, v140 op_sel_hi:[0,0,0]
	v_mfma_scale_f32_16x16x128_f8f6f4 v[84:87], v[142:149], v[32:39], v[178:181], v140, v140 op_sel_hi:[0,0,0]
	v_mfma_scale_f32_16x16x128_f8f6f4 v[76:79], v[150:157], v[32:39], v[182:185], v140, v140 op_sel_hi:[0,0,0]
	v_mfma_scale_f32_16x16x128_f8f6f4 v[68:71], v[142:149], v[40:47], v[186:189], v140, v140 op_sel_hi:[0,0,0]
	v_mfma_scale_f32_16x16x128_f8f6f4 v[64:67], v[150:157], v[40:47], v[190:193], v140, v140 op_sel_hi:[0,0,0]
	s_setprio 0
	s_barrier
	s_add_u32 s28, s38, 0x80
	s_addc_u32 s29, s39, 0
	s_add_i32 s40, s62, s43
	s_mov_b32 m0, s40
	ds_read_b128 v[158:161], v139 offset:49152
	ds_read_b128 v[162:165], v139 offset:50176
	ds_read_b128 v[166:169], v139 offset:51200
	ds_read_b128 v[170:173], v139 offset:52224
	ds_read_b128 v[174:177], v139 offset:53248
	ds_read_b128 v[178:181], v139 offset:54272
	ds_read_b128 v[182:185], v139 offset:55296
	ds_read_b128 v[186:189], v139 offset:56320
	global_load_lds_dwordx4 v128, s[28:29]
	s_add_i32 m0, s40, 0x2000
	v_lshl_add_u64 v[16:17], s[28:29], 0, v[130:131]
	s_add_u32 s28, s38, 0x40080
	s_addc_u32 s29, s39, 0
	s_add_i32 s38, s63, s43
	global_load_lds_dwordx4 v[16:17], off
	s_mov_b32 m0, s38
	s_nop 0
	global_load_lds_dwordx4 v128, s[28:29]
	s_add_i32 m0, s38, 0x2000
	s_nop 0
	global_load_lds_dwordx4 v130, s[28:29]
	s_waitcnt vmcnt(4)
	s_waitcnt lgkmcnt(0)
	s_barrier
	s_setprio 1
	s_waitcnt lgkmcnt(0)
	v_mfma_scale_f32_16x16x128_f8f6f4 v[60:63], v[0:7], v[158:165], v[60:63], v140, v140 op_sel_hi:[0,0,0]
	v_mfma_scale_f32_16x16x128_f8f6f4 v[56:59], v[8:15], v[158:165], v[56:59], v140, v140 op_sel_hi:[0,0,0]
	v_mfma_scale_f32_16x16x128_f8f6f4 v[48:51], v[0:7], v[166:173], v[48:51], v140, v140 op_sel_hi:[0,0,0]
	v_mfma_scale_f32_16x16x128_f8f6f4 v[40:43], v[8:15], v[166:173], v[194:197], v140, v140 op_sel_hi:[0,0,0]
	v_mfma_scale_f32_16x16x128_f8f6f4 v[32:35], v[0:7], v[174:181], v[198:201], v140, v140 op_sel_hi:[0,0,0]
	v_mfma_scale_f32_16x16x128_f8f6f4 v[24:27], v[8:15], v[174:181], v[202:205], v140, v140 op_sel_hi:[0,0,0]
	v_mfma_scale_f32_16x16x128_f8f6f4 v[16:19], v[0:7], v[182:189], v[218:221], v140, v140 op_sel_hi:[0,0,0]
	v_mfma_scale_f32_16x16x128_f8f6f4 v[8:11], v[8:15], v[182:189], v[222:225], v140, v140 op_sel_hi:[0,0,0]
	s_setprio 0
	s_setprio 1
	v_mfma_scale_f32_16x16x128_f8f6f4 v[52:55], v[142:149], v[158:165], v[52:55], v140, v140 op_sel_hi:[0,0,0]
	v_mfma_scale_f32_16x16x128_f8f6f4 v[44:47], v[150:157], v[158:165], v[226:229], v140, v140 op_sel_hi:[0,0,0]
	v_mfma_scale_f32_16x16x128_f8f6f4 v[36:39], v[142:149], v[166:173], v[230:233], v140, v140 op_sel_hi:[0,0,0]
	v_mfma_scale_f32_16x16x128_f8f6f4 v[28:31], v[150:157], v[166:173], v[234:237], v140, v140 op_sel_hi:[0,0,0]
	v_mfma_scale_f32_16x16x128_f8f6f4 v[20:23], v[142:149], v[174:181], v[238:241], v140, v140 op_sel_hi:[0,0,0]
	v_mfma_scale_f32_16x16x128_f8f6f4 v[12:15], v[150:157], v[174:181], v[242:245], v140, v140 op_sel_hi:[0,0,0]
	v_mfma_scale_f32_16x16x128_f8f6f4 v[4:7], v[142:149], v[182:189], v[246:249], v140, v140 op_sel_hi:[0,0,0]
	v_mfma_scale_f32_16x16x128_f8f6f4 v[0:3], v[150:157], v[182:189], v[250:253], v140, v140 op_sel_hi:[0,0,0]
	s_setprio 0
	s_barrier
	s_add_i32 s61, s61, 2
	s_add_u32 s59, s59, 0x100
	s_addc_u32 s60, s60, 0
	s_cmp_gt_u32 s61, 13
	s_mov_b64 s[28:29], s[30:31]
	s_cbranch_scc0 .LBB0_542
	s_and_b64 vcc, exec, s[6:7]
	s_cbranch_vccz .LBB0_545
	s_barrier

; #define PG8_WAIT_V(n) asm volatile("s_waitcnt vmcnt(" #n ")" ::: "memory")
; #define PG8_WAIT_L(n) asm volatile("s_waitcnt lgkmcnt(" #n ")" ::: "memory")
; #define PG8_BAR __builtin_amdgcn_s_barrier()
; #define PG8_SCHED __builtin_amdgcn_sched_barrier(0)
;     ...
;             const char* a1 = cA + (size_t)(t + 1) * kstep;
;             const char* a2 = last ? nA : cA + (size_t)(t + 2) * kstep; const char* b2 = last ? nB : cB + (size_t)(t + 2) * kstep;
;             const char* a3 = a2 + kstep; const char* b3 = b2 + kstep;
;             if (last && has_next) S.a_ready(nxt);
;             if constexpr (SP2) {
;             PG8_LDB(B0, 0, 0); PG8_LDB(B1, 0, 1); PG8_SCHED; PG8_LDA(At, 0, 0); PG8_STAGE(PG8_SA(1, 1), a1 + hstepA, voffA);
;             PG8_WAIT_V(8); PG8_WAIT_L(0); PG8_BAR; PG8_MMA(0, 0, At, B0); PG8_MMA(0, 1, At, B1); PG8_BAR; PG8_SCHED;
;             if constexpr (!HALFU) PG8_LDA(At, 0, 1); PG8_STAGE(PG8_SB(0, 0), b2, voffB); PG8_STAGE(PG8_SB(0, 1), b2 + hstep, voffB); PG8_STAGE(PG8_SA(0, 0), a2, voffA);
;             PG8_WAIT_V(8); PG8_WAIT_L(0); PG8_BAR; if constexpr (!HALFU) { PG8_MMA(1, 0, At, B0); PG8_MMA(1, 1, At, B1); } PG8_BAR; PG8_SCHED;
.LBB0_670:
	s_add_u32 s98, s18, 0x80
	s_addc_u32 s99, s19, 0
	s_mov_b32 m0, s43
	s_nop 0
	global_load_lds_dwordx4 v134, s[98:99]
	s_mov_b32 m0, s44
	s_nop 0
	global_load_lds_dwordx4 v132, s[98:99]
	s_add_u32 s20, s18, 0x100
	s_addc_u32 s21, s19, 0
	s_cmp_eq_u32 s53, 60
	s_cselect_b32 s26, s49, s20
	s_cselect_b32 s27, s11, s21
	s_cselect_b32 s24, s50, s51
	s_cselect_b32 s25, s9, s52
	s_add_u32 s22, s26, 0x80
	s_addc_u32 s23, s27, 0
	s_add_u32 s18, s18, 0x100080
	s_addc_u32 s19, s19, 0
	s_add_i32 m0, s17, 0xc000
	s_nop 0
	global_load_lds_dwordx4 v134, s[18:19]
	s_add_i32 m0, s17, 0xe000
	s_nop 0
	global_load_lds_dwordx4 v132, s[18:19]
	ds_read_b128 v[144:147], v141
	ds_read_b128 v[148:151], v141 offset:1024
	ds_read_b128 v[152:155], v141 offset:2048
	ds_read_b128 v[156:159], v141 offset:3072
	ds_read_b128 v[160:163], v142
	ds_read_b128 v[164:167], v142 offset:1024
	ds_read_b128 v[168:171], v142 offset:2048
	ds_read_b128 v[172:175], v142 offset:3072
	ds_read_b128 v[176:179], v143
	ds_read_b128 v[180:183], v143 offset:1024
	ds_read_b128 v[184:187], v143 offset:2048
	ds_read_b128 v[188:191], v143 offset:3072
	ds_read_b128 v[192:195], v143 offset:4096
	ds_read_b128 v[196:199], v143 offset:5120
	ds_read_b128 v[200:203], v143 offset:6144
	ds_read_b128 v[204:207], v143 offset:7168
	s_waitcnt vmcnt(8)
	s_waitcnt lgkmcnt(0)
	s_barrier
	s_setprio 1
	s_waitcnt lgkmcnt(0)
	v_mfma_f32_16x16x32_bf16 v[124:127], v[144:147], v[176:179], v[124:127]
	v_mfma_f32_16x16x32_bf16 v[120:123], v[152:155], v[176:179], v[120:123]
	v_mfma_f32_16x16x32_bf16 v[108:111], v[144:147], v[184:187], v[108:111]
	v_mfma_f32_16x16x32_bf16 v[104:107], v[152:155], v[184:187], v[104:107]
	v_mfma_f32_16x16x32_bf16 v[92:95], v[144:147], v[192:195], v[92:95]
	v_mfma_f32_16x16x32_bf16 v[88:91], v[152:155], v[192:195], v[88:91]
	v_mfma_f32_16x16x32_bf16 v[76:79], v[144:147], v[200:203], v[76:79]
	v_mfma_f32_16x16x32_bf16 v[72:75], v[152:155], v[200:203], v[72:75]
	v_mfma_f32_16x16x32_bf16 v[124:127], v[148:151], v[180:183], v[124:127]
	v_mfma_f32_16x16x32_bf16 v[120:123], v[156:159], v[180:183], v[120:123]
	v_mfma_f32_16x16x32_bf16 v[108:111], v[148:151], v[188:191], v[108:111]
	v_mfma_f32_16x16x32_bf16 v[104:107], v[156:159], v[188:191], v[104:107]
	v_mfma_f32_16x16x32_bf16 v[92:95], v[148:151], v[196:199], v[92:95]
	v_mfma_f32_16x16x32_bf16 v[88:91], v[156:159], v[196:199], v[88:91]
	v_mfma_f32_16x16x32_bf16 v[76:79], v[148:151], v[204:207], v[76:79]
	v_mfma_f32_16x16x32_bf16 v[72:75], v[156:159], v[204:207], v[72:75]
	s_setprio 0
	s_setprio 1
	v_mfma_f32_16x16x32_bf16 v[116:119], v[160:163], v[176:179], v[116:119]
	v_mfma_f32_16x16x32_bf16 v[112:115], v[168:171], v[176:179], v[112:115]
	v_mfma_f32_16x16x32_bf16 v[100:103], v[160:163], v[184:187], v[100:103]
	v_mfma_f32_16x16x32_bf16 v[96:99], v[168:171], v[184:187], v[96:99]
	v_mfma_f32_16x16x32_bf16 v[84:87], v[160:163], v[192:195], v[84:87]
	v_mfma_f32_16x16x32_bf16 v[80:83], v[168:171], v[192:195], v[80:83]
	v_mfma_f32_16x16x32_bf16 v[68:71], v[160:163], v[200:203], v[68:71]
	v_mfma_f32_16x16x32_bf16 v[64:67], v[168:171], v[200:203], v[64:67]
	v_mfma_f32_16x16x32_bf16 v[116:119], v[164:167], v[180:183], v[116:119]
	v_mfma_f32_16x16x32_bf16 v[112:115], v[172:175], v[180:183], v[112:115]
	v_mfma_f32_16x16x32_bf16 v[100:103], v[164:167], v[188:191], v[100:103]
	v_mfma_f32_16x16x32_bf16 v[96:99], v[172:175], v[188:191], v[96:99]
	v_mfma_f32_16x16x32_bf16 v[84:87], v[164:167], v[196:199], v[84:87]
	v_mfma_f32_16x16x32_bf16 v[80:83], v[172:175], v[196:199], v[80:83]
	v_mfma_f32_16x16x32_bf16 v[68:71], v[164:167], v[204:207], v[68:71]
	v_mfma_f32_16x16x32_bf16 v[64:67], v[172:175], v[204:207], v[64:67]
	s_setprio 0
	s_barrier
	s_add_i32 s18, s45, s30
	s_mov_b32 m0, s18
	s_nop 0
	global_load_lds_dwordx4 v128, s[24:25]
	s_add_i32 m0, s18, 0x2000
	s_add_u32 s18, s24, 0x100000
	s_addc_u32 s19, s25, 0
	s_add_i32 s54, s46, s30
	global_load_lds_dwordx4 v130, s[24:25]
	s_mov_b32 m0, s54
	s_nop 0
	global_load_lds_dwordx4 v128, s[18:19]
	s_add_i32 m0, s54, 0x2000
	s_nop 0
	global_load_lds_dwordx4 v130, s[18:19]
	ds_read_b128 v[176:179], v143 offset:16384
	ds_read_b128 v[180:183], v143 offset:17408
	ds_read_b128 v[184:187], v143 offset:18432
	ds_read_b128 v[188:191], v143 offset:19456
	ds_read_b128 v[192:195], v143 offset:20480
	ds_read_b128 v[196:199], v143 offset:21504
	ds_read_b128 v[200:203], v143 offset:22528
	ds_read_b128 v[204:207], v143 offset:23552
	s_waitcnt vmcnt(4)
	s_waitcnt lgkmcnt(0)
	s_barrier
	s_setprio 1
	s_waitcnt lgkmcnt(0)
	v_mfma_f32_16x16x32_bf16 v[60:63], v[144:147], v[176:179], v[60:63]
	v_mfma_f32_16x16x32_bf16 v[56:59], v[152:155], v[176:179], v[56:59]
	v_mfma_f32_16x16x32_bf16 v[44:47], v[144:147], v[184:187], v[44:47]
	v_mfma_f32_16x16x32_bf16 v[40:43], v[152:155], v[184:187], v[40:43]
	v_mfma_f32_16x16x32_bf16 v[28:31], v[144:147], v[192:195], v[28:31]
	v_mfma_f32_16x16x32_bf16 v[24:27], v[152:155], v[192:195], v[24:27]
	v_mfma_f32_16x16x32_bf16 v[12:15], v[144:147], v[200:203], v[12:15]
	v_mfma_f32_16x16x32_bf16 v[8:11], v[152:155], v[200:203], v[8:11]
	v_mfma_f32_16x16x32_bf16 v[60:63], v[148:151], v[180:183], v[60:63]
	v_mfma_f32_16x16x32_bf16 v[56:59], v[156:159], v[180:183], v[56:59]
	v_mfma_f32_16x16x32_bf16 v[44:47], v[148:151], v[188:191], v[44:47]
	v_mfma_f32_16x16x32_bf16 v[40:43], v[156:159], v[188:191], v[40:43]
	v_mfma_f32_16x16x32_bf16 v[28:31], v[148:151], v[196:199], v[28:31]
	v_mfma_f32_16x16x32_bf16 v[24:27], v[156:159], v[196:199], v[24:27]
	v_mfma_f32_16x16x32_bf16 v[12:15], v[148:151], v[204:207], v[12:15]
	v_mfma_f32_16x16x32_bf16 v[8:11], v[156:159], v[204:207], v[8:11]
	s_setprio 0
	s_setprio 1
	v_mfma_f32_16x16x32_bf16 v[52:55], v[160:163], v[176:179], v[52:55]
	v_mfma_f32_16x16x32_bf16 v[48:51], v[168:171], v[176:179], v[48:51]
	v_mfma_f32_16x16x32_bf16 v[36:39], v[160:163], v[184:187], v[36:39]
	v_mfma_f32_16x16x32_bf16 v[32:35], v[168:171], v[184:187], v[32:35]
	v_mfma_f32_16x16x32_bf16 v[20:23], v[160:163], v[192:195], v[20:23]
	v_mfma_f32_16x16x32_bf16 v[16:19], v[168:171], v[192:195], v[16:19]
	v_mfma_f32_16x16x32_bf16 v[4:7], v[160:163], v[200:203], v[4:7]
	v_mfma_f32_16x16x32_bf16 v[0:3], v[168:171], v[200:203], v[0:3]
	v_mfma_f32_16x16x32_bf16 v[52:55], v[164:167], v[180:183], v[52:55]
	v_mfma_f32_16x16x32_bf16 v[48:51], v[172:175], v[180:183], v[48:51]
	v_mfma_f32_16x16x32_bf16 v[36:39], v[164:167], v[188:191], v[36:39]
	v_mfma_f32_16x16x32_bf16 v[32:35], v[172:175], v[188:191], v[32:35]
	v_mfma_f32_16x16x32_bf16 v[20:23], v[164:167], v[196:199], v[20:23]
	v_mfma_f32_16x16x32_bf16 v[16:19], v[172:175], v[196:199], v[16:19]
	v_mfma_f32_16x16x32_bf16 v[4:7], v[164:167], v[204:207], v[4:7]
	v_mfma_f32_16x16x32_bf16 v[0:3], v[172:175], v[204:207], v[0:3]
	s_setprio 0
	s_barrier
; #define PG8_WAIT_V(n) asm volatile("s_waitcnt vmcnt(" #n ")" ::: "memory")
; #define PG8_WAIT_L(n) asm volatile("s_waitcnt lgkmcnt(" #n ")" ::: "memory")
; #define PG8_BAR __builtin_amdgcn_s_barrier()
; #define PG8_SCHED __builtin_amdgcn_sched_barrier(0)
;     ...
;             PG8_LDB(B0, 1, 0); PG8_LDB(B1, 1, 1); PG8_SCHED; PG8_LDA(At, 1, 0); PG8_STAGE(PG8_SA(0, 1), a2 + hstepA, voffA);
;             PG8_WAIT_V(8); PG8_WAIT_L(0); PG8_BAR; PG8_MMA(0, 0, At, B0); PG8_MMA(0, 1, At, B1); PG8_BAR; PG8_SCHED;
;             if constexpr (!HALFU) PG8_LDA(At, 1, 1); PG8_STAGE(PG8_SB(1, 0), b3, voffB); PG8_STAGE(PG8_SB(1, 1), b3 + hstep, voffB); PG8_STAGE(PG8_SA(1, 0), a3, voffA);
;             PG8_WAIT_V(8); PG8_WAIT_L(0); PG8_BAR; if constexpr (!HALFU) { PG8_MMA(1, 0, At, B0); PG8_MMA(1, 1, At, B1); } PG8_BAR; PG8_SCHED;
	s_mov_b32 m0, s17
	s_nop 0
	global_load_lds_dwordx4 v134, s[26:27]
	s_mov_b32 m0, s36
	s_nop 0
	global_load_lds_dwordx4 v132, s[26:27]
	s_add_i32 s54, 0, 0x18000
	s_add_i32 s55, 0, 0x1c000
	s_add_u32 s18, s26, 0x100000
	s_addc_u32 s19, s27, 0
	s_mov_b32 m0, s37
	s_nop 0
	global_load_lds_dwordx4 v134, s[18:19]
	s_mov_b32 m0, s38
	s_nop 0
	global_load_lds_dwordx4 v132, s[18:19]
	v_add_u32_e32 v156, s54, v140
	v_add_u32_e32 v172, s55, v140
	ds_read_b128 v[144:147], v156
	ds_read_b128 v[148:151], v156 offset:1024
	ds_read_b128 v[152:155], v156 offset:2048
	ds_read_b128 v[156:159], v156 offset:3072
	ds_read_b128 v[160:163], v172
	ds_read_b128 v[164:167], v172 offset:1024
	ds_read_b128 v[168:171], v172 offset:2048
	ds_read_b128 v[172:175], v172 offset:3072
	ds_read_b128 v[176:179], v143 offset:32768
	ds_read_b128 v[180:183], v143 offset:33792
	ds_read_b128 v[184:187], v143 offset:34816
	ds_read_b128 v[188:191], v143 offset:35840
	ds_read_b128 v[192:195], v143 offset:36864
	ds_read_b128 v[196:199], v143 offset:37888
	ds_read_b128 v[200:203], v143 offset:38912
	ds_read_b128 v[204:207], v143 offset:39936
	s_waitcnt vmcnt(8)
	s_waitcnt lgkmcnt(0)
	s_barrier
	s_setprio 1
	s_waitcnt lgkmcnt(0)
	v_mfma_f32_16x16x32_bf16 v[124:127], v[144:147], v[176:179], v[124:127]
	v_mfma_f32_16x16x32_bf16 v[120:123], v[152:155], v[176:179], v[120:123]
	v_mfma_f32_16x16x32_bf16 v[108:111], v[144:147], v[184:187], v[108:111]
	v_mfma_f32_16x16x32_bf16 v[104:107], v[152:155], v[184:187], v[104:107]
	v_mfma_f32_16x16x32_bf16 v[92:95], v[144:147], v[192:195], v[92:95]
	v_mfma_f32_16x16x32_bf16 v[88:91], v[152:155], v[192:195], v[88:91]
	v_mfma_f32_16x16x32_bf16 v[76:79], v[144:147], v[200:203], v[76:79]
	v_mfma_f32_16x16x32_bf16 v[72:75], v[152:155], v[200:203], v[72:75]
	v_mfma_f32_16x16x32_bf16 v[124:127], v[148:151], v[180:183], v[124:127]
	v_mfma_f32_16x16x32_bf16 v[120:123], v[156:159], v[180:183], v[120:123]
	v_mfma_f32_16x16x32_bf16 v[108:111], v[148:151], v[188:191], v[108:111]
	v_mfma_f32_16x16x32_bf16 v[104:107], v[156:159], v[188:191], v[104:107]
	v_mfma_f32_16x16x32_bf16 v[92:95], v[148:151], v[196:199], v[92:95]
	v_mfma_f32_16x16x32_bf16 v[88:91], v[156:159], v[196:199], v[88:91]
	v_mfma_f32_16x16x32_bf16 v[76:79], v[148:151], v[204:207], v[76:79]
	v_mfma_f32_16x16x32_bf16 v[72:75], v[156:159], v[204:207], v[72:75]
	s_setprio 0
	s_setprio 1
	v_mfma_f32_16x16x32_bf16 v[116:119], v[160:163], v[176:179], v[116:119]
	v_mfma_f32_16x16x32_bf16 v[112:115], v[168:171], v[176:179], v[112:115]
	v_mfma_f32_16x16x32_bf16 v[100:103], v[160:163], v[184:187], v[100:103]
	v_mfma_f32_16x16x32_bf16 v[96:99], v[168:171], v[184:187], v[96:99]
	v_mfma_f32_16x16x32_bf16 v[84:87], v[160:163], v[192:195], v[84:87]
	v_mfma_f32_16x16x32_bf16 v[80:83], v[168:171], v[192:195], v[80:83]
	v_mfma_f32_16x16x32_bf16 v[68:71], v[160:163], v[200:203], v[68:71]
	v_mfma_f32_16x16x32_bf16 v[64:67], v[168:171], v[200:203], v[64:67]
	v_mfma_f32_16x16x32_bf16 v[116:119], v[164:167], v[180:183], v[116:119]
	v_mfma_f32_16x16x32_bf16 v[112:115], v[172:175], v[180:183], v[112:115]
	v_mfma_f32_16x16x32_bf16 v[100:103], v[164:167], v[188:191], v[100:103]
	v_mfma_f32_16x16x32_bf16 v[96:99], v[172:175], v[188:191], v[96:99]
	v_mfma_f32_16x16x32_bf16 v[84:87], v[164:167], v[196:199], v[84:87]
	v_mfma_f32_16x16x32_bf16 v[80:83], v[172:175], v[196:199], v[80:83]
	v_mfma_f32_16x16x32_bf16 v[68:71], v[164:167], v[204:207], v[68:71]
	v_mfma_f32_16x16x32_bf16 v[64:67], v[172:175], v[204:207], v[64:67]
	s_setprio 0
	s_barrier
	s_add_u32 s18, s24, 0x80
	s_addc_u32 s19, s25, 0
	s_add_i32 s26, s54, s30
	s_mov_b32 m0, s26
	ds_read_b128 v[176:179], v143 offset:49152
	ds_read_b128 v[180:183], v143 offset:50176
	ds_read_b128 v[184:187], v143 offset:51200
	ds_read_b128 v[188:191], v143 offset:52224
	ds_read_b128 v[192:195], v143 offset:53248
	ds_read_b128 v[196:199], v143 offset:54272
	ds_read_b128 v[200:203], v143 offset:55296
	ds_read_b128 v[204:207], v143 offset:56320
	global_load_lds_dwordx4 v128, s[18:19]
	s_add_i32 m0, s26, 0x2000
	v_lshl_add_u64 v[208:209], s[18:19], 0, v[130:131]
	s_add_u32 s18, s24, 0x100080
	s_addc_u32 s19, s25, 0
	s_add_i32 s24, s55, s30
	global_load_lds_dwordx4 v[208:209], off
	s_mov_b32 m0, s24
	s_nop 0
	global_load_lds_dwordx4 v128, s[18:19]
	s_add_i32 m0, s24, 0x2000
	s_nop 0
	global_load_lds_dwordx4 v130, s[18:19]
	s_waitcnt vmcnt(4)
	s_waitcnt lgkmcnt(0)
	s_barrier
	s_setprio 1
	s_waitcnt lgkmcnt(0)
	v_mfma_f32_16x16x32_bf16 v[60:63], v[144:147], v[176:179], v[60:63]
	v_mfma_f32_16x16x32_bf16 v[56:59], v[152:155], v[176:179], v[56:59]
	v_mfma_f32_16x16x32_bf16 v[44:47], v[144:147], v[184:187], v[44:47]
	v_mfma_f32_16x16x32_bf16 v[40:43], v[152:155], v[184:187], v[40:43]
	v_mfma_f32_16x16x32_bf16 v[28:31], v[144:147], v[192:195], v[28:31]
	v_mfma_f32_16x16x32_bf16 v[24:27], v[152:155], v[192:195], v[24:27]
	v_mfma_f32_16x16x32_bf16 v[12:15], v[144:147], v[200:203], v[12:15]
	v_mfma_f32_16x16x32_bf16 v[8:11], v[152:155], v[200:203], v[8:11]
	v_mfma_f32_16x16x32_bf16 v[60:63], v[148:151], v[180:183], v[60:63]
	v_mfma_f32_16x16x32_bf16 v[56:59], v[156:159], v[180:183], v[56:59]
	v_mfma_f32_16x16x32_bf16 v[44:47], v[148:151], v[188:191], v[44:47]
	v_mfma_f32_16x16x32_bf16 v[40:43], v[156:159], v[188:191], v[40:43]
	v_mfma_f32_16x16x32_bf16 v[28:31], v[148:151], v[196:199], v[28:31]
	v_mfma_f32_16x16x32_bf16 v[24:27], v[156:159], v[196:199], v[24:27]
	v_mfma_f32_16x16x32_bf16 v[12:15], v[148:151], v[204:207], v[12:15]
	v_mfma_f32_16x16x32_bf16 v[8:11], v[156:159], v[204:207], v[8:11]
	s_setprio 0
	s_setprio 1
	v_mfma_f32_16x16x32_bf16 v[52:55], v[160:163], v[176:179], v[52:55]
	v_mfma_f32_16x16x32_bf16 v[48:51], v[168:171], v[176:179], v[48:51]
	v_mfma_f32_16x16x32_bf16 v[36:39], v[160:163], v[184:187], v[36:39]
	v_mfma_f32_16x16x32_bf16 v[32:35], v[168:171], v[184:187], v[32:35]
	v_mfma_f32_16x16x32_bf16 v[20:23], v[160:163], v[192:195], v[20:23]
	v_mfma_f32_16x16x32_bf16 v[16:19], v[168:171], v[192:195], v[16:19]
	v_mfma_f32_16x16x32_bf16 v[4:7], v[160:163], v[200:203], v[4:7]
	v_mfma_f32_16x16x32_bf16 v[0:3], v[168:171], v[200:203], v[0:3]
	v_mfma_f32_16x16x32_bf16 v[52:55], v[164:167], v[180:183], v[52:55]
	v_mfma_f32_16x16x32_bf16 v[48:51], v[172:175], v[180:183], v[48:51]
	v_mfma_f32_16x16x32_bf16 v[36:39], v[164:167], v[188:191], v[36:39]
	v_mfma_f32_16x16x32_bf16 v[32:35], v[172:175], v[188:191], v[32:35]
	v_mfma_f32_16x16x32_bf16 v[20:23], v[164:167], v[196:199], v[20:23]
	v_mfma_f32_16x16x32_bf16 v[16:19], v[172:175], v[196:199], v[16:19]
	v_mfma_f32_16x16x32_bf16 v[4:7], v[164:167], v[204:207], v[4:7]
	v_mfma_f32_16x16x32_bf16 v[0:3], v[172:175], v[204:207], v[0:3]
	s_setprio 0
	s_barrier
	s_add_i32 s53, s53, 2
	s_add_u32 s51, s51, 0x100
	s_addc_u32 s52, s52, 0
	s_cmp_gt_u32 s53, 61
	s_mov_b64 s[18:19], s[20:21]
	s_cbranch_scc0 .LBB0_670
	s_and_b64 vcc, exec, s[6:7]
	s_cbranch_vccz .LBB0_673
	s_barrier

; #define PG8_WAIT_V(n) asm volatile("s_waitcnt vmcnt(" #n ")" ::: "memory")
; #define PG8_WAIT_L(n) asm volatile("s_waitcnt lgkmcnt(" #n ")" ::: "memory")
; #define PG8_BAR __builtin_amdgcn_s_barrier()
; #define PG8_SCHED __builtin_amdgcn_sched_barrier(0)
;     ...
;         for (int t = 0; t < nt; t += 2) {
;             const bool last = (t == nt - 2);
;             const char* a1 = cA + (size_t)(t + 1) * kstep;
;             const char* a2 = last ? nA : cA + (size_t)(t + 2) * kstep; const char* b2 = last ? nB : cB + (size_t)(t + 2) * kstep;
;             const char* a3 = a2 + kstep; const char* b3 = b2 + kstep;
;             if (last && has_next) S.a_ready(nxt);
;             if constexpr (SP2) {
;             PG8_LDB(B0, 0, 0); PG8_LDB(B1, 0, 1); PG8_SCHED; PG8_LDA(At, 0, 0); PG8_STAGE(PG8_SA(1, 1), a1 + hstepA, voffA);
;             PG8_WAIT_V(8); PG8_WAIT_L(0); PG8_BAR; PG8_MMA(0, 0, At, B0); PG8_MMA(0, 1, At, B1); PG8_BAR; PG8_SCHED;
;             if constexpr (!HALFU) PG8_LDA(At, 0, 1); PG8_STAGE(PG8_SB(0, 0), b2, voffB); PG8_STAGE(PG8_SB(0, 1), b2 + hstep, voffB); PG8_STAGE(PG8_SA(0, 0), a2, voffA);
;             PG8_WAIT_V(8); PG8_WAIT_L(0); PG8_BAR; if constexpr (!HALFU) { PG8_MMA(1, 0, At, B0); PG8_MMA(1, 1, At, B1); } PG8_BAR; PG8_SCHED;
.LBB0_793:
	s_add_u32 s98, s10, 0x80
	s_addc_u32 s99, s11, 0
	s_mov_b32 m0, s43
	s_nop 0
	global_load_lds_dwordx4 v128, s[98:99]
	s_mov_b32 m0, s44
	s_nop 0
	global_load_lds_dwordx4 v130, s[98:99]
	s_add_u32 s22, s10, 0x100
	s_addc_u32 s23, s11, 0
	s_cmpk_eq_i32 s54, 0xa8
	s_cselect_b32 s28, s6, s22
	s_cselect_b32 s29, s7, s23
	s_cselect_b32 s26, s20, s52
	s_cselect_b32 s27, s21, s53
	s_add_u32 s24, s28, 0x80
	s_addc_u32 s25, s29, 0
	s_add_u32 s10, s10, 0x2b0080
	s_addc_u32 s11, s11, 0
	s_add_i32 m0, s36, 0xc000
	s_nop 0
	global_load_lds_dwordx4 v128, s[10:11]
	s_add_i32 m0, s36, 0xe000
	s_nop 0
	global_load_lds_dwordx4 v130, s[10:11]
	ds_read_b128 v[140:143], v137
	ds_read_b128 v[144:147], v137 offset:1024
	ds_read_b128 v[148:151], v137 offset:2048
	ds_read_b128 v[152:155], v137 offset:3072
	ds_read_b128 v[156:159], v138
	ds_read_b128 v[160:163], v138 offset:1024
	ds_read_b128 v[164:167], v138 offset:2048
	ds_read_b128 v[168:171], v138 offset:3072
	ds_read_b128 v[172:175], v139
	ds_read_b128 v[176:179], v139 offset:1024
	ds_read_b128 v[180:183], v139 offset:2048
	ds_read_b128 v[184:187], v139 offset:3072
	ds_read_b128 v[188:191], v139 offset:4096
	ds_read_b128 v[192:195], v139 offset:5120
	ds_read_b128 v[196:199], v139 offset:6144
	ds_read_b128 v[200:203], v139 offset:7168
	s_waitcnt vmcnt(8)
	s_waitcnt lgkmcnt(0)
	s_barrier
	s_setprio 1
	s_waitcnt lgkmcnt(0)
	v_mfma_f32_16x16x32_bf16 v[124:127], v[140:143], v[172:175], v[124:127]
	v_mfma_f32_16x16x32_bf16 v[120:123], v[148:151], v[172:175], v[120:123]
	v_mfma_f32_16x16x32_bf16 v[112:115], v[140:143], v[180:183], v[112:115]
	v_mfma_f32_16x16x32_bf16 v[104:107], v[148:151], v[180:183], v[104:107]
	v_mfma_f32_16x16x32_bf16 v[96:99], v[140:143], v[188:191], v[96:99]
	v_mfma_f32_16x16x32_bf16 v[88:91], v[148:151], v[188:191], v[88:91]
	v_mfma_f32_16x16x32_bf16 v[80:83], v[140:143], v[196:199], v[80:83]
	v_mfma_f32_16x16x32_bf16 v[72:75], v[148:151], v[196:199], v[72:75]
	v_mfma_f32_16x16x32_bf16 v[124:127], v[144:147], v[176:179], v[124:127]
	v_mfma_f32_16x16x32_bf16 v[120:123], v[152:155], v[176:179], v[120:123]
	v_mfma_f32_16x16x32_bf16 v[112:115], v[144:147], v[184:187], v[112:115]
	v_mfma_f32_16x16x32_bf16 v[104:107], v[152:155], v[184:187], v[104:107]
	v_mfma_f32_16x16x32_bf16 v[96:99], v[144:147], v[192:195], v[96:99]
	v_mfma_f32_16x16x32_bf16 v[88:91], v[152:155], v[192:195], v[88:91]
	v_mfma_f32_16x16x32_bf16 v[80:83], v[144:147], v[200:203], v[80:83]
	v_mfma_f32_16x16x32_bf16 v[72:75], v[152:155], v[200:203], v[72:75]
	s_setprio 0
	s_setprio 1
	v_mfma_f32_16x16x32_bf16 v[116:119], v[156:159], v[172:175], v[116:119]
	v_mfma_f32_16x16x32_bf16 v[108:111], v[164:167], v[172:175], v[108:111]
	v_mfma_f32_16x16x32_bf16 v[100:103], v[156:159], v[180:183], v[100:103]
	v_mfma_f32_16x16x32_bf16 v[92:95], v[164:167], v[180:183], v[92:95]
	v_mfma_f32_16x16x32_bf16 v[84:87], v[156:159], v[188:191], v[84:87]
	v_mfma_f32_16x16x32_bf16 v[76:79], v[164:167], v[188:191], v[76:79]
	v_mfma_f32_16x16x32_bf16 v[68:71], v[156:159], v[196:199], v[68:71]
	v_mfma_f32_16x16x32_bf16 v[64:67], v[164:167], v[196:199], v[64:67]
	v_mfma_f32_16x16x32_bf16 v[116:119], v[160:163], v[176:179], v[116:119]
	v_mfma_f32_16x16x32_bf16 v[108:111], v[168:171], v[176:179], v[108:111]
	v_mfma_f32_16x16x32_bf16 v[100:103], v[160:163], v[184:187], v[100:103]
	v_mfma_f32_16x16x32_bf16 v[92:95], v[168:171], v[184:187], v[92:95]
	v_mfma_f32_16x16x32_bf16 v[84:87], v[160:163], v[192:195], v[84:87]
	v_mfma_f32_16x16x32_bf16 v[76:79], v[168:171], v[192:195], v[76:79]
	v_mfma_f32_16x16x32_bf16 v[68:71], v[160:163], v[200:203], v[68:71]
	v_mfma_f32_16x16x32_bf16 v[64:67], v[168:171], v[200:203], v[64:67]
	s_setprio 0
	s_barrier
	s_add_i32 s10, s46, s31
	s_mov_b32 m0, s10
	s_nop 0
	global_load_lds_dwordx4 v128, s[26:27]
	s_add_i32 m0, s10, 0x2000
	s_add_u32 s10, s26, 0x2b0000
	s_addc_u32 s11, s27, 0
	s_add_i32 s55, s47, s31
	global_load_lds_dwordx4 v130, s[26:27]
	s_mov_b32 m0, s55
	s_nop 0
	global_load_lds_dwordx4 v128, s[10:11]
	s_add_i32 m0, s55, 0x2000
	s_nop 0
	global_load_lds_dwordx4 v130, s[10:11]
	ds_read_b128 v[172:175], v139 offset:16384
	ds_read_b128 v[176:179], v139 offset:17408
	ds_read_b128 v[180:183], v139 offset:18432
	ds_read_b128 v[184:187], v139 offset:19456
	ds_read_b128 v[188:191], v139 offset:20480
	ds_read_b128 v[192:195], v139 offset:21504
	ds_read_b128 v[196:199], v139 offset:22528
	ds_read_b128 v[200:203], v139 offset:23552
	s_waitcnt vmcnt(4)
	s_waitcnt lgkmcnt(0)
	s_barrier
	s_setprio 1
	s_waitcnt lgkmcnt(0)
	v_mfma_f32_16x16x32_bf16 v[60:63], v[140:143], v[172:175], v[60:63]
	v_mfma_f32_16x16x32_bf16 v[56:59], v[148:151], v[172:175], v[56:59]
	v_mfma_f32_16x16x32_bf16 v[48:51], v[140:143], v[180:183], v[48:51]
	v_mfma_f32_16x16x32_bf16 v[40:43], v[148:151], v[180:183], v[40:43]
	v_mfma_f32_16x16x32_bf16 v[32:35], v[140:143], v[188:191], v[32:35]
	v_mfma_f32_16x16x32_bf16 v[24:27], v[148:151], v[188:191], v[24:27]
	v_mfma_f32_16x16x32_bf16 v[16:19], v[140:143], v[196:199], v[16:19]
	v_mfma_f32_16x16x32_bf16 v[8:11], v[148:151], v[196:199], v[8:11]
	v_mfma_f32_16x16x32_bf16 v[60:63], v[144:147], v[176:179], v[60:63]
	v_mfma_f32_16x16x32_bf16 v[56:59], v[152:155], v[176:179], v[56:59]
	v_mfma_f32_16x16x32_bf16 v[48:51], v[144:147], v[184:187], v[48:51]
	v_mfma_f32_16x16x32_bf16 v[40:43], v[152:155], v[184:187], v[40:43]
	v_mfma_f32_16x16x32_bf16 v[32:35], v[144:147], v[192:195], v[32:35]
	v_mfma_f32_16x16x32_bf16 v[24:27], v[152:155], v[192:195], v[24:27]
	v_mfma_f32_16x16x32_bf16 v[16:19], v[144:147], v[200:203], v[16:19]
	v_mfma_f32_16x16x32_bf16 v[8:11], v[152:155], v[200:203], v[8:11]
	s_setprio 0
	s_setprio 1
	v_mfma_f32_16x16x32_bf16 v[52:55], v[156:159], v[172:175], v[52:55]
	v_mfma_f32_16x16x32_bf16 v[44:47], v[164:167], v[172:175], v[44:47]
	v_mfma_f32_16x16x32_bf16 v[36:39], v[156:159], v[180:183], v[36:39]
	v_mfma_f32_16x16x32_bf16 v[28:31], v[164:167], v[180:183], v[28:31]
	v_mfma_f32_16x16x32_bf16 v[20:23], v[156:159], v[188:191], v[20:23]
	v_mfma_f32_16x16x32_bf16 v[12:15], v[164:167], v[188:191], v[12:15]
	v_mfma_f32_16x16x32_bf16 v[4:7], v[156:159], v[196:199], v[4:7]
	v_mfma_f32_16x16x32_bf16 v[0:3], v[164:167], v[196:199], v[0:3]
	v_mfma_f32_16x16x32_bf16 v[52:55], v[160:163], v[176:179], v[52:55]
	v_mfma_f32_16x16x32_bf16 v[44:47], v[168:171], v[176:179], v[44:47]
	v_mfma_f32_16x16x32_bf16 v[36:39], v[160:163], v[184:187], v[36:39]
	v_mfma_f32_16x16x32_bf16 v[28:31], v[168:171], v[184:187], v[28:31]
	v_mfma_f32_16x16x32_bf16 v[20:23], v[160:163], v[192:195], v[20:23]
	v_mfma_f32_16x16x32_bf16 v[12:15], v[168:171], v[192:195], v[12:15]
	v_mfma_f32_16x16x32_bf16 v[4:7], v[160:163], v[200:203], v[4:7]
	v_mfma_f32_16x16x32_bf16 v[0:3], v[168:171], v[200:203], v[0:3]
	s_setprio 0
	s_barrier
; #define PG8_WAIT_V(n) asm volatile("s_waitcnt vmcnt(" #n ")" ::: "memory")
; #define PG8_WAIT_L(n) asm volatile("s_waitcnt lgkmcnt(" #n ")" ::: "memory")
; #define PG8_BAR __builtin_amdgcn_s_barrier()
; #define PG8_SCHED __builtin_amdgcn_sched_barrier(0)
;     ...
;             PG8_LDB(B0, 1, 0); PG8_LDB(B1, 1, 1); PG8_SCHED; PG8_LDA(At, 1, 0); PG8_STAGE(PG8_SA(0, 1), a2 + hstepA, voffA);
;             PG8_WAIT_V(8); PG8_WAIT_L(0); PG8_BAR; PG8_MMA(0, 0, At, B0); PG8_MMA(0, 1, At, B1); PG8_BAR; PG8_SCHED;
;             if constexpr (!HALFU) PG8_LDA(At, 1, 1); PG8_STAGE(PG8_SB(1, 0), b3, voffB); PG8_STAGE(PG8_SB(1, 1), b3 + hstep, voffB); PG8_STAGE(PG8_SA(1, 0), a3, voffA);
;             PG8_WAIT_V(8); PG8_WAIT_L(0); PG8_BAR; if constexpr (!HALFU) { PG8_MMA(1, 0, At, B0); PG8_MMA(1, 1, At, B1); } PG8_BAR; PG8_SCHED;
	s_mov_b32 m0, s36
	s_nop 0
	global_load_lds_dwordx4 v128, s[28:29]
	s_mov_b32 m0, s37
	s_nop 0
	global_load_lds_dwordx4 v130, s[28:29]
	s_add_i32 s55, 0, 0x18000
	s_add_i32 s56, 0, 0x1c000
	s_add_u32 s10, s28, 0x2b0000
	s_addc_u32 s11, s29, 0
	s_mov_b32 m0, s38
	s_nop 0
	global_load_lds_dwordx4 v128, s[10:11]
	s_mov_b32 m0, s39
	s_nop 0
	global_load_lds_dwordx4 v130, s[10:11]
	v_add_u32_e32 v152, s55, v136
	v_add_u32_e32 v168, s56, v136
	ds_read_b128 v[140:143], v152
	ds_read_b128 v[144:147], v152 offset:1024
	ds_read_b128 v[148:151], v152 offset:2048
	ds_read_b128 v[152:155], v152 offset:3072
	ds_read_b128 v[156:159], v168
	ds_read_b128 v[160:163], v168 offset:1024
	ds_read_b128 v[164:167], v168 offset:2048
	ds_read_b128 v[168:171], v168 offset:3072
	ds_read_b128 v[172:175], v139 offset:32768
	ds_read_b128 v[176:179], v139 offset:33792
	ds_read_b128 v[180:183], v139 offset:34816
	ds_read_b128 v[184:187], v139 offset:35840
	ds_read_b128 v[188:191], v139 offset:36864
	ds_read_b128 v[192:195], v139 offset:37888
	ds_read_b128 v[196:199], v139 offset:38912
	ds_read_b128 v[200:203], v139 offset:39936
	s_waitcnt vmcnt(8)
	s_waitcnt lgkmcnt(0)
	s_barrier
	s_setprio 1
	s_waitcnt lgkmcnt(0)
	v_mfma_f32_16x16x32_bf16 v[124:127], v[140:143], v[172:175], v[124:127]
	v_mfma_f32_16x16x32_bf16 v[120:123], v[148:151], v[172:175], v[120:123]
	v_mfma_f32_16x16x32_bf16 v[112:115], v[140:143], v[180:183], v[112:115]
	v_mfma_f32_16x16x32_bf16 v[104:107], v[148:151], v[180:183], v[104:107]
	v_mfma_f32_16x16x32_bf16 v[96:99], v[140:143], v[188:191], v[96:99]
	v_mfma_f32_16x16x32_bf16 v[88:91], v[148:151], v[188:191], v[88:91]
	v_mfma_f32_16x16x32_bf16 v[80:83], v[140:143], v[196:199], v[80:83]
	v_mfma_f32_16x16x32_bf16 v[72:75], v[148:151], v[196:199], v[72:75]
	v_mfma_f32_16x16x32_bf16 v[124:127], v[144:147], v[176:179], v[124:127]
	v_mfma_f32_16x16x32_bf16 v[120:123], v[152:155], v[176:179], v[120:123]
	v_mfma_f32_16x16x32_bf16 v[112:115], v[144:147], v[184:187], v[112:115]
	v_mfma_f32_16x16x32_bf16 v[104:107], v[152:155], v[184:187], v[104:107]
	v_mfma_f32_16x16x32_bf16 v[96:99], v[144:147], v[192:195], v[96:99]
	v_mfma_f32_16x16x32_bf16 v[88:91], v[152:155], v[192:195], v[88:91]
	v_mfma_f32_16x16x32_bf16 v[80:83], v[144:147], v[200:203], v[80:83]
	v_mfma_f32_16x16x32_bf16 v[72:75], v[152:155], v[200:203], v[72:75]
	s_setprio 0
	s_setprio 1
	v_mfma_f32_16x16x32_bf16 v[116:119], v[156:159], v[172:175], v[116:119]
	v_mfma_f32_16x16x32_bf16 v[108:111], v[164:167], v[172:175], v[108:111]
	v_mfma_f32_16x16x32_bf16 v[100:103], v[156:159], v[180:183], v[100:103]
	v_mfma_f32_16x16x32_bf16 v[92:95], v[164:167], v[180:183], v[92:95]
	v_mfma_f32_16x16x32_bf16 v[84:87], v[156:159], v[188:191], v[84:87]
	v_mfma_f32_16x16x32_bf16 v[76:79], v[164:167], v[188:191], v[76:79]
	v_mfma_f32_16x16x32_bf16 v[68:71], v[156:159], v[196:199], v[68:71]
	v_mfma_f32_16x16x32_bf16 v[64:67], v[164:167], v[196:199], v[64:67]
	v_mfma_f32_16x16x32_bf16 v[116:119], v[160:163], v[176:179], v[116:119]
	v_mfma_f32_16x16x32_bf16 v[108:111], v[168:171], v[176:179], v[108:111]
	v_mfma_f32_16x16x32_bf16 v[100:103], v[160:163], v[184:187], v[100:103]
	v_mfma_f32_16x16x32_bf16 v[92:95], v[168:171], v[184:187], v[92:95]
	v_mfma_f32_16x16x32_bf16 v[84:87], v[160:163], v[192:195], v[84:87]
	v_mfma_f32_16x16x32_bf16 v[76:79], v[168:171], v[192:195], v[76:79]
	v_mfma_f32_16x16x32_bf16 v[68:71], v[160:163], v[200:203], v[68:71]
	v_mfma_f32_16x16x32_bf16 v[64:67], v[168:171], v[200:203], v[64:67]
	s_setprio 0
	s_barrier
	s_add_u32 s10, s26, 0x80
	s_addc_u32 s11, s27, 0
	s_add_i32 s28, s55, s31
	s_mov_b32 m0, s28
	ds_read_b128 v[172:175], v139 offset:49152
	ds_read_b128 v[176:179], v139 offset:50176
	ds_read_b128 v[180:183], v139 offset:51200
	ds_read_b128 v[184:187], v139 offset:52224
	ds_read_b128 v[188:191], v139 offset:53248
	ds_read_b128 v[192:195], v139 offset:54272
	ds_read_b128 v[196:199], v139 offset:55296
	ds_read_b128 v[200:203], v139 offset:56320
	global_load_lds_dwordx4 v128, s[10:11]
	s_add_i32 m0, s28, 0x2000
	v_lshl_add_u64 v[204:205], s[10:11], 0, v[130:131]
	s_add_u32 s10, s26, 0x2b0080
	s_addc_u32 s11, s27, 0
	s_add_i32 s26, s56, s31
	global_load_lds_dwordx4 v[204:205], off
	s_mov_b32 m0, s26
	s_nop 0
	global_load_lds_dwordx4 v128, s[10:11]
	s_add_i32 m0, s26, 0x2000
	s_nop 0
	global_load_lds_dwordx4 v130, s[10:11]
	s_waitcnt vmcnt(4)
	s_waitcnt lgkmcnt(0)
	s_barrier
	s_setprio 1
	s_waitcnt lgkmcnt(0)
	v_mfma_f32_16x16x32_bf16 v[60:63], v[140:143], v[172:175], v[60:63]
	v_mfma_f32_16x16x32_bf16 v[56:59], v[148:151], v[172:175], v[56:59]
	v_mfma_f32_16x16x32_bf16 v[48:51], v[140:143], v[180:183], v[48:51]
	v_mfma_f32_16x16x32_bf16 v[40:43], v[148:151], v[180:183], v[40:43]
	v_mfma_f32_16x16x32_bf16 v[32:35], v[140:143], v[188:191], v[32:35]
	v_mfma_f32_16x16x32_bf16 v[24:27], v[148:151], v[188:191], v[24:27]
	v_mfma_f32_16x16x32_bf16 v[16:19], v[140:143], v[196:199], v[16:19]
	v_mfma_f32_16x16x32_bf16 v[8:11], v[148:151], v[196:199], v[8:11]
	v_mfma_f32_16x16x32_bf16 v[60:63], v[144:147], v[176:179], v[60:63]
	v_mfma_f32_16x16x32_bf16 v[56:59], v[152:155], v[176:179], v[56:59]
	v_mfma_f32_16x16x32_bf16 v[48:51], v[144:147], v[184:187], v[48:51]
	v_mfma_f32_16x16x32_bf16 v[40:43], v[152:155], v[184:187], v[40:43]
	v_mfma_f32_16x16x32_bf16 v[32:35], v[144:147], v[192:195], v[32:35]
	v_mfma_f32_16x16x32_bf16 v[24:27], v[152:155], v[192:195], v[24:27]
	v_mfma_f32_16x16x32_bf16 v[16:19], v[144:147], v[200:203], v[16:19]
	v_mfma_f32_16x16x32_bf16 v[8:11], v[152:155], v[200:203], v[8:11]
	s_setprio 0
	s_setprio 1
	v_mfma_f32_16x16x32_bf16 v[52:55], v[156:159], v[172:175], v[52:55]
	v_mfma_f32_16x16x32_bf16 v[44:47], v[164:167], v[172:175], v[44:47]
	v_mfma_f32_16x16x32_bf16 v[36:39], v[156:159], v[180:183], v[36:39]
	v_mfma_f32_16x16x32_bf16 v[28:31], v[164:167], v[180:183], v[28:31]
	v_mfma_f32_16x16x32_bf16 v[20:23], v[156:159], v[188:191], v[20:23]
	v_mfma_f32_16x16x32_bf16 v[12:15], v[164:167], v[188:191], v[12:15]
	v_mfma_f32_16x16x32_bf16 v[4:7], v[156:159], v[196:199], v[4:7]
	v_mfma_f32_16x16x32_bf16 v[0:3], v[164:167], v[196:199], v[0:3]
	v_mfma_f32_16x16x32_bf16 v[52:55], v[160:163], v[176:179], v[52:55]
	v_mfma_f32_16x16x32_bf16 v[44:47], v[168:171], v[176:179], v[44:47]
	v_mfma_f32_16x16x32_bf16 v[36:39], v[160:163], v[184:187], v[36:39]
	v_mfma_f32_16x16x32_bf16 v[28:31], v[168:171], v[184:187], v[28:31]
	v_mfma_f32_16x16x32_bf16 v[20:23], v[160:163], v[192:195], v[20:23]
	v_mfma_f32_16x16x32_bf16 v[12:15], v[168:171], v[192:195], v[12:15]
	v_mfma_f32_16x16x32_bf16 v[4:7], v[160:163], v[200:203], v[4:7]
	v_mfma_f32_16x16x32_bf16 v[0:3], v[168:171], v[200:203], v[0:3]
	s_setprio 0
	s_barrier
	s_add_i32 s54, s54, 2
	s_add_u32 s52, s52, 0x100
	s_addc_u32 s53, s53, 0
	s_cmpk_gt_u32 s54, 0xa9
	s_mov_b64 s[10:11], s[22:23]
	s_cbranch_scc0 .LBB0_793
	s_and_b64 vcc, exec, s[12:13]
	s_cbranch_vccz .LBB0_796
	s_barrier

; #define PG8_WAIT_V(n) asm volatile("s_waitcnt vmcnt(" #n ")" ::: "memory")
; #define PG8_WAIT_L(n) asm volatile("s_waitcnt lgkmcnt(" #n ")" ::: "memory")
; #define PG8_BAR __builtin_amdgcn_s_barrier()
; #define PG8_SCHED __builtin_amdgcn_sched_barrier(0)
;     ...
;         for (int t = 0; t < nt; t += 2) {
;             const bool last = (t == nt - 2);
;             const char* a1 = cA + (size_t)(t + 1) * kstep;
;             const char* a2 = last ? nA : cA + (size_t)(t + 2) * kstep; const char* b2 = last ? nB : cB + (size_t)(t + 2) * kstep;
;             const char* a3 = a2 + kstep; const char* b3 = b2 + kstep;
;             if (last && has_next) S.a_ready(nxt);
;             if constexpr (SP2) {
;             PG8_LDB(B0, 0, 0); PG8_LDB(B1, 0, 1); PG8_SCHED; PG8_LDA(At, 0, 0); PG8_STAGE(PG8_SA(1, 1), a1 + hstepA, voffA);
;             PG8_WAIT_V(8); PG8_WAIT_L(0); PG8_BAR; PG8_MMA(0, 0, At, B0); PG8_MMA(0, 1, At, B1); PG8_BAR; PG8_SCHED;
;             if constexpr (!HALFU) PG8_LDA(At, 0, 1); PG8_STAGE(PG8_SB(0, 0), b2, voffB); PG8_STAGE(PG8_SB(0, 1), b2 + hstep, voffB); PG8_STAGE(PG8_SA(0, 0), a2, voffA);
;             PG8_WAIT_V(8); PG8_WAIT_L(0); PG8_BAR; if constexpr (!HALFU) { PG8_MMA(1, 0, At, B0); PG8_MMA(1, 1, At, B1); } PG8_BAR; PG8_SCHED;
.LBB0_1200:
	s_add_u32 s98, s10, 0x80
	s_addc_u32 s99, s11, 0
	s_mov_b32 m0, s68
	s_nop 0
	global_load_lds_dwordx4 v136, s[98:99]
	s_mov_b32 m0, s69
	s_nop 0
	global_load_lds_dwordx4 v140, s[98:99]
	s_add_u32 s26, s10, 0x100
	s_addc_u32 s27, s11, 0
	s_cmp_eq_u32 s76, 28
	s_cselect_b32 s50, s9, s26
	s_cselect_b32 s51, s7, s27
	s_cselect_b32 s48, s43, s74
	s_cselect_b32 s49, s41, s75
	s_add_u32 s30, s50, 0x80
	s_addc_u32 s31, s51, 0
	s_add_u32 s10, s10, 0x80080
	s_addc_u32 s11, s11, 0
	s_add_i32 m0, s57, 0xc000
	s_nop 0
	global_load_lds_dwordx4 v136, s[10:11]
	s_add_i32 m0, s57, 0xe000
	s_nop 0
	global_load_lds_dwordx4 v140, s[10:11]
	ds_read_b128 v[128:131], v149
	ds_read_b128 v[132:135], v149 offset:1024
	ds_read_b128 v[154:157], v149 offset:2048
	ds_read_b128 v[158:161], v149 offset:3072
	ds_read_b128 v[162:165], v150
	ds_read_b128 v[166:169], v150 offset:1024
	ds_read_b128 v[170:173], v150 offset:2048
	ds_read_b128 v[174:177], v150 offset:3072
	ds_read_b128 v[178:181], v151
	ds_read_b128 v[182:185], v151 offset:1024
	ds_read_b128 v[186:189], v151 offset:2048
	ds_read_b128 v[190:193], v151 offset:3072
	ds_read_b128 v[194:197], v151 offset:4096
	ds_read_b128 v[198:201], v151 offset:5120
	ds_read_b128 v[202:205], v151 offset:6144
	ds_read_b128 v[206:209], v151 offset:7168
	s_waitcnt vmcnt(8)
	s_waitcnt lgkmcnt(0)
	s_barrier
	s_setprio 1
	s_waitcnt lgkmcnt(0)
	v_mfma_scale_f32_16x16x128_f8f6f4 v[124:127], v[128:135], v[178:185], v[124:127], v152, v152 op_sel_hi:[0,0,0]
	v_mfma_scale_f32_16x16x128_f8f6f4 v[120:123], v[154:161], v[178:185], v[120:123], v152, v152 op_sel_hi:[0,0,0]
	v_mfma_scale_f32_16x16x128_f8f6f4 v[108:111], v[128:135], v[186:193], v[108:111], v152, v152 op_sel_hi:[0,0,0]
	v_mfma_scale_f32_16x16x128_f8f6f4 v[104:107], v[154:161], v[186:193], v[104:107], v152, v152 op_sel_hi:[0,0,0]
	v_mfma_scale_f32_16x16x128_f8f6f4 v[210:213], v[128:135], v[194:201], v[92:95], v152, v152 op_sel_hi:[0,0,0]
	v_mfma_scale_f32_16x16x128_f8f6f4 v[214:217], v[154:161], v[194:201], v[88:91], v152, v152 op_sel_hi:[0,0,0]
	v_mfma_scale_f32_16x16x128_f8f6f4 v[218:221], v[128:135], v[202:209], v[76:79], v152, v152 op_sel_hi:[0,0,0]
	v_mfma_scale_f32_16x16x128_f8f6f4 v[222:225], v[154:161], v[202:209], v[72:75], v152, v152 op_sel_hi:[0,0,0]
	s_setprio 0
	s_setprio 1
	v_mfma_scale_f32_16x16x128_f8f6f4 v[116:119], v[162:169], v[178:185], v[116:119], v152, v152 op_sel_hi:[0,0,0]
	v_mfma_scale_f32_16x16x128_f8f6f4 v[112:115], v[170:177], v[178:185], v[112:115], v152, v152 op_sel_hi:[0,0,0]
	v_mfma_scale_f32_16x16x128_f8f6f4 v[100:103], v[162:169], v[186:193], v[100:103], v152, v152 op_sel_hi:[0,0,0]
	v_mfma_scale_f32_16x16x128_f8f6f4 v[96:99], v[170:177], v[186:193], v[96:99], v152, v152 op_sel_hi:[0,0,0]
	v_mfma_scale_f32_16x16x128_f8f6f4 v[178:181], v[162:169], v[194:201], v[84:87], v152, v152 op_sel_hi:[0,0,0]
	v_mfma_scale_f32_16x16x128_f8f6f4 v[182:185], v[170:177], v[194:201], v[80:83], v152, v152 op_sel_hi:[0,0,0]
	v_mfma_scale_f32_16x16x128_f8f6f4 v[186:189], v[162:169], v[202:209], v[68:71], v152, v152 op_sel_hi:[0,0,0]
	v_mfma_scale_f32_16x16x128_f8f6f4 v[190:193], v[170:177], v[202:209], v[64:67], v152, v152 op_sel_hi:[0,0,0]
	s_setprio 0
	s_barrier
	s_add_i32 s10, s71, s56
	s_mov_b32 m0, s10
	s_nop 1
	global_load_lds_dwordx4 v138, s[48:49]
	s_add_i32 m0, s10, 0x2000
	s_add_u32 s10, s48, 0x80000
	s_addc_u32 s11, s49, 0
	s_add_i32 s77, s72, s56
	global_load_lds_dwordx4 v142, s[48:49]
	s_mov_b32 m0, s77
	s_nop 0
	global_load_lds_dwordx4 v138, s[10:11]
	s_add_i32 m0, s77, 0x2000
	s_nop 0
	global_load_lds_dwordx4 v142, s[10:11]
	ds_read_b128 v[64:67], v151 offset:16384
	ds_read_b128 v[68:71], v151 offset:17408
	ds_read_b128 v[72:75], v151 offset:18432
	ds_read_b128 v[76:79], v151 offset:19456
	ds_read_b128 v[80:83], v151 offset:20480
	ds_read_b128 v[84:87], v151 offset:21504
	ds_read_b128 v[88:91], v151 offset:22528
	ds_read_b128 v[92:95], v151 offset:23552
	s_waitcnt vmcnt(4)
	s_waitcnt lgkmcnt(0)
	s_barrier
	s_setprio 1
	s_waitcnt lgkmcnt(0)
	v_mfma_scale_f32_16x16x128_f8f6f4 v[60:63], v[128:135], v[64:71], v[60:63], v152, v152 op_sel_hi:[0,0,0]
	v_mfma_scale_f32_16x16x128_f8f6f4 v[56:59], v[154:161], v[64:71], v[56:59], v152, v152 op_sel_hi:[0,0,0]
	v_mfma_scale_f32_16x16x128_f8f6f4 v[194:197], v[128:135], v[72:79], v[44:47], v152, v152 op_sel_hi:[0,0,0]
	v_mfma_scale_f32_16x16x128_f8f6f4 v[198:201], v[154:161], v[72:79], v[40:43], v152, v152 op_sel_hi:[0,0,0]
	v_mfma_scale_f32_16x16x128_f8f6f4 v[202:205], v[128:135], v[80:87], v[28:31], v152, v152 op_sel_hi:[0,0,0]
	v_mfma_scale_f32_16x16x128_f8f6f4 v[206:209], v[154:161], v[80:87], v[24:27], v152, v152 op_sel_hi:[0,0,0]
	v_mfma_scale_f32_16x16x128_f8f6f4 v[226:229], v[128:135], v[88:95], v[12:15], v152, v152 op_sel_hi:[0,0,0]
	v_mfma_scale_f32_16x16x128_f8f6f4 v[230:233], v[154:161], v[88:95], v[8:11], v152, v152 op_sel_hi:[0,0,0]
	s_setprio 0
	s_setprio 1
	v_mfma_scale_f32_16x16x128_f8f6f4 v[52:55], v[162:169], v[64:71], v[52:55], v152, v152 op_sel_hi:[0,0,0]
	v_mfma_scale_f32_16x16x128_f8f6f4 v[48:51], v[170:177], v[64:71], v[48:51], v152, v152 op_sel_hi:[0,0,0]
	v_mfma_scale_f32_16x16x128_f8f6f4 v[234:237], v[162:169], v[72:79], v[36:39], v152, v152 op_sel_hi:[0,0,0]
	v_mfma_scale_f32_16x16x128_f8f6f4 v[238:241], v[170:177], v[72:79], v[32:35], v152, v152 op_sel_hi:[0,0,0]
	v_mfma_scale_f32_16x16x128_f8f6f4 v[242:245], v[162:169], v[80:87], v[20:23], v152, v152 op_sel_hi:[0,0,0]
	v_mfma_scale_f32_16x16x128_f8f6f4 v[246:249], v[170:177], v[80:87], v[16:19], v152, v152 op_sel_hi:[0,0,0]
	v_mfma_scale_f32_16x16x128_f8f6f4 v[250:253], v[162:169], v[88:95], v[4:7], v152, v152 op_sel_hi:[0,0,0]
	v_mfma_scale_f32_16x16x128_f8f6f4 v[144:147], v[170:177], v[88:95], v[0:3], v152, v152 op_sel_hi:[0,0,0]
	s_setprio 0
	s_barrier
; #define PG8_WAIT_V(n) asm volatile("s_waitcnt vmcnt(" #n ")" ::: "memory")
; #define PG8_WAIT_L(n) asm volatile("s_waitcnt lgkmcnt(" #n ")" ::: "memory")
; #define PG8_BAR __builtin_amdgcn_s_barrier()
; #define PG8_SCHED __builtin_amdgcn_sched_barrier(0)
;     ...
;             PG8_LDB(B0, 1, 0); PG8_LDB(B1, 1, 1); PG8_SCHED; PG8_LDA(At, 1, 0); PG8_STAGE(PG8_SA(0, 1), a2 + hstepA, voffA);
;             PG8_WAIT_V(8); PG8_WAIT_L(0); PG8_BAR; PG8_MMA(0, 0, At, B0); PG8_MMA(0, 1, At, B1); PG8_BAR; PG8_SCHED;
;             if constexpr (!HALFU) PG8_LDA(At, 1, 1); PG8_STAGE(PG8_SB(1, 0), b3, voffB); PG8_STAGE(PG8_SB(1, 1), b3 + hstep, voffB); PG8_STAGE(PG8_SA(1, 0), a3, voffA);
;             PG8_WAIT_V(8); PG8_WAIT_L(0); PG8_BAR; if constexpr (!HALFU) { PG8_MMA(1, 0, At, B0); PG8_MMA(1, 1, At, B1); } PG8_BAR; PG8_SCHED;
	s_mov_b32 m0, s57
	s_nop 0
	global_load_lds_dwordx4 v136, s[50:51]
	s_mov_b32 m0, s62
	s_nop 0
	global_load_lds_dwordx4 v140, s[50:51]
	s_add_i32 s77, 0, 0x18000
	s_add_i32 s78, 0, 0x1c000
	s_nop 1
	s_add_u32 s10, s50, 0x80000
	s_addc_u32 s11, s51, 0
	s_mov_b32 m0, s63
	s_nop 0
	global_load_lds_dwordx4 v136, s[10:11]
	s_mov_b32 m0, s64
	s_nop 0
	global_load_lds_dwordx4 v140, s[10:11]
	v_add_u32_e32 v8, s77, v148
	ds_read_b128 v[0:3], v8
	ds_read_b128 v[4:7], v8 offset:1024
	ds_read_b128 v[16:19], v8 offset:2048
	ds_read_b128 v[20:23], v8 offset:3072
	v_add_u32_e32 v8, s78, v148
	ds_read_b128 v[128:131], v8
	ds_read_b128 v[132:135], v8 offset:1024
	ds_read_b128 v[154:157], v8 offset:2048
	ds_read_b128 v[158:161], v8 offset:3072
	ds_read_b128 v[8:11], v151 offset:32768
	ds_read_b128 v[12:15], v151 offset:33792
	ds_read_b128 v[24:27], v151 offset:34816
	ds_read_b128 v[28:31], v151 offset:35840
	ds_read_b128 v[32:35], v151 offset:36864
	ds_read_b128 v[36:39], v151 offset:37888
	ds_read_b128 v[40:43], v151 offset:38912
	ds_read_b128 v[44:47], v151 offset:39936
	s_waitcnt vmcnt(8)
	s_waitcnt lgkmcnt(0)
	s_barrier
	s_setprio 1
	s_waitcnt lgkmcnt(0)
	v_mfma_scale_f32_16x16x128_f8f6f4 v[124:127], v[0:7], v[8:15], v[124:127], v152, v152 op_sel_hi:[0,0,0]
	v_mfma_scale_f32_16x16x128_f8f6f4 v[120:123], v[16:23], v[8:15], v[120:123], v152, v152 op_sel_hi:[0,0,0]
	v_mfma_scale_f32_16x16x128_f8f6f4 v[108:111], v[0:7], v[24:31], v[108:111], v152, v152 op_sel_hi:[0,0,0]
	v_mfma_scale_f32_16x16x128_f8f6f4 v[104:107], v[16:23], v[24:31], v[104:107], v152, v152 op_sel_hi:[0,0,0]
	v_mfma_scale_f32_16x16x128_f8f6f4 v[92:95], v[0:7], v[32:39], v[210:213], v152, v152 op_sel_hi:[0,0,0]
	v_mfma_scale_f32_16x16x128_f8f6f4 v[88:91], v[16:23], v[32:39], v[214:217], v152, v152 op_sel_hi:[0,0,0]
	v_mfma_scale_f32_16x16x128_f8f6f4 v[76:79], v[0:7], v[40:47], v[218:221], v152, v152 op_sel_hi:[0,0,0]
	v_mfma_scale_f32_16x16x128_f8f6f4 v[72:75], v[16:23], v[40:47], v[222:225], v152, v152 op_sel_hi:[0,0,0]
	s_setprio 0
	s_setprio 1
	v_mfma_scale_f32_16x16x128_f8f6f4 v[116:119], v[128:135], v[8:15], v[116:119], v152, v152 op_sel_hi:[0,0,0]
	v_mfma_scale_f32_16x16x128_f8f6f4 v[112:115], v[154:161], v[8:15], v[112:115], v152, v152 op_sel_hi:[0,0,0]
	v_mfma_scale_f32_16x16x128_f8f6f4 v[100:103], v[128:135], v[24:31], v[100:103], v152, v152 op_sel_hi:[0,0,0]
	v_mfma_scale_f32_16x16x128_f8f6f4 v[96:99], v[154:161], v[24:31], v[96:99], v152, v152 op_sel_hi:[0,0,0]
	v_mfma_scale_f32_16x16x128_f8f6f4 v[84:87], v[128:135], v[32:39], v[178:181], v152, v152 op_sel_hi:[0,0,0]
	v_mfma_scale_f32_16x16x128_f8f6f4 v[80:83], v[154:161], v[32:39], v[182:185], v152, v152 op_sel_hi:[0,0,0]
	v_mfma_scale_f32_16x16x128_f8f6f4 v[68:71], v[128:135], v[40:47], v[186:189], v152, v152 op_sel_hi:[0,0,0]
	v_mfma_scale_f32_16x16x128_f8f6f4 v[64:67], v[154:161], v[40:47], v[190:193], v152, v152 op_sel_hi:[0,0,0]
	s_setprio 0
	s_barrier
	s_add_u32 s10, s48, 0x80
	s_addc_u32 s11, s49, 0
	s_add_i32 s50, s77, s56
	s_mov_b32 m0, s50
	ds_read_b128 v[32:35], v151 offset:49152
	ds_read_b128 v[36:39], v151 offset:50176
	ds_read_b128 v[162:165], v151 offset:51200
	ds_read_b128 v[166:169], v151 offset:52224
	ds_read_b128 v[170:173], v151 offset:53248
	ds_read_b128 v[174:177], v151 offset:54272
	ds_read_b128 v[178:181], v151 offset:55296
	ds_read_b128 v[182:185], v151 offset:56320
	global_load_lds_dwordx4 v138, s[10:11]
	s_add_i32 m0, s50, 0x2000
	v_lshl_add_u64 v[8:9], s[10:11], 0, v[142:143]
	s_add_u32 s10, s48, 0x80080
	s_addc_u32 s11, s49, 0
	s_add_i32 s48, s78, s56
	global_load_lds_dwordx4 v[8:9], off
	s_mov_b32 m0, s48
	s_nop 0
	global_load_lds_dwordx4 v138, s[10:11]
	s_add_i32 m0, s48, 0x2000
	s_nop 0
	global_load_lds_dwordx4 v142, s[10:11]
	s_waitcnt vmcnt(4)
	s_waitcnt lgkmcnt(0)
	s_barrier
	s_setprio 1
	s_waitcnt lgkmcnt(0)
	v_mfma_scale_f32_16x16x128_f8f6f4 v[60:63], v[0:7], v[32:39], v[60:63], v152, v152 op_sel_hi:[0,0,0]
	v_mfma_scale_f32_16x16x128_f8f6f4 v[56:59], v[16:23], v[32:39], v[56:59], v152, v152 op_sel_hi:[0,0,0]
	v_mfma_scale_f32_16x16x128_f8f6f4 v[44:47], v[0:7], v[162:169], v[194:197], v152, v152 op_sel_hi:[0,0,0]
	v_mfma_scale_f32_16x16x128_f8f6f4 v[40:43], v[16:23], v[162:169], v[198:201], v152, v152 op_sel_hi:[0,0,0]
	v_mfma_scale_f32_16x16x128_f8f6f4 v[28:31], v[0:7], v[170:177], v[202:205], v152, v152 op_sel_hi:[0,0,0]
	v_mfma_scale_f32_16x16x128_f8f6f4 v[24:27], v[16:23], v[170:177], v[206:209], v152, v152 op_sel_hi:[0,0,0]
	v_mfma_scale_f32_16x16x128_f8f6f4 v[12:15], v[0:7], v[178:185], v[226:229], v152, v152 op_sel_hi:[0,0,0]
	v_mfma_scale_f32_16x16x128_f8f6f4 v[8:11], v[16:23], v[178:185], v[230:233], v152, v152 op_sel_hi:[0,0,0]
	s_setprio 0
	s_setprio 1
	v_mfma_scale_f32_16x16x128_f8f6f4 v[52:55], v[128:135], v[32:39], v[52:55], v152, v152 op_sel_hi:[0,0,0]
	v_mfma_scale_f32_16x16x128_f8f6f4 v[48:51], v[154:161], v[32:39], v[48:51], v152, v152 op_sel_hi:[0,0,0]
	v_mfma_scale_f32_16x16x128_f8f6f4 v[36:39], v[128:135], v[162:169], v[234:237], v152, v152 op_sel_hi:[0,0,0]
	v_mfma_scale_f32_16x16x128_f8f6f4 v[32:35], v[154:161], v[162:169], v[238:241], v152, v152 op_sel_hi:[0,0,0]
	v_mfma_scale_f32_16x16x128_f8f6f4 v[20:23], v[128:135], v[170:177], v[242:245], v152, v152 op_sel_hi:[0,0,0]
	v_mfma_scale_f32_16x16x128_f8f6f4 v[16:19], v[154:161], v[170:177], v[246:249], v152, v152 op_sel_hi:[0,0,0]
	v_mfma_scale_f32_16x16x128_f8f6f4 v[4:7], v[128:135], v[178:185], v[250:253], v152, v152 op_sel_hi:[0,0,0]
	v_mfma_scale_f32_16x16x128_f8f6f4 v[0:3], v[154:161], v[178:185], v[144:147], v152, v152 op_sel_hi:[0,0,0]
	s_setprio 0
	s_barrier
	s_add_i32 s76, s76, 2
	s_add_u32 s74, s74, 0x100
	s_addc_u32 s75, s75, 0
	s_cmp_gt_u32 s76, 29
	s_mov_b64 s[10:11], s[26:27]
	s_cbranch_scc0 .LBB0_1200
	s_and_b64 vcc, exec, s[36:37]
	s_cbranch_vccz .LBB0_1203
	s_barrier

; #define PG8_WAIT_V(n) asm volatile("s_waitcnt vmcnt(" #n ")" ::: "memory")
; #define PG8_WAIT_L(n) asm volatile("s_waitcnt lgkmcnt(" #n ")" ::: "memory")
; #define PG8_BAR __builtin_amdgcn_s_barrier()
; #define PG8_SCHED __builtin_amdgcn_sched_barrier(0)
;     ...
;         for (int t = 0; t < nt; t += 2) {
;             const bool last = (t == nt - 2);
;             const char* a1 = cA + (size_t)(t + 1) * kstep;
;             const char* a2 = last ? nA : cA + (size_t)(t + 2) * kstep; const char* b2 = last ? nB : cB + (size_t)(t + 2) * kstep;
;             const char* a3 = a2 + kstep; const char* b3 = b2 + kstep;
;             if (last && has_next) S.a_ready(nxt);
;             if constexpr (SP2) {
;             PG8_LDB(B0, 0, 0); PG8_LDB(B1, 0, 1); PG8_SCHED; PG8_LDA(At, 0, 0); PG8_STAGE(PG8_SA(1, 1), a1 + hstepA, voffA);
;             PG8_WAIT_V(8); PG8_WAIT_L(0); PG8_BAR; PG8_MMA(0, 0, At, B0); PG8_MMA(0, 1, At, B1); PG8_BAR; PG8_SCHED;
;             if constexpr (!HALFU) PG8_LDA(At, 0, 1); PG8_STAGE(PG8_SB(0, 0), b2, voffB); PG8_STAGE(PG8_SB(0, 1), b2 + hstep, voffB); PG8_STAGE(PG8_SA(0, 0), a2, voffA);
;             PG8_WAIT_V(8); PG8_WAIT_L(0); PG8_BAR; if constexpr (!HALFU) { PG8_MMA(1, 0, At, B0); PG8_MMA(1, 1, At, B1); } PG8_BAR; PG8_SCHED;
.LBB0_1370:
	s_add_u32 s98, s10, 0x80
	s_addc_u32 s99, s11, 0
	s_mov_b32 m0, s67
	s_nop 0
	global_load_lds_dwordx4 v136, s[98:99]
	s_mov_b32 m0, s68
	s_nop 0
	global_load_lds_dwordx4 v140, s[98:99]
	s_add_u32 s12, s10, 0x100
	s_addc_u32 s13, s11, 0
	s_cmp_eq_u32 s53, 60
	s_cselect_b32 s50, s7, s12
	s_cselect_b32 s51, s0, s13
	s_cselect_b32 s48, s39, s41
	s_cselect_b32 s49, s9, s52
	s_add_u32 s46, s50, 0x80
	s_addc_u32 s47, s51, 0
	s_add_u32 s10, s10, 0x100080
	s_addc_u32 s11, s11, 0
	s_add_i32 m0, s37, 0xc000
	s_nop 0
	global_load_lds_dwordx4 v136, s[10:11]
	s_add_i32 m0, s37, 0xe000
	s_nop 0
	global_load_lds_dwordx4 v140, s[10:11]
	ds_read_b128 v[128:131], v163
	ds_read_b128 v[132:135], v163 offset:1024
	ds_read_b128 v[150:153], v163 offset:2048
	ds_read_b128 v[154:157], v163 offset:3072
	ds_read_b128 v[158:161], v164
	ds_read_b128 v[166:169], v164 offset:1024
	ds_read_b128 v[170:173], v164 offset:2048
	ds_read_b128 v[174:177], v164 offset:3072
	ds_read_b128 v[178:181], v165
	ds_read_b128 v[182:185], v165 offset:1024
	ds_read_b128 v[186:189], v165 offset:2048
	ds_read_b128 v[190:193], v165 offset:3072
	ds_read_b128 v[194:197], v165 offset:4096
	ds_read_b128 v[198:201], v165 offset:5120
	ds_read_b128 v[202:205], v165 offset:6144
	ds_read_b128 v[206:209], v165 offset:7168
	s_waitcnt vmcnt(8)
	s_waitcnt lgkmcnt(0)
	s_barrier
	s_setprio 1
	s_waitcnt lgkmcnt(0)
	v_mfma_f32_16x16x32_bf16 v[124:127], v[128:131], v[178:181], v[124:127]
	v_mfma_f32_16x16x32_bf16 v[120:123], v[150:153], v[178:181], v[120:123]
	v_mfma_f32_16x16x32_bf16 v[108:111], v[128:131], v[186:189], v[108:111]
	v_mfma_f32_16x16x32_bf16 v[104:107], v[150:153], v[186:189], v[104:107]
	v_mfma_f32_16x16x32_bf16 v[92:95], v[128:131], v[194:197], v[92:95]
	v_mfma_f32_16x16x32_bf16 v[88:91], v[150:153], v[194:197], v[88:91]
	v_mfma_f32_16x16x32_bf16 v[76:79], v[128:131], v[202:205], v[76:79]
	v_mfma_f32_16x16x32_bf16 v[72:75], v[150:153], v[202:205], v[72:75]
	v_mfma_f32_16x16x32_bf16 v[124:127], v[132:135], v[182:185], v[124:127]
	v_mfma_f32_16x16x32_bf16 v[120:123], v[154:157], v[182:185], v[120:123]
	v_mfma_f32_16x16x32_bf16 v[108:111], v[132:135], v[190:193], v[108:111]
	v_mfma_f32_16x16x32_bf16 v[104:107], v[154:157], v[190:193], v[104:107]
	v_mfma_f32_16x16x32_bf16 v[92:95], v[132:135], v[198:201], v[92:95]
	v_mfma_f32_16x16x32_bf16 v[88:91], v[154:157], v[198:201], v[88:91]
	v_mfma_f32_16x16x32_bf16 v[76:79], v[132:135], v[206:209], v[76:79]
	v_mfma_f32_16x16x32_bf16 v[72:75], v[154:157], v[206:209], v[72:75]
	s_setprio 0
	s_setprio 1
	v_mfma_f32_16x16x32_bf16 v[116:119], v[158:161], v[178:181], v[116:119]
	v_mfma_f32_16x16x32_bf16 v[112:115], v[170:173], v[178:181], v[112:115]
	v_mfma_f32_16x16x32_bf16 v[100:103], v[158:161], v[186:189], v[100:103]
	v_mfma_f32_16x16x32_bf16 v[96:99], v[170:173], v[186:189], v[96:99]
	v_mfma_f32_16x16x32_bf16 v[84:87], v[158:161], v[194:197], v[84:87]
	v_mfma_f32_16x16x32_bf16 v[80:83], v[170:173], v[194:197], v[80:83]
	v_mfma_f32_16x16x32_bf16 v[68:71], v[158:161], v[202:205], v[68:71]
	v_mfma_f32_16x16x32_bf16 v[64:67], v[170:173], v[202:205], v[64:67]
	v_mfma_f32_16x16x32_bf16 v[116:119], v[166:169], v[182:185], v[116:119]
	v_mfma_f32_16x16x32_bf16 v[112:115], v[174:177], v[182:185], v[112:115]
	v_mfma_f32_16x16x32_bf16 v[100:103], v[166:169], v[190:193], v[100:103]
	v_mfma_f32_16x16x32_bf16 v[96:99], v[174:177], v[190:193], v[96:99]
	v_mfma_f32_16x16x32_bf16 v[84:87], v[166:169], v[198:201], v[84:87]
	v_mfma_f32_16x16x32_bf16 v[80:83], v[174:177], v[198:201], v[80:83]
	v_mfma_f32_16x16x32_bf16 v[68:71], v[166:169], v[206:209], v[68:71]
	v_mfma_f32_16x16x32_bf16 v[64:67], v[174:177], v[206:209], v[64:67]
	s_setprio 0
	s_barrier
	s_add_i32 s10, s71, s21
	s_mov_b32 m0, s10
	s_nop 0
	global_load_lds_dwordx4 v138, s[48:49]
	s_add_i32 m0, s10, 0x2000
	s_add_u32 s10, s48, 0x100000
	s_addc_u32 s11, s49, 0
	s_add_i32 s54, s72, s21
	global_load_lds_dwordx4 v142, s[48:49]
	s_mov_b32 m0, s54
	s_nop 0
	global_load_lds_dwordx4 v138, s[10:11]
	s_add_i32 m0, s54, 0x2000
	s_nop 0
	global_load_lds_dwordx4 v142, s[10:11]
	ds_read_b128 v[178:181], v165 offset:16384
	ds_read_b128 v[182:185], v165 offset:17408
	ds_read_b128 v[186:189], v165 offset:18432
	ds_read_b128 v[190:193], v165 offset:19456
	ds_read_b128 v[194:197], v165 offset:20480
	ds_read_b128 v[198:201], v165 offset:21504
	ds_read_b128 v[202:205], v165 offset:22528
	ds_read_b128 v[206:209], v165 offset:23552
	s_waitcnt vmcnt(4)
	s_waitcnt lgkmcnt(0)
	s_barrier
	s_setprio 1
	s_waitcnt lgkmcnt(0)
	v_mfma_f32_16x16x32_bf16 v[60:63], v[128:131], v[178:181], v[60:63]
	v_mfma_f32_16x16x32_bf16 v[56:59], v[150:153], v[178:181], v[56:59]
	v_mfma_f32_16x16x32_bf16 v[44:47], v[128:131], v[186:189], v[44:47]
	v_mfma_f32_16x16x32_bf16 v[40:43], v[150:153], v[186:189], v[40:43]
	v_mfma_f32_16x16x32_bf16 v[28:31], v[128:131], v[194:197], v[28:31]
	v_mfma_f32_16x16x32_bf16 v[24:27], v[150:153], v[194:197], v[24:27]
	v_mfma_f32_16x16x32_bf16 v[12:15], v[128:131], v[202:205], v[12:15]
	v_mfma_f32_16x16x32_bf16 v[8:11], v[150:153], v[202:205], v[8:11]
	v_mfma_f32_16x16x32_bf16 v[60:63], v[132:135], v[182:185], v[60:63]
	v_mfma_f32_16x16x32_bf16 v[56:59], v[154:157], v[182:185], v[56:59]
	v_mfma_f32_16x16x32_bf16 v[44:47], v[132:135], v[190:193], v[44:47]
	v_mfma_f32_16x16x32_bf16 v[40:43], v[154:157], v[190:193], v[40:43]
	v_mfma_f32_16x16x32_bf16 v[28:31], v[132:135], v[198:201], v[28:31]
	v_mfma_f32_16x16x32_bf16 v[24:27], v[154:157], v[198:201], v[24:27]
	v_mfma_f32_16x16x32_bf16 v[12:15], v[132:135], v[206:209], v[12:15]
	v_mfma_f32_16x16x32_bf16 v[8:11], v[154:157], v[206:209], v[8:11]
	s_setprio 0
	s_setprio 1
	v_mfma_f32_16x16x32_bf16 v[52:55], v[158:161], v[178:181], v[52:55]
	v_mfma_f32_16x16x32_bf16 v[48:51], v[170:173], v[178:181], v[48:51]
	v_mfma_f32_16x16x32_bf16 v[36:39], v[158:161], v[186:189], v[36:39]
	v_mfma_f32_16x16x32_bf16 v[32:35], v[170:173], v[186:189], v[32:35]
	v_mfma_f32_16x16x32_bf16 v[20:23], v[158:161], v[194:197], v[20:23]
	v_mfma_f32_16x16x32_bf16 v[16:19], v[170:173], v[194:197], v[16:19]
	v_mfma_f32_16x16x32_bf16 v[4:7], v[158:161], v[202:205], v[4:7]
	v_mfma_f32_16x16x32_bf16 v[0:3], v[170:173], v[202:205], v[0:3]
	v_mfma_f32_16x16x32_bf16 v[52:55], v[166:169], v[182:185], v[52:55]
	v_mfma_f32_16x16x32_bf16 v[48:51], v[174:177], v[182:185], v[48:51]
	v_mfma_f32_16x16x32_bf16 v[36:39], v[166:169], v[190:193], v[36:39]
	v_mfma_f32_16x16x32_bf16 v[32:35], v[174:177], v[190:193], v[32:35]
	v_mfma_f32_16x16x32_bf16 v[20:23], v[166:169], v[198:201], v[20:23]
	v_mfma_f32_16x16x32_bf16 v[16:19], v[174:177], v[198:201], v[16:19]
	v_mfma_f32_16x16x32_bf16 v[4:7], v[166:169], v[206:209], v[4:7]
	v_mfma_f32_16x16x32_bf16 v[0:3], v[174:177], v[206:209], v[0:3]
	s_setprio 0
	s_barrier
; #define PG8_WAIT_V(n) asm volatile("s_waitcnt vmcnt(" #n ")" ::: "memory")
; #define PG8_WAIT_L(n) asm volatile("s_waitcnt lgkmcnt(" #n ")" ::: "memory")
; #define PG8_BAR __builtin_amdgcn_s_barrier()
; #define PG8_SCHED __builtin_amdgcn_sched_barrier(0)
;     ...
;             PG8_LDB(B0, 1, 0); PG8_LDB(B1, 1, 1); PG8_SCHED; PG8_LDA(At, 1, 0); PG8_STAGE(PG8_SA(0, 1), a2 + hstepA, voffA);
;             PG8_WAIT_V(8); PG8_WAIT_L(0); PG8_BAR; PG8_MMA(0, 0, At, B0); PG8_MMA(0, 1, At, B1); PG8_BAR; PG8_SCHED;
;             if constexpr (!HALFU) PG8_LDA(At, 1, 1); PG8_STAGE(PG8_SB(1, 0), b3, voffB); PG8_STAGE(PG8_SB(1, 1), b3 + hstep, voffB); PG8_STAGE(PG8_SA(1, 0), a3, voffA);
;             PG8_WAIT_V(8); PG8_WAIT_L(0); PG8_BAR; if constexpr (!HALFU) { PG8_MMA(1, 0, At, B0); PG8_MMA(1, 1, At, B1); } PG8_BAR; PG8_SCHED;
	s_mov_b32 m0, s37
	s_nop 0
	global_load_lds_dwordx4 v136, s[50:51]
	s_mov_b32 m0, s62
	s_nop 0
	global_load_lds_dwordx4 v140, s[50:51]
	s_add_i32 s54, 0, 0x18000
	s_add_i32 s55, 0, 0x1c000
	s_add_u32 s10, s50, 0x100000
	s_addc_u32 s11, s51, 0
	s_mov_b32 m0, s63
	s_nop 0
	global_load_lds_dwordx4 v136, s[10:11]
	s_mov_b32 m0, s64
	s_nop 0
	global_load_lds_dwordx4 v140, s[10:11]
	v_add_u32_e32 v144, s54, v162
	ds_read_b128 v[128:131], v144
	ds_read_b128 v[132:135], v144 offset:1024
	ds_read_b128 v[150:153], v144 offset:2048
	ds_read_b128 v[154:157], v144 offset:3072
	v_add_u32_e32 v144, s55, v162
	ds_read_b128 v[158:161], v144
	ds_read_b128 v[166:169], v144 offset:1024
	ds_read_b128 v[170:173], v144 offset:2048
	ds_read_b128 v[174:177], v144 offset:3072
	ds_read_b128 v[178:181], v165 offset:32768
	ds_read_b128 v[182:185], v165 offset:33792
	ds_read_b128 v[186:189], v165 offset:34816
	ds_read_b128 v[190:193], v165 offset:35840
	ds_read_b128 v[194:197], v165 offset:36864
	ds_read_b128 v[198:201], v165 offset:37888
	ds_read_b128 v[202:205], v165 offset:38912
	ds_read_b128 v[206:209], v165 offset:39936
	s_waitcnt vmcnt(8)
	s_waitcnt lgkmcnt(0)
	s_barrier
	s_setprio 1
	s_waitcnt lgkmcnt(0)
	v_mfma_f32_16x16x32_bf16 v[124:127], v[128:131], v[178:181], v[124:127]
	v_mfma_f32_16x16x32_bf16 v[120:123], v[150:153], v[178:181], v[120:123]
	v_mfma_f32_16x16x32_bf16 v[108:111], v[128:131], v[186:189], v[108:111]
	v_mfma_f32_16x16x32_bf16 v[104:107], v[150:153], v[186:189], v[104:107]
	v_mfma_f32_16x16x32_bf16 v[92:95], v[128:131], v[194:197], v[92:95]
	v_mfma_f32_16x16x32_bf16 v[88:91], v[150:153], v[194:197], v[88:91]
	v_mfma_f32_16x16x32_bf16 v[76:79], v[128:131], v[202:205], v[76:79]
	v_mfma_f32_16x16x32_bf16 v[72:75], v[150:153], v[202:205], v[72:75]
	v_mfma_f32_16x16x32_bf16 v[124:127], v[132:135], v[182:185], v[124:127]
	v_mfma_f32_16x16x32_bf16 v[120:123], v[154:157], v[182:185], v[120:123]
	v_mfma_f32_16x16x32_bf16 v[108:111], v[132:135], v[190:193], v[108:111]
	v_mfma_f32_16x16x32_bf16 v[104:107], v[154:157], v[190:193], v[104:107]
	v_mfma_f32_16x16x32_bf16 v[92:95], v[132:135], v[198:201], v[92:95]
	v_mfma_f32_16x16x32_bf16 v[88:91], v[154:157], v[198:201], v[88:91]
	v_mfma_f32_16x16x32_bf16 v[76:79], v[132:135], v[206:209], v[76:79]
	v_mfma_f32_16x16x32_bf16 v[72:75], v[154:157], v[206:209], v[72:75]
	s_setprio 0
	s_setprio 1
	v_mfma_f32_16x16x32_bf16 v[116:119], v[158:161], v[178:181], v[116:119]
	v_mfma_f32_16x16x32_bf16 v[112:115], v[170:173], v[178:181], v[112:115]
	v_mfma_f32_16x16x32_bf16 v[100:103], v[158:161], v[186:189], v[100:103]
	v_mfma_f32_16x16x32_bf16 v[96:99], v[170:173], v[186:189], v[96:99]
	v_mfma_f32_16x16x32_bf16 v[84:87], v[158:161], v[194:197], v[84:87]
	v_mfma_f32_16x16x32_bf16 v[80:83], v[170:173], v[194:197], v[80:83]
	v_mfma_f32_16x16x32_bf16 v[68:71], v[158:161], v[202:205], v[68:71]
	v_mfma_f32_16x16x32_bf16 v[64:67], v[170:173], v[202:205], v[64:67]
	v_mfma_f32_16x16x32_bf16 v[116:119], v[166:169], v[182:185], v[116:119]
	v_mfma_f32_16x16x32_bf16 v[112:115], v[174:177], v[182:185], v[112:115]
	v_mfma_f32_16x16x32_bf16 v[100:103], v[166:169], v[190:193], v[100:103]
	v_mfma_f32_16x16x32_bf16 v[96:99], v[174:177], v[190:193], v[96:99]
	v_mfma_f32_16x16x32_bf16 v[84:87], v[166:169], v[198:201], v[84:87]
	v_mfma_f32_16x16x32_bf16 v[80:83], v[174:177], v[198:201], v[80:83]
	v_mfma_f32_16x16x32_bf16 v[68:71], v[166:169], v[206:209], v[68:71]
	v_mfma_f32_16x16x32_bf16 v[64:67], v[174:177], v[206:209], v[64:67]
	s_setprio 0
	s_barrier
	s_add_u32 s10, s48, 0x80
	s_addc_u32 s11, s49, 0
	s_add_i32 s50, s54, s21
	s_mov_b32 m0, s50
	ds_read_b128 v[178:181], v165 offset:49152
	ds_read_b128 v[182:185], v165 offset:50176
	ds_read_b128 v[186:189], v165 offset:51200
	ds_read_b128 v[190:193], v165 offset:52224
	ds_read_b128 v[194:197], v165 offset:53248
	ds_read_b128 v[198:201], v165 offset:54272
	ds_read_b128 v[202:205], v165 offset:55296
	ds_read_b128 v[206:209], v165 offset:56320
	global_load_lds_dwordx4 v138, s[10:11]
	s_add_i32 m0, s50, 0x2000
	v_lshl_add_u64 v[210:211], s[10:11], 0, v[142:143]
	s_add_u32 s10, s48, 0x100080
	s_addc_u32 s11, s49, 0
	s_add_i32 s48, s55, s21
	global_load_lds_dwordx4 v[210:211], off
	s_mov_b32 m0, s48
	s_nop 0
	global_load_lds_dwordx4 v138, s[10:11]
	s_add_i32 m0, s48, 0x2000
	s_nop 0
	global_load_lds_dwordx4 v142, s[10:11]
	s_waitcnt vmcnt(4)
	s_waitcnt lgkmcnt(0)
	s_barrier
	s_setprio 1
	s_waitcnt lgkmcnt(0)
	v_mfma_f32_16x16x32_bf16 v[60:63], v[128:131], v[178:181], v[60:63]
	v_mfma_f32_16x16x32_bf16 v[56:59], v[150:153], v[178:181], v[56:59]
	v_mfma_f32_16x16x32_bf16 v[44:47], v[128:131], v[186:189], v[44:47]
	v_mfma_f32_16x16x32_bf16 v[40:43], v[150:153], v[186:189], v[40:43]
	v_mfma_f32_16x16x32_bf16 v[28:31], v[128:131], v[194:197], v[28:31]
	v_mfma_f32_16x16x32_bf16 v[24:27], v[150:153], v[194:197], v[24:27]
	v_mfma_f32_16x16x32_bf16 v[12:15], v[128:131], v[202:205], v[12:15]
	v_mfma_f32_16x16x32_bf16 v[8:11], v[150:153], v[202:205], v[8:11]
	v_mfma_f32_16x16x32_bf16 v[60:63], v[132:135], v[182:185], v[60:63]
	v_mfma_f32_16x16x32_bf16 v[56:59], v[154:157], v[182:185], v[56:59]
	v_mfma_f32_16x16x32_bf16 v[44:47], v[132:135], v[190:193], v[44:47]
	v_mfma_f32_16x16x32_bf16 v[40:43], v[154:157], v[190:193], v[40:43]
	v_mfma_f32_16x16x32_bf16 v[28:31], v[132:135], v[198:201], v[28:31]
	v_mfma_f32_16x16x32_bf16 v[24:27], v[154:157], v[198:201], v[24:27]
	v_mfma_f32_16x16x32_bf16 v[12:15], v[132:135], v[206:209], v[12:15]
	v_mfma_f32_16x16x32_bf16 v[8:11], v[154:157], v[206:209], v[8:11]
	s_setprio 0
	s_setprio 1
	v_mfma_f32_16x16x32_bf16 v[52:55], v[158:161], v[178:181], v[52:55]
	v_mfma_f32_16x16x32_bf16 v[48:51], v[170:173], v[178:181], v[48:51]
	v_mfma_f32_16x16x32_bf16 v[36:39], v[158:161], v[186:189], v[36:39]
	v_mfma_f32_16x16x32_bf16 v[32:35], v[170:173], v[186:189], v[32:35]
	v_mfma_f32_16x16x32_bf16 v[20:23], v[158:161], v[194:197], v[20:23]
	v_mfma_f32_16x16x32_bf16 v[16:19], v[170:173], v[194:197], v[16:19]
	v_mfma_f32_16x16x32_bf16 v[4:7], v[158:161], v[202:205], v[4:7]
	v_mfma_f32_16x16x32_bf16 v[0:3], v[170:173], v[202:205], v[0:3]
	v_mfma_f32_16x16x32_bf16 v[52:55], v[166:169], v[182:185], v[52:55]
	v_mfma_f32_16x16x32_bf16 v[48:51], v[174:177], v[182:185], v[48:51]
	v_mfma_f32_16x16x32_bf16 v[36:39], v[166:169], v[190:193], v[36:39]
	v_mfma_f32_16x16x32_bf16 v[32:35], v[174:177], v[190:193], v[32:35]
	v_mfma_f32_16x16x32_bf16 v[20:23], v[166:169], v[198:201], v[20:23]
	v_mfma_f32_16x16x32_bf16 v[16:19], v[174:177], v[198:201], v[16:19]
	v_mfma_f32_16x16x32_bf16 v[4:7], v[166:169], v[206:209], v[4:7]
	v_mfma_f32_16x16x32_bf16 v[0:3], v[174:177], v[206:209], v[0:3]
	s_setprio 0
	s_barrier
	s_add_i32 s53, s53, 2
	s_add_u32 s41, s41, 0x100
	s_addc_u32 s52, s52, 0
	s_cmp_gt_u32 s53, 61
	s_mov_b64 s[10:11], s[12:13]
	s_cbranch_scc0 .LBB0_1370
	s_and_b64 vcc, exec, s[28:29]
	s_cbranch_vccz .LBB0_1373
	s_barrier

; #define PG8_WAIT_V(n) asm volatile("s_waitcnt vmcnt(" #n ")" ::: "memory")
; #define PG8_WAIT_L(n) asm volatile("s_waitcnt lgkmcnt(" #n ")" ::: "memory")
; #define PG8_BAR __builtin_amdgcn_s_barrier()
; #define PG8_SCHED __builtin_amdgcn_sched_barrier(0)
;     ...
;         for (int t = 0; t < nt; t += 2) {
;             const bool last = (t == nt - 2);
;             const char* a1 = cA + (size_t)(t + 1) * kstep;
;             const char* a2 = last ? nA : cA + (size_t)(t + 2) * kstep; const char* b2 = last ? nB : cB + (size_t)(t + 2) * kstep;
;             const char* a3 = a2 + kstep; const char* b3 = b2 + kstep;
;             if (last && has_next) S.a_ready(nxt);
;             if constexpr (SP2) {
;             PG8_LDB(B0, 0, 0); PG8_LDB(B1, 0, 1); PG8_SCHED; PG8_LDA(At, 0, 0); PG8_STAGE(PG8_SA(1, 1), a1 + hstepA, voffA);
;             PG8_WAIT_V(8); PG8_WAIT_L(0); PG8_BAR; PG8_MMA(0, 0, At, B0); PG8_MMA(0, 1, At, B1); PG8_BAR; PG8_SCHED;
;             if constexpr (!HALFU) PG8_LDA(At, 0, 1); PG8_STAGE(PG8_SB(0, 0), b2, voffB); PG8_STAGE(PG8_SB(0, 1), b2 + hstep, voffB); PG8_STAGE(PG8_SA(0, 0), a2, voffA);
;             PG8_WAIT_V(8); PG8_WAIT_L(0); PG8_BAR; if constexpr (!HALFU) { PG8_MMA(1, 0, At, B0); PG8_MMA(1, 1, At, B1); } PG8_BAR; PG8_SCHED;
.LBB0_3426:
	s_sub_u32 s98, s28, 0x80000
	s_subb_u32 s99, s29, 0
	s_mov_b32 m0, s50
	s_nop 0
	global_load_lds_dwordx4 v128, s[98:99]
	s_mov_b32 m0, s51
	s_nop 0
	global_load_lds_dwordx4 v130, s[98:99]
	s_cmp_eq_u32 s62, 28
	s_cselect_b32 s38, s55, s57
	s_cselect_b32 s39, s23, s59
	s_cselect_b32 s36, s56, s60
	s_cselect_b32 s37, s21, s61
	s_add_u32 s30, s38, 0x80
	s_addc_u32 s31, s39, 0
	s_add_i32 m0, s43, 0xc000
	s_nop 0
	global_load_lds_dwordx4 v128, s[28:29]
	s_add_i32 m0, s43, 0xe000
	s_nop 0
	global_load_lds_dwordx4 v130, s[28:29]
	ds_read_b128 v[142:145], v137
	ds_read_b128 v[146:149], v137 offset:1024
	ds_read_b128 v[150:153], v137 offset:2048
	ds_read_b128 v[154:157], v137 offset:3072
	ds_read_b128 v[158:161], v138
	ds_read_b128 v[162:165], v138 offset:1024
	ds_read_b128 v[166:169], v138 offset:2048
	ds_read_b128 v[170:173], v138 offset:3072
	ds_read_b128 v[174:177], v139
	ds_read_b128 v[178:181], v139 offset:1024
	ds_read_b128 v[182:185], v139 offset:2048
	ds_read_b128 v[186:189], v139 offset:3072
	ds_read_b128 v[190:193], v139 offset:4096
	ds_read_b128 v[194:197], v139 offset:5120
	ds_read_b128 v[198:201], v139 offset:6144
	ds_read_b128 v[202:205], v139 offset:7168
	s_waitcnt vmcnt(8)
	s_waitcnt lgkmcnt(0)
	s_barrier
	s_setprio 1
	s_waitcnt lgkmcnt(0)
	v_mfma_scale_f32_16x16x128_f8f6f4 v[124:127], v[142:149], v[174:181], v[124:127], v140, v140 op_sel_hi:[0,0,0]
	v_mfma_scale_f32_16x16x128_f8f6f4 v[120:123], v[150:157], v[174:181], v[120:123], v140, v140 op_sel_hi:[0,0,0]
	v_mfma_scale_f32_16x16x128_f8f6f4 v[112:115], v[142:149], v[182:189], v[112:115], v140, v140 op_sel_hi:[0,0,0]
	v_mfma_scale_f32_16x16x128_f8f6f4 v[104:107], v[150:157], v[182:189], v[104:107], v140, v140 op_sel_hi:[0,0,0]
	v_mfma_scale_f32_16x16x128_f8f6f4 v[96:99], v[142:149], v[190:197], v[96:99], v140, v140 op_sel_hi:[0,0,0]
	v_mfma_scale_f32_16x16x128_f8f6f4 v[206:209], v[150:157], v[190:197], v[88:91], v140, v140 op_sel_hi:[0,0,0]
	v_mfma_scale_f32_16x16x128_f8f6f4 v[210:213], v[142:149], v[198:205], v[80:83], v140, v140 op_sel_hi:[0,0,0]
	v_mfma_scale_f32_16x16x128_f8f6f4 v[214:217], v[150:157], v[198:205], v[72:75], v140, v140 op_sel_hi:[0,0,0]
	s_setprio 0
	s_setprio 1
	v_mfma_scale_f32_16x16x128_f8f6f4 v[116:119], v[158:165], v[174:181], v[116:119], v140, v140 op_sel_hi:[0,0,0]
	v_mfma_scale_f32_16x16x128_f8f6f4 v[108:111], v[166:173], v[174:181], v[108:111], v140, v140 op_sel_hi:[0,0,0]
	v_mfma_scale_f32_16x16x128_f8f6f4 v[100:103], v[158:165], v[182:189], v[100:103], v140, v140 op_sel_hi:[0,0,0]
	v_mfma_scale_f32_16x16x128_f8f6f4 v[174:177], v[166:173], v[182:189], v[92:95], v140, v140 op_sel_hi:[0,0,0]
	v_mfma_scale_f32_16x16x128_f8f6f4 v[178:181], v[158:165], v[190:197], v[84:87], v140, v140 op_sel_hi:[0,0,0]
	v_mfma_scale_f32_16x16x128_f8f6f4 v[182:185], v[166:173], v[190:197], v[76:79], v140, v140 op_sel_hi:[0,0,0]
	v_mfma_scale_f32_16x16x128_f8f6f4 v[186:189], v[158:165], v[198:205], v[68:71], v140, v140 op_sel_hi:[0,0,0]
	v_mfma_scale_f32_16x16x128_f8f6f4 v[190:193], v[166:173], v[198:205], v[64:67], v140, v140 op_sel_hi:[0,0,0]
	s_setprio 0
	s_barrier
	s_add_i32 s63, s53, s41
	s_mov_b32 m0, s63
	s_nop 1
	global_load_lds_dwordx4 v128, s[36:37]
	s_add_i32 m0, s63, 0x2000
	s_add_u32 s64, s36, 0x80000
	s_addc_u32 s65, s37, 0
	s_add_i32 s63, s54, s41
	global_load_lds_dwordx4 v130, s[36:37]
	s_mov_b32 m0, s63
	s_nop 0
	global_load_lds_dwordx4 v128, s[64:65]
	s_add_i32 m0, s63, 0x2000
	s_nop 0
	global_load_lds_dwordx4 v130, s[64:65]
	ds_read_b128 v[64:67], v139 offset:16384
	ds_read_b128 v[68:71], v139 offset:17408
	ds_read_b128 v[72:75], v139 offset:18432
	ds_read_b128 v[76:79], v139 offset:19456
	ds_read_b128 v[80:83], v139 offset:20480
	ds_read_b128 v[84:87], v139 offset:21504
	ds_read_b128 v[88:91], v139 offset:22528
	ds_read_b128 v[92:95], v139 offset:23552
	s_waitcnt vmcnt(4)
	s_waitcnt lgkmcnt(0)
	s_barrier
	s_setprio 1
	s_waitcnt lgkmcnt(0)
	v_mfma_scale_f32_16x16x128_f8f6f4 v[60:63], v[142:149], v[64:71], v[60:63], v140, v140 op_sel_hi:[0,0,0]
	v_mfma_scale_f32_16x16x128_f8f6f4 v[56:59], v[150:157], v[64:71], v[56:59], v140, v140 op_sel_hi:[0,0,0]
	v_mfma_scale_f32_16x16x128_f8f6f4 v[48:51], v[142:149], v[72:79], v[48:51], v140, v140 op_sel_hi:[0,0,0]
	v_mfma_scale_f32_16x16x128_f8f6f4 v[194:197], v[150:157], v[72:79], v[40:43], v140, v140 op_sel_hi:[0,0,0]
	v_mfma_scale_f32_16x16x128_f8f6f4 v[198:201], v[142:149], v[80:87], v[32:35], v140, v140 op_sel_hi:[0,0,0]
	v_mfma_scale_f32_16x16x128_f8f6f4 v[202:205], v[150:157], v[80:87], v[24:27], v140, v140 op_sel_hi:[0,0,0]
	v_mfma_scale_f32_16x16x128_f8f6f4 v[218:221], v[142:149], v[88:95], v[16:19], v140, v140 op_sel_hi:[0,0,0]
	v_mfma_scale_f32_16x16x128_f8f6f4 v[222:225], v[150:157], v[88:95], v[8:11], v140, v140 op_sel_hi:[0,0,0]
	s_setprio 0
	s_setprio 1
	v_mfma_scale_f32_16x16x128_f8f6f4 v[52:55], v[158:165], v[64:71], v[52:55], v140, v140 op_sel_hi:[0,0,0]
	v_mfma_scale_f32_16x16x128_f8f6f4 v[226:229], v[166:173], v[64:71], v[44:47], v140, v140 op_sel_hi:[0,0,0]
	v_mfma_scale_f32_16x16x128_f8f6f4 v[230:233], v[158:165], v[72:79], v[36:39], v140, v140 op_sel_hi:[0,0,0]
	v_mfma_scale_f32_16x16x128_f8f6f4 v[234:237], v[166:173], v[72:79], v[28:31], v140, v140 op_sel_hi:[0,0,0]
	v_mfma_scale_f32_16x16x128_f8f6f4 v[238:241], v[158:165], v[80:87], v[20:23], v140, v140 op_sel_hi:[0,0,0]
	v_mfma_scale_f32_16x16x128_f8f6f4 v[242:245], v[166:173], v[80:87], v[12:15], v140, v140 op_sel_hi:[0,0,0]
	v_mfma_scale_f32_16x16x128_f8f6f4 v[246:249], v[158:165], v[88:95], v[4:7], v140, v140 op_sel_hi:[0,0,0]
	v_mfma_scale_f32_16x16x128_f8f6f4 v[250:253], v[166:173], v[88:95], v[0:3], v140, v140 op_sel_hi:[0,0,0]
	s_setprio 0
	s_barrier
; #define PG8_WAIT_V(n) asm volatile("s_waitcnt vmcnt(" #n ")" ::: "memory")
; #define PG8_WAIT_L(n) asm volatile("s_waitcnt lgkmcnt(" #n ")" ::: "memory")
; #define PG8_BAR __builtin_amdgcn_s_barrier()
; #define PG8_SCHED __builtin_amdgcn_sched_barrier(0)
;     ...
;             PG8_LDB(B0, 1, 0); PG8_LDB(B1, 1, 1); PG8_SCHED; PG8_LDA(At, 1, 0); PG8_STAGE(PG8_SA(0, 1), a2 + hstepA, voffA);
;             PG8_WAIT_V(8); PG8_WAIT_L(0); PG8_BAR; PG8_MMA(0, 0, At, B0); PG8_MMA(0, 1, At, B1); PG8_BAR; PG8_SCHED;
;             if constexpr (!HALFU) PG8_LDA(At, 1, 1); PG8_STAGE(PG8_SB(1, 0), b3, voffB); PG8_STAGE(PG8_SB(1, 1), b3 + hstep, voffB); PG8_STAGE(PG8_SA(1, 0), a3, voffA);
;             PG8_WAIT_V(8); PG8_WAIT_L(0); PG8_BAR; if constexpr (!HALFU) { PG8_MMA(1, 0, At, B0); PG8_MMA(1, 1, At, B1); } PG8_BAR; PG8_SCHED;
	s_mov_b32 m0, s43
	s_nop 0
	global_load_lds_dwordx4 v128, s[38:39]
	s_mov_b32 m0, s44
	s_nop 0
	global_load_lds_dwordx4 v130, s[38:39]
	s_add_i32 s63, 0, 0x18000
	s_add_i32 s64, 0, 0x1c000
	s_nop 0
	s_add_u32 s38, s38, 0x80000
	s_addc_u32 s39, s39, 0
	s_mov_b32 m0, s45
	s_nop 0
	global_load_lds_dwordx4 v128, s[38:39]
	s_mov_b32 m0, s46
	s_nop 0
	global_load_lds_dwordx4 v130, s[38:39]
	v_add_u32_e32 v12, s63, v136
	v_add_u32_e32 v16, s64, v136
	ds_read_b128 v[0:3], v12
	ds_read_b128 v[4:7], v12 offset:1024
	ds_read_b128 v[8:11], v12 offset:2048
	ds_read_b128 v[12:15], v12 offset:3072
	ds_read_b128 v[142:145], v16
	ds_read_b128 v[146:149], v16 offset:1024
	ds_read_b128 v[150:153], v16 offset:2048
	ds_read_b128 v[154:157], v16 offset:3072
	ds_read_b128 v[16:19], v139 offset:32768
	ds_read_b128 v[20:23], v139 offset:33792
	ds_read_b128 v[24:27], v139 offset:34816
	ds_read_b128 v[28:31], v139 offset:35840
	ds_read_b128 v[32:35], v139 offset:36864
	ds_read_b128 v[36:39], v139 offset:37888
	ds_read_b128 v[40:43], v139 offset:38912
	ds_read_b128 v[44:47], v139 offset:39936
	s_waitcnt vmcnt(8)
	s_waitcnt lgkmcnt(0)
	s_barrier
	s_setprio 1
	s_waitcnt lgkmcnt(0)
	v_mfma_scale_f32_16x16x128_f8f6f4 v[124:127], v[0:7], v[16:23], v[124:127], v140, v140 op_sel_hi:[0,0,0]
	v_mfma_scale_f32_16x16x128_f8f6f4 v[120:123], v[8:15], v[16:23], v[120:123], v140, v140 op_sel_hi:[0,0,0]
	v_mfma_scale_f32_16x16x128_f8f6f4 v[112:115], v[0:7], v[24:31], v[112:115], v140, v140 op_sel_hi:[0,0,0]
	v_mfma_scale_f32_16x16x128_f8f6f4 v[104:107], v[8:15], v[24:31], v[104:107], v140, v140 op_sel_hi:[0,0,0]
	v_mfma_scale_f32_16x16x128_f8f6f4 v[96:99], v[0:7], v[32:39], v[96:99], v140, v140 op_sel_hi:[0,0,0]
	v_mfma_scale_f32_16x16x128_f8f6f4 v[88:91], v[8:15], v[32:39], v[206:209], v140, v140 op_sel_hi:[0,0,0]
	v_mfma_scale_f32_16x16x128_f8f6f4 v[80:83], v[0:7], v[40:47], v[210:213], v140, v140 op_sel_hi:[0,0,0]
	v_mfma_scale_f32_16x16x128_f8f6f4 v[72:75], v[8:15], v[40:47], v[214:217], v140, v140 op_sel_hi:[0,0,0]
	s_setprio 0
	s_setprio 1
	v_mfma_scale_f32_16x16x128_f8f6f4 v[116:119], v[142:149], v[16:23], v[116:119], v140, v140 op_sel_hi:[0,0,0]
	v_mfma_scale_f32_16x16x128_f8f6f4 v[108:111], v[150:157], v[16:23], v[108:111], v140, v140 op_sel_hi:[0,0,0]
	v_mfma_scale_f32_16x16x128_f8f6f4 v[100:103], v[142:149], v[24:31], v[100:103], v140, v140 op_sel_hi:[0,0,0]
	v_mfma_scale_f32_16x16x128_f8f6f4 v[92:95], v[150:157], v[24:31], v[174:177], v140, v140 op_sel_hi:[0,0,0]
	v_mfma_scale_f32_16x16x128_f8f6f4 v[84:87], v[142:149], v[32:39], v[178:181], v140, v140 op_sel_hi:[0,0,0]
	v_mfma_scale_f32_16x16x128_f8f6f4 v[76:79], v[150:157], v[32:39], v[182:185], v140, v140 op_sel_hi:[0,0,0]
	v_mfma_scale_f32_16x16x128_f8f6f4 v[68:71], v[142:149], v[40:47], v[186:189], v140, v140 op_sel_hi:[0,0,0]
	v_mfma_scale_f32_16x16x128_f8f6f4 v[64:67], v[150:157], v[40:47], v[190:193], v140, v140 op_sel_hi:[0,0,0]
	s_setprio 0
	s_barrier
	s_add_u32 s38, s36, 0x80
	s_addc_u32 s39, s37, 0
	s_add_i32 s63, s63, s41
	s_mov_b32 m0, s63
	ds_read_b128 v[158:161], v139 offset:49152
	ds_read_b128 v[162:165], v139 offset:50176
	ds_read_b128 v[166:169], v139 offset:51200
	ds_read_b128 v[170:173], v139 offset:52224
	ds_read_b128 v[174:177], v139 offset:53248
	ds_read_b128 v[178:181], v139 offset:54272
	ds_read_b128 v[182:185], v139 offset:55296
	ds_read_b128 v[186:189], v139 offset:56320
	global_load_lds_dwordx4 v128, s[38:39]
	s_add_i32 m0, s63, 0x2000
	s_add_u32 s36, s36, 0x80080
	v_lshl_add_u64 v[16:17], s[38:39], 0, v[130:131]
	s_addc_u32 s37, s37, 0
	s_add_i32 s38, s64, s41
	global_load_lds_dwordx4 v[16:17], off
	s_mov_b32 m0, s38
	s_nop 0
	global_load_lds_dwordx4 v128, s[36:37]
	s_add_i32 m0, s38, 0x2000
	s_nop 0
	global_load_lds_dwordx4 v130, s[36:37]
	s_waitcnt vmcnt(4)
	s_waitcnt lgkmcnt(0)
	s_barrier
	s_setprio 1
	s_waitcnt lgkmcnt(0)
	v_mfma_scale_f32_16x16x128_f8f6f4 v[60:63], v[0:7], v[158:165], v[60:63], v140, v140 op_sel_hi:[0,0,0]
	v_mfma_scale_f32_16x16x128_f8f6f4 v[56:59], v[8:15], v[158:165], v[56:59], v140, v140 op_sel_hi:[0,0,0]
	v_mfma_scale_f32_16x16x128_f8f6f4 v[48:51], v[0:7], v[166:173], v[48:51], v140, v140 op_sel_hi:[0,0,0]
	v_mfma_scale_f32_16x16x128_f8f6f4 v[40:43], v[8:15], v[166:173], v[194:197], v140, v140 op_sel_hi:[0,0,0]
	v_mfma_scale_f32_16x16x128_f8f6f4 v[32:35], v[0:7], v[174:181], v[198:201], v140, v140 op_sel_hi:[0,0,0]
	v_mfma_scale_f32_16x16x128_f8f6f4 v[24:27], v[8:15], v[174:181], v[202:205], v140, v140 op_sel_hi:[0,0,0]
	v_mfma_scale_f32_16x16x128_f8f6f4 v[16:19], v[0:7], v[182:189], v[218:221], v140, v140 op_sel_hi:[0,0,0]
	v_mfma_scale_f32_16x16x128_f8f6f4 v[8:11], v[8:15], v[182:189], v[222:225], v140, v140 op_sel_hi:[0,0,0]
	s_setprio 0
	s_setprio 1
	v_mfma_scale_f32_16x16x128_f8f6f4 v[52:55], v[142:149], v[158:165], v[52:55], v140, v140 op_sel_hi:[0,0,0]
	v_mfma_scale_f32_16x16x128_f8f6f4 v[44:47], v[150:157], v[158:165], v[226:229], v140, v140 op_sel_hi:[0,0,0]
	v_mfma_scale_f32_16x16x128_f8f6f4 v[36:39], v[142:149], v[166:173], v[230:233], v140, v140 op_sel_hi:[0,0,0]
	v_mfma_scale_f32_16x16x128_f8f6f4 v[28:31], v[150:157], v[166:173], v[234:237], v140, v140 op_sel_hi:[0,0,0]
	v_mfma_scale_f32_16x16x128_f8f6f4 v[20:23], v[142:149], v[174:181], v[238:241], v140, v140 op_sel_hi:[0,0,0]
	v_mfma_scale_f32_16x16x128_f8f6f4 v[12:15], v[150:157], v[174:181], v[242:245], v140, v140 op_sel_hi:[0,0,0]
	v_mfma_scale_f32_16x16x128_f8f6f4 v[4:7], v[142:149], v[182:189], v[246:249], v140, v140 op_sel_hi:[0,0,0]
	v_mfma_scale_f32_16x16x128_f8f6f4 v[0:3], v[150:157], v[182:189], v[250:253], v140, v140 op_sel_hi:[0,0,0]
	s_setprio 0
	s_barrier
	s_add_i32 s62, s62, 2
	s_add_u32 s57, s57, 0x100
	s_addc_u32 s59, s59, 0
	s_add_u32 s60, s60, 0x100
	s_addc_u32 s61, s61, 0
	s_add_u32 s28, s28, 0x100
	s_addc_u32 s29, s29, 0
	s_cmp_gt_u32 s62, 29
	s_cbranch_scc0 .LBB0_3426
	s_and_b64 vcc, exec, s[6:7]
	s_cbranch_vccz .LBB0_3429
	s_barrier

; #define PG8_WAIT_V(n) asm volatile("s_waitcnt vmcnt(" #n ")" ::: "memory")
; #define PG8_WAIT_L(n) asm volatile("s_waitcnt lgkmcnt(" #n ")" ::: "memory")
; #define PG8_BAR __builtin_amdgcn_s_barrier()
; #define PG8_SCHED __builtin_amdgcn_sched_barrier(0)
;     ...
;         for (int t = 0; t < nt; t += 2) {
;             const bool last = (t == nt - 2);
;             const char* a1 = cA + (size_t)(t + 1) * kstep;
;             const char* a2 = last ? nA : cA + (size_t)(t + 2) * kstep; const char* b2 = last ? nB : cB + (size_t)(t + 2) * kstep;
;             const char* a3 = a2 + kstep; const char* b3 = b2 + kstep;
;             if (last && has_next) S.a_ready(nxt);
;             if constexpr (SP2) {
;             PG8_LDB(B0, 0, 0); PG8_LDB(B1, 0, 1); PG8_SCHED; PG8_LDA(At, 0, 0); PG8_STAGE(PG8_SA(1, 1), a1 + hstepA, voffA);
;             PG8_WAIT_V(8); PG8_WAIT_L(0); PG8_BAR; PG8_MMA(0, 0, At, B0); PG8_MMA(0, 1, At, B1); PG8_BAR; PG8_SCHED;
;             if constexpr (!HALFU) PG8_LDA(At, 0, 1); PG8_STAGE(PG8_SB(0, 0), b2, voffB); PG8_STAGE(PG8_SB(0, 1), b2 + hstep, voffB); PG8_STAGE(PG8_SA(0, 0), a2, voffA);
;             PG8_WAIT_V(8); PG8_WAIT_L(0); PG8_BAR; if constexpr (!HALFU) { PG8_MMA(1, 0, At, B0); PG8_MMA(1, 1, At, B1); } PG8_BAR; PG8_SCHED;
.LBB0_3554:
	s_add_u32 s98, s24, 0x80
	s_addc_u32 s99, s25, 0
	s_mov_b32 m0, s49
	s_nop 0
	global_load_lds_dwordx4 v134, s[98:99]
	s_mov_b32 m0, s50
	s_nop 0
	global_load_lds_dwordx4 v132, s[98:99]
	s_add_u32 s26, s24, 0x100
	s_addc_u32 s27, s25, 0
	s_cmp_eq_u32 s59, 60
	s_cselect_b32 s36, s54, s26
	s_cselect_b32 s37, s15, s27
	s_cselect_b32 s30, s55, s56
	s_cselect_b32 s31, s13, s57
	s_add_u32 s28, s36, 0x80
	s_addc_u32 s29, s37, 0
	s_add_u32 s24, s24, 0x100080
	s_addc_u32 s25, s25, 0
	s_add_i32 m0, s23, 0xc000
	s_nop 0
	global_load_lds_dwordx4 v134, s[24:25]
	s_add_i32 m0, s23, 0xe000
	s_nop 0
	global_load_lds_dwordx4 v132, s[24:25]
	ds_read_b128 v[144:147], v141
	ds_read_b128 v[148:151], v141 offset:1024
	ds_read_b128 v[152:155], v141 offset:2048
	ds_read_b128 v[156:159], v141 offset:3072
	ds_read_b128 v[160:163], v142
	ds_read_b128 v[164:167], v142 offset:1024
	ds_read_b128 v[168:171], v142 offset:2048
	ds_read_b128 v[172:175], v142 offset:3072
	ds_read_b128 v[176:179], v143
	ds_read_b128 v[180:183], v143 offset:1024
	ds_read_b128 v[184:187], v143 offset:2048
	ds_read_b128 v[188:191], v143 offset:3072
	ds_read_b128 v[192:195], v143 offset:4096
	ds_read_b128 v[196:199], v143 offset:5120
	ds_read_b128 v[200:203], v143 offset:6144
	ds_read_b128 v[204:207], v143 offset:7168
	s_waitcnt vmcnt(8)
	s_waitcnt lgkmcnt(0)
	s_barrier
	s_setprio 1
	s_waitcnt lgkmcnt(0)
	v_mfma_f32_16x16x32_bf16 v[124:127], v[144:147], v[176:179], v[124:127]
	v_mfma_f32_16x16x32_bf16 v[120:123], v[152:155], v[176:179], v[120:123]
	v_mfma_f32_16x16x32_bf16 v[108:111], v[144:147], v[184:187], v[108:111]
	v_mfma_f32_16x16x32_bf16 v[104:107], v[152:155], v[184:187], v[104:107]
	v_mfma_f32_16x16x32_bf16 v[92:95], v[144:147], v[192:195], v[92:95]
	v_mfma_f32_16x16x32_bf16 v[88:91], v[152:155], v[192:195], v[88:91]
	v_mfma_f32_16x16x32_bf16 v[76:79], v[144:147], v[200:203], v[76:79]
	v_mfma_f32_16x16x32_bf16 v[72:75], v[152:155], v[200:203], v[72:75]
	v_mfma_f32_16x16x32_bf16 v[124:127], v[148:151], v[180:183], v[124:127]
	v_mfma_f32_16x16x32_bf16 v[120:123], v[156:159], v[180:183], v[120:123]
	v_mfma_f32_16x16x32_bf16 v[108:111], v[148:151], v[188:191], v[108:111]
	v_mfma_f32_16x16x32_bf16 v[104:107], v[156:159], v[188:191], v[104:107]
	v_mfma_f32_16x16x32_bf16 v[92:95], v[148:151], v[196:199], v[92:95]
	v_mfma_f32_16x16x32_bf16 v[88:91], v[156:159], v[196:199], v[88:91]
	v_mfma_f32_16x16x32_bf16 v[76:79], v[148:151], v[204:207], v[76:79]
	v_mfma_f32_16x16x32_bf16 v[72:75], v[156:159], v[204:207], v[72:75]
	s_setprio 0
	s_setprio 1
	v_mfma_f32_16x16x32_bf16 v[116:119], v[160:163], v[176:179], v[116:119]
	v_mfma_f32_16x16x32_bf16 v[112:115], v[168:171], v[176:179], v[112:115]
	v_mfma_f32_16x16x32_bf16 v[100:103], v[160:163], v[184:187], v[100:103]
	v_mfma_f32_16x16x32_bf16 v[96:99], v[168:171], v[184:187], v[96:99]
	v_mfma_f32_16x16x32_bf16 v[84:87], v[160:163], v[192:195], v[84:87]
	v_mfma_f32_16x16x32_bf16 v[80:83], v[168:171], v[192:195], v[80:83]
	v_mfma_f32_16x16x32_bf16 v[68:71], v[160:163], v[200:203], v[68:71]
	v_mfma_f32_16x16x32_bf16 v[64:67], v[168:171], v[200:203], v[64:67]
	v_mfma_f32_16x16x32_bf16 v[116:119], v[164:167], v[180:183], v[116:119]
	v_mfma_f32_16x16x32_bf16 v[112:115], v[172:175], v[180:183], v[112:115]
	v_mfma_f32_16x16x32_bf16 v[100:103], v[164:167], v[188:191], v[100:103]
	v_mfma_f32_16x16x32_bf16 v[96:99], v[172:175], v[188:191], v[96:99]
	v_mfma_f32_16x16x32_bf16 v[84:87], v[164:167], v[196:199], v[84:87]
	v_mfma_f32_16x16x32_bf16 v[80:83], v[172:175], v[196:199], v[80:83]
	v_mfma_f32_16x16x32_bf16 v[68:71], v[164:167], v[204:207], v[68:71]
	v_mfma_f32_16x16x32_bf16 v[64:67], v[172:175], v[204:207], v[64:67]
	s_setprio 0
	s_barrier
	s_add_i32 s24, s6, s40
	s_mov_b32 m0, s24
	s_nop 0
	global_load_lds_dwordx4 v128, s[30:31]
	s_add_i32 m0, s24, 0x2000
	s_add_u32 s24, s30, 0x100000
	s_addc_u32 s25, s31, 0
	s_add_i32 s60, s51, s40
	global_load_lds_dwordx4 v130, s[30:31]
	s_mov_b32 m0, s60
	s_nop 0
	global_load_lds_dwordx4 v128, s[24:25]
	s_add_i32 m0, s60, 0x2000
	s_nop 0
	global_load_lds_dwordx4 v130, s[24:25]
	ds_read_b128 v[176:179], v143 offset:16384
	ds_read_b128 v[180:183], v143 offset:17408
	ds_read_b128 v[184:187], v143 offset:18432
	ds_read_b128 v[188:191], v143 offset:19456
	ds_read_b128 v[192:195], v143 offset:20480
	ds_read_b128 v[196:199], v143 offset:21504
	ds_read_b128 v[200:203], v143 offset:22528
	ds_read_b128 v[204:207], v143 offset:23552
	s_waitcnt vmcnt(4)
	s_waitcnt lgkmcnt(0)
	s_barrier
	s_setprio 1
	s_waitcnt lgkmcnt(0)
	v_mfma_f32_16x16x32_bf16 v[60:63], v[144:147], v[176:179], v[60:63]
	v_mfma_f32_16x16x32_bf16 v[56:59], v[152:155], v[176:179], v[56:59]
	v_mfma_f32_16x16x32_bf16 v[44:47], v[144:147], v[184:187], v[44:47]
	v_mfma_f32_16x16x32_bf16 v[40:43], v[152:155], v[184:187], v[40:43]
	v_mfma_f32_16x16x32_bf16 v[28:31], v[144:147], v[192:195], v[28:31]
	v_mfma_f32_16x16x32_bf16 v[24:27], v[152:155], v[192:195], v[24:27]
	v_mfma_f32_16x16x32_bf16 v[12:15], v[144:147], v[200:203], v[12:15]
	v_mfma_f32_16x16x32_bf16 v[8:11], v[152:155], v[200:203], v[8:11]
	v_mfma_f32_16x16x32_bf16 v[60:63], v[148:151], v[180:183], v[60:63]
	v_mfma_f32_16x16x32_bf16 v[56:59], v[156:159], v[180:183], v[56:59]
	v_mfma_f32_16x16x32_bf16 v[44:47], v[148:151], v[188:191], v[44:47]
	v_mfma_f32_16x16x32_bf16 v[40:43], v[156:159], v[188:191], v[40:43]
	v_mfma_f32_16x16x32_bf16 v[28:31], v[148:151], v[196:199], v[28:31]
	v_mfma_f32_16x16x32_bf16 v[24:27], v[156:159], v[196:199], v[24:27]
	v_mfma_f32_16x16x32_bf16 v[12:15], v[148:151], v[204:207], v[12:15]
	v_mfma_f32_16x16x32_bf16 v[8:11], v[156:159], v[204:207], v[8:11]
	s_setprio 0
	s_setprio 1
	v_mfma_f32_16x16x32_bf16 v[52:55], v[160:163], v[176:179], v[52:55]
	v_mfma_f32_16x16x32_bf16 v[48:51], v[168:171], v[176:179], v[48:51]
	v_mfma_f32_16x16x32_bf16 v[36:39], v[160:163], v[184:187], v[36:39]
	v_mfma_f32_16x16x32_bf16 v[32:35], v[168:171], v[184:187], v[32:35]
	v_mfma_f32_16x16x32_bf16 v[20:23], v[160:163], v[192:195], v[20:23]
	v_mfma_f32_16x16x32_bf16 v[16:19], v[168:171], v[192:195], v[16:19]
	v_mfma_f32_16x16x32_bf16 v[4:7], v[160:163], v[200:203], v[4:7]
	v_mfma_f32_16x16x32_bf16 v[0:3], v[168:171], v[200:203], v[0:3]
	v_mfma_f32_16x16x32_bf16 v[52:55], v[164:167], v[180:183], v[52:55]
	v_mfma_f32_16x16x32_bf16 v[48:51], v[172:175], v[180:183], v[48:51]
	v_mfma_f32_16x16x32_bf16 v[36:39], v[164:167], v[188:191], v[36:39]
	v_mfma_f32_16x16x32_bf16 v[32:35], v[172:175], v[188:191], v[32:35]
	v_mfma_f32_16x16x32_bf16 v[20:23], v[164:167], v[196:199], v[20:23]
	v_mfma_f32_16x16x32_bf16 v[16:19], v[172:175], v[196:199], v[16:19]
	v_mfma_f32_16x16x32_bf16 v[4:7], v[164:167], v[204:207], v[4:7]
	v_mfma_f32_16x16x32_bf16 v[0:3], v[172:175], v[204:207], v[0:3]
	s_setprio 0
	s_barrier
; #define PG8_WAIT_V(n) asm volatile("s_waitcnt vmcnt(" #n ")" ::: "memory")
; #define PG8_WAIT_L(n) asm volatile("s_waitcnt lgkmcnt(" #n ")" ::: "memory")
; #define PG8_BAR __builtin_amdgcn_s_barrier()
; #define PG8_SCHED __builtin_amdgcn_sched_barrier(0)
;     ...
;             PG8_LDB(B0, 1, 0); PG8_LDB(B1, 1, 1); PG8_SCHED; PG8_LDA(At, 1, 0); PG8_STAGE(PG8_SA(0, 1), a2 + hstepA, voffA);
;             PG8_WAIT_V(8); PG8_WAIT_L(0); PG8_BAR; PG8_MMA(0, 0, At, B0); PG8_MMA(0, 1, At, B1); PG8_BAR; PG8_SCHED;
;             if constexpr (!HALFU) PG8_LDA(At, 1, 1); PG8_STAGE(PG8_SB(1, 0), b3, voffB); PG8_STAGE(PG8_SB(1, 1), b3 + hstep, voffB); PG8_STAGE(PG8_SA(1, 0), a3, voffA);
;             PG8_WAIT_V(8); PG8_WAIT_L(0); PG8_BAR; if constexpr (!HALFU) { PG8_MMA(1, 0, At, B0); PG8_MMA(1, 1, At, B1); } PG8_BAR; PG8_SCHED;
	s_mov_b32 m0, s23
	s_nop 0
	global_load_lds_dwordx4 v134, s[36:37]
	s_mov_b32 m0, s43
	s_nop 0
	global_load_lds_dwordx4 v132, s[36:37]
	s_add_i32 s60, 0, 0x18000
	s_add_i32 s61, 0, 0x1c000
	s_add_u32 s24, s36, 0x100000
	s_addc_u32 s25, s37, 0
	s_mov_b32 m0, s44
	s_nop 0
	global_load_lds_dwordx4 v134, s[24:25]
	s_mov_b32 m0, s45
	s_nop 0
	global_load_lds_dwordx4 v132, s[24:25]
	v_add_u32_e32 v138, s60, v140
	ds_read_b128 v[144:147], v138
	ds_read_b128 v[148:151], v138 offset:1024
	ds_read_b128 v[152:155], v138 offset:2048
	ds_read_b128 v[156:159], v138 offset:3072
	v_add_u32_e32 v138, s61, v140
	ds_read_b128 v[160:163], v138
	ds_read_b128 v[164:167], v138 offset:1024
	ds_read_b128 v[168:171], v138 offset:2048
	ds_read_b128 v[172:175], v138 offset:3072
	ds_read_b128 v[176:179], v143 offset:32768
	ds_read_b128 v[180:183], v143 offset:33792
	ds_read_b128 v[184:187], v143 offset:34816
	ds_read_b128 v[188:191], v143 offset:35840
	ds_read_b128 v[192:195], v143 offset:36864
	ds_read_b128 v[196:199], v143 offset:37888
	ds_read_b128 v[200:203], v143 offset:38912
	ds_read_b128 v[204:207], v143 offset:39936
	s_waitcnt vmcnt(8)
	s_waitcnt lgkmcnt(0)
	s_barrier
	s_setprio 1
	s_waitcnt lgkmcnt(0)
	v_mfma_f32_16x16x32_bf16 v[124:127], v[144:147], v[176:179], v[124:127]
	v_mfma_f32_16x16x32_bf16 v[120:123], v[152:155], v[176:179], v[120:123]
	v_mfma_f32_16x16x32_bf16 v[108:111], v[144:147], v[184:187], v[108:111]
	v_mfma_f32_16x16x32_bf16 v[104:107], v[152:155], v[184:187], v[104:107]
	v_mfma_f32_16x16x32_bf16 v[92:95], v[144:147], v[192:195], v[92:95]
	v_mfma_f32_16x16x32_bf16 v[88:91], v[152:155], v[192:195], v[88:91]
	v_mfma_f32_16x16x32_bf16 v[76:79], v[144:147], v[200:203], v[76:79]
	v_mfma_f32_16x16x32_bf16 v[72:75], v[152:155], v[200:203], v[72:75]
	v_mfma_f32_16x16x32_bf16 v[124:127], v[148:151], v[180:183], v[124:127]
	v_mfma_f32_16x16x32_bf16 v[120:123], v[156:159], v[180:183], v[120:123]
	v_mfma_f32_16x16x32_bf16 v[108:111], v[148:151], v[188:191], v[108:111]
	v_mfma_f32_16x16x32_bf16 v[104:107], v[156:159], v[188:191], v[104:107]
	v_mfma_f32_16x16x32_bf16 v[92:95], v[148:151], v[196:199], v[92:95]
	v_mfma_f32_16x16x32_bf16 v[88:91], v[156:159], v[196:199], v[88:91]
	v_mfma_f32_16x16x32_bf16 v[76:79], v[148:151], v[204:207], v[76:79]
	v_mfma_f32_16x16x32_bf16 v[72:75], v[156:159], v[204:207], v[72:75]
	s_setprio 0
	s_setprio 1
	v_mfma_f32_16x16x32_bf16 v[116:119], v[160:163], v[176:179], v[116:119]
	v_mfma_f32_16x16x32_bf16 v[112:115], v[168:171], v[176:179], v[112:115]
	v_mfma_f32_16x16x32_bf16 v[100:103], v[160:163], v[184:187], v[100:103]
	v_mfma_f32_16x16x32_bf16 v[96:99], v[168:171], v[184:187], v[96:99]
	v_mfma_f32_16x16x32_bf16 v[84:87], v[160:163], v[192:195], v[84:87]
	v_mfma_f32_16x16x32_bf16 v[80:83], v[168:171], v[192:195], v[80:83]
	v_mfma_f32_16x16x32_bf16 v[68:71], v[160:163], v[200:203], v[68:71]
	v_mfma_f32_16x16x32_bf16 v[64:67], v[168:171], v[200:203], v[64:67]
	v_mfma_f32_16x16x32_bf16 v[116:119], v[164:167], v[180:183], v[116:119]
	v_mfma_f32_16x16x32_bf16 v[112:115], v[172:175], v[180:183], v[112:115]
	v_mfma_f32_16x16x32_bf16 v[100:103], v[164:167], v[188:191], v[100:103]
	v_mfma_f32_16x16x32_bf16 v[96:99], v[172:175], v[188:191], v[96:99]
	v_mfma_f32_16x16x32_bf16 v[84:87], v[164:167], v[196:199], v[84:87]
	v_mfma_f32_16x16x32_bf16 v[80:83], v[172:175], v[196:199], v[80:83]
	v_mfma_f32_16x16x32_bf16 v[68:71], v[164:167], v[204:207], v[68:71]
	v_mfma_f32_16x16x32_bf16 v[64:67], v[172:175], v[204:207], v[64:67]
	s_setprio 0
	s_barrier
	s_add_u32 s24, s30, 0x80
	s_addc_u32 s25, s31, 0
	s_add_i32 s36, s60, s40
	s_mov_b32 m0, s36
	ds_read_b128 v[176:179], v143 offset:49152
	ds_read_b128 v[180:183], v143 offset:50176
	ds_read_b128 v[184:187], v143 offset:51200
	ds_read_b128 v[188:191], v143 offset:52224
	ds_read_b128 v[192:195], v143 offset:53248
	ds_read_b128 v[196:199], v143 offset:54272
	ds_read_b128 v[200:203], v143 offset:55296
	ds_read_b128 v[204:207], v143 offset:56320
	global_load_lds_dwordx4 v128, s[24:25]
	s_add_i32 m0, s36, 0x2000
	v_lshl_add_u64 v[138:139], s[24:25], 0, v[130:131]
	s_add_u32 s24, s30, 0x100080
	s_addc_u32 s25, s31, 0
	s_add_i32 s30, s61, s40
	global_load_lds_dwordx4 v[138:139], off
	s_mov_b32 m0, s30
	s_nop 0
	global_load_lds_dwordx4 v128, s[24:25]
	s_add_i32 m0, s30, 0x2000
	s_nop 0
	global_load_lds_dwordx4 v130, s[24:25]
	s_waitcnt vmcnt(4)
	s_waitcnt lgkmcnt(0)
	s_barrier
	s_setprio 1
	s_waitcnt lgkmcnt(0)
	v_mfma_f32_16x16x32_bf16 v[60:63], v[144:147], v[176:179], v[60:63]
	v_mfma_f32_16x16x32_bf16 v[56:59], v[152:155], v[176:179], v[56:59]
	v_mfma_f32_16x16x32_bf16 v[44:47], v[144:147], v[184:187], v[44:47]
	v_mfma_f32_16x16x32_bf16 v[40:43], v[152:155], v[184:187], v[40:43]
	v_mfma_f32_16x16x32_bf16 v[28:31], v[144:147], v[192:195], v[28:31]
	v_mfma_f32_16x16x32_bf16 v[24:27], v[152:155], v[192:195], v[24:27]
	v_mfma_f32_16x16x32_bf16 v[12:15], v[144:147], v[200:203], v[12:15]
	v_mfma_f32_16x16x32_bf16 v[8:11], v[152:155], v[200:203], v[8:11]
	v_mfma_f32_16x16x32_bf16 v[60:63], v[148:151], v[180:183], v[60:63]
	v_mfma_f32_16x16x32_bf16 v[56:59], v[156:159], v[180:183], v[56:59]
	v_mfma_f32_16x16x32_bf16 v[44:47], v[148:151], v[188:191], v[44:47]
	v_mfma_f32_16x16x32_bf16 v[40:43], v[156:159], v[188:191], v[40:43]
	v_mfma_f32_16x16x32_bf16 v[28:31], v[148:151], v[196:199], v[28:31]
	v_mfma_f32_16x16x32_bf16 v[24:27], v[156:159], v[196:199], v[24:27]
	v_mfma_f32_16x16x32_bf16 v[12:15], v[148:151], v[204:207], v[12:15]
	v_mfma_f32_16x16x32_bf16 v[8:11], v[156:159], v[204:207], v[8:11]
	s_setprio 0
	s_setprio 1
	v_mfma_f32_16x16x32_bf16 v[52:55], v[160:163], v[176:179], v[52:55]
	v_mfma_f32_16x16x32_bf16 v[48:51], v[168:171], v[176:179], v[48:51]
	v_mfma_f32_16x16x32_bf16 v[36:39], v[160:163], v[184:187], v[36:39]
	v_mfma_f32_16x16x32_bf16 v[32:35], v[168:171], v[184:187], v[32:35]
	v_mfma_f32_16x16x32_bf16 v[20:23], v[160:163], v[192:195], v[20:23]
	v_mfma_f32_16x16x32_bf16 v[16:19], v[168:171], v[192:195], v[16:19]
	v_mfma_f32_16x16x32_bf16 v[4:7], v[160:163], v[200:203], v[4:7]
	v_mfma_f32_16x16x32_bf16 v[0:3], v[168:171], v[200:203], v[0:3]
	v_mfma_f32_16x16x32_bf16 v[52:55], v[164:167], v[180:183], v[52:55]
	v_mfma_f32_16x16x32_bf16 v[48:51], v[172:175], v[180:183], v[48:51]
	v_mfma_f32_16x16x32_bf16 v[36:39], v[164:167], v[188:191], v[36:39]
	v_mfma_f32_16x16x32_bf16 v[32:35], v[172:175], v[188:191], v[32:35]
	v_mfma_f32_16x16x32_bf16 v[20:23], v[164:167], v[196:199], v[20:23]
	v_mfma_f32_16x16x32_bf16 v[16:19], v[172:175], v[196:199], v[16:19]
	v_mfma_f32_16x16x32_bf16 v[4:7], v[164:167], v[204:207], v[4:7]
	v_mfma_f32_16x16x32_bf16 v[0:3], v[172:175], v[204:207], v[0:3]
	s_setprio 0
	s_barrier
	s_add_i32 s59, s59, 2
	s_add_u32 s56, s56, 0x100
	s_addc_u32 s57, s57, 0
	s_cmp_gt_u32 s59, 61
	s_mov_b64 s[24:25], s[26:27]
	s_cbranch_scc0 .LBB0_3554
	s_and_b64 vcc, exec, s[10:11]
	s_cbranch_vccz .LBB0_3557
	s_barrier

; #define PG8_WAIT_V(n) asm volatile("s_waitcnt vmcnt(" #n ")" ::: "memory")
; #define PG8_WAIT_L(n) asm volatile("s_waitcnt lgkmcnt(" #n ")" ::: "memory")
; #define PG8_BAR __builtin_amdgcn_s_barrier()
; #define PG8_SCHED __builtin_amdgcn_sched_barrier(0)
;     ...
;         for (int t = 0; t < nt; t += 2) {
;             const bool last = (t == nt - 2);
;             const char* a1 = cA + (size_t)(t + 1) * kstep;
;             const char* a2 = last ? nA : cA + (size_t)(t + 2) * kstep; const char* b2 = last ? nB : cB + (size_t)(t + 2) * kstep;
;             const char* a3 = a2 + kstep; const char* b3 = b2 + kstep;
;             if (last && has_next) S.a_ready(nxt);
;             if constexpr (SP2) {
;             PG8_LDB(B0, 0, 0); PG8_LDB(B1, 0, 1); PG8_SCHED; PG8_LDA(At, 0, 0); PG8_STAGE(PG8_SA(1, 1), a1 + hstepA, voffA);
;             PG8_WAIT_V(8); PG8_WAIT_L(0); PG8_BAR; PG8_MMA(0, 0, At, B0); PG8_MMA(0, 1, At, B1); PG8_BAR; PG8_SCHED;
;             if constexpr (!HALFU) PG8_LDA(At, 0, 1); PG8_STAGE(PG8_SB(0, 0), b2, voffB); PG8_STAGE(PG8_SB(0, 1), b2 + hstep, voffB); PG8_STAGE(PG8_SA(0, 0), a2, voffA);
;             PG8_WAIT_V(8); PG8_WAIT_L(0); PG8_BAR; if constexpr (!HALFU) { PG8_MMA(1, 0, At, B0); PG8_MMA(1, 1, At, B1); } PG8_BAR; PG8_SCHED;
.LBB0_3640:
	s_sub_u32 s98, s10, 0x158000
	s_subb_u32 s99, s11, 0
	s_mov_b32 m0, s42
	s_nop 0
	global_load_lds_dwordx4 v128, s[98:99]
	s_mov_b32 m0, s43
	s_nop 0
	global_load_lds_dwordx4 v130, s[98:99]
	s_cmpk_eq_i32 s55, 0x52
	s_cselect_b32 s28, s6, s51
	s_cselect_b32 s29, s7, s52
	s_cselect_b32 s26, s22, s53
	s_cselect_b32 s27, s23, s54
	s_add_u32 s24, s28, 0x80
	s_addc_u32 s25, s29, 0
	s_add_i32 m0, s33, 0xc000
	s_nop 0
	global_load_lds_dwordx4 v128, s[10:11]
	s_add_i32 m0, s33, 0xe000
	s_nop 0
	global_load_lds_dwordx4 v130, s[10:11]
	ds_read_b128 v[142:145], v137
	ds_read_b128 v[146:149], v137 offset:1024
	ds_read_b128 v[150:153], v137 offset:2048
	ds_read_b128 v[154:157], v137 offset:3072
	ds_read_b128 v[158:161], v138
	ds_read_b128 v[162:165], v138 offset:1024
	ds_read_b128 v[166:169], v138 offset:2048
	ds_read_b128 v[170:173], v138 offset:3072
	ds_read_b128 v[174:177], v139
	ds_read_b128 v[178:181], v139 offset:1024
	ds_read_b128 v[182:185], v139 offset:2048
	ds_read_b128 v[186:189], v139 offset:3072
	ds_read_b128 v[190:193], v139 offset:4096
	ds_read_b128 v[194:197], v139 offset:5120
	ds_read_b128 v[198:201], v139 offset:6144
	ds_read_b128 v[202:205], v139 offset:7168
	s_waitcnt vmcnt(8)
	s_waitcnt lgkmcnt(0)
	s_barrier
	s_setprio 1
	s_waitcnt lgkmcnt(0)
	v_mfma_scale_f32_16x16x128_f8f6f4 v[124:127], v[142:149], v[174:181], v[124:127], v140, v140 op_sel_hi:[0,0,0]
	v_mfma_scale_f32_16x16x128_f8f6f4 v[120:123], v[150:157], v[174:181], v[120:123], v140, v140 op_sel_hi:[0,0,0]
	v_mfma_scale_f32_16x16x128_f8f6f4 v[112:115], v[142:149], v[182:189], v[112:115], v140, v140 op_sel_hi:[0,0,0]
	v_mfma_scale_f32_16x16x128_f8f6f4 v[104:107], v[150:157], v[182:189], v[104:107], v140, v140 op_sel_hi:[0,0,0]
	v_mfma_scale_f32_16x16x128_f8f6f4 v[96:99], v[142:149], v[190:197], v[96:99], v140, v140 op_sel_hi:[0,0,0]
	v_mfma_scale_f32_16x16x128_f8f6f4 v[206:209], v[150:157], v[190:197], v[88:91], v140, v140 op_sel_hi:[0,0,0]
	v_mfma_scale_f32_16x16x128_f8f6f4 v[210:213], v[142:149], v[198:205], v[80:83], v140, v140 op_sel_hi:[0,0,0]
	v_mfma_scale_f32_16x16x128_f8f6f4 v[214:217], v[150:157], v[198:205], v[72:75], v140, v140 op_sel_hi:[0,0,0]
	s_setprio 0
	s_setprio 1
	v_mfma_scale_f32_16x16x128_f8f6f4 v[116:119], v[158:165], v[174:181], v[116:119], v140, v140 op_sel_hi:[0,0,0]
	v_mfma_scale_f32_16x16x128_f8f6f4 v[108:111], v[166:173], v[174:181], v[108:111], v140, v140 op_sel_hi:[0,0,0]
	v_mfma_scale_f32_16x16x128_f8f6f4 v[100:103], v[158:165], v[182:189], v[100:103], v140, v140 op_sel_hi:[0,0,0]
	v_mfma_scale_f32_16x16x128_f8f6f4 v[174:177], v[166:173], v[182:189], v[92:95], v140, v140 op_sel_hi:[0,0,0]
	v_mfma_scale_f32_16x16x128_f8f6f4 v[178:181], v[158:165], v[190:197], v[84:87], v140, v140 op_sel_hi:[0,0,0]
	v_mfma_scale_f32_16x16x128_f8f6f4 v[182:185], v[166:173], v[190:197], v[76:79], v140, v140 op_sel_hi:[0,0,0]
	v_mfma_scale_f32_16x16x128_f8f6f4 v[186:189], v[158:165], v[198:205], v[68:71], v140, v140 op_sel_hi:[0,0,0]
	v_mfma_scale_f32_16x16x128_f8f6f4 v[190:193], v[166:173], v[198:205], v[64:67], v140, v140 op_sel_hi:[0,0,0]
	s_setprio 0
	s_barrier
	s_add_i32 s56, s45, s30
	s_mov_b32 m0, s56
	s_nop 1
	global_load_lds_dwordx4 v128, s[26:27]
	s_add_i32 m0, s56, 0x2000
	s_add_u32 s56, s26, 0x158000
	s_addc_u32 s57, s27, 0
	s_add_i32 s58, s46, s30
	global_load_lds_dwordx4 v130, s[26:27]
	s_mov_b32 m0, s58
	s_nop 0
	global_load_lds_dwordx4 v128, s[56:57]
	s_add_i32 m0, s58, 0x2000
	s_nop 0
	global_load_lds_dwordx4 v130, s[56:57]
	ds_read_b128 v[64:67], v139 offset:16384
	ds_read_b128 v[68:71], v139 offset:17408
	ds_read_b128 v[72:75], v139 offset:18432
	ds_read_b128 v[76:79], v139 offset:19456
	ds_read_b128 v[80:83], v139 offset:20480
	ds_read_b128 v[84:87], v139 offset:21504
	ds_read_b128 v[88:91], v139 offset:22528
	ds_read_b128 v[92:95], v139 offset:23552
	s_waitcnt vmcnt(4)
	s_waitcnt lgkmcnt(0)
	s_barrier
	s_setprio 1
	s_waitcnt lgkmcnt(0)
	v_mfma_scale_f32_16x16x128_f8f6f4 v[60:63], v[142:149], v[64:71], v[60:63], v140, v140 op_sel_hi:[0,0,0]
	v_mfma_scale_f32_16x16x128_f8f6f4 v[56:59], v[150:157], v[64:71], v[56:59], v140, v140 op_sel_hi:[0,0,0]
	v_mfma_scale_f32_16x16x128_f8f6f4 v[48:51], v[142:149], v[72:79], v[48:51], v140, v140 op_sel_hi:[0,0,0]
	v_mfma_scale_f32_16x16x128_f8f6f4 v[194:197], v[150:157], v[72:79], v[40:43], v140, v140 op_sel_hi:[0,0,0]
	v_mfma_scale_f32_16x16x128_f8f6f4 v[198:201], v[142:149], v[80:87], v[32:35], v140, v140 op_sel_hi:[0,0,0]
	v_mfma_scale_f32_16x16x128_f8f6f4 v[202:205], v[150:157], v[80:87], v[24:27], v140, v140 op_sel_hi:[0,0,0]
	v_mfma_scale_f32_16x16x128_f8f6f4 v[218:221], v[142:149], v[88:95], v[16:19], v140, v140 op_sel_hi:[0,0,0]
	v_mfma_scale_f32_16x16x128_f8f6f4 v[222:225], v[150:157], v[88:95], v[8:11], v140, v140 op_sel_hi:[0,0,0]
	s_setprio 0
	s_setprio 1
	v_mfma_scale_f32_16x16x128_f8f6f4 v[52:55], v[158:165], v[64:71], v[52:55], v140, v140 op_sel_hi:[0,0,0]
	v_mfma_scale_f32_16x16x128_f8f6f4 v[226:229], v[166:173], v[64:71], v[44:47], v140, v140 op_sel_hi:[0,0,0]
	v_mfma_scale_f32_16x16x128_f8f6f4 v[230:233], v[158:165], v[72:79], v[36:39], v140, v140 op_sel_hi:[0,0,0]
	v_mfma_scale_f32_16x16x128_f8f6f4 v[234:237], v[166:173], v[72:79], v[28:31], v140, v140 op_sel_hi:[0,0,0]
	v_mfma_scale_f32_16x16x128_f8f6f4 v[238:241], v[158:165], v[80:87], v[20:23], v140, v140 op_sel_hi:[0,0,0]
	v_mfma_scale_f32_16x16x128_f8f6f4 v[242:245], v[166:173], v[80:87], v[12:15], v140, v140 op_sel_hi:[0,0,0]
	v_mfma_scale_f32_16x16x128_f8f6f4 v[246:249], v[158:165], v[88:95], v[4:7], v140, v140 op_sel_hi:[0,0,0]
	v_mfma_scale_f32_16x16x128_f8f6f4 v[250:253], v[166:173], v[88:95], v[0:3], v140, v140 op_sel_hi:[0,0,0]
	s_setprio 0
	s_barrier
; #define PG8_WAIT_V(n) asm volatile("s_waitcnt vmcnt(" #n ")" ::: "memory")
; #define PG8_WAIT_L(n) asm volatile("s_waitcnt lgkmcnt(" #n ")" ::: "memory")
; #define PG8_BAR __builtin_amdgcn_s_barrier()
; #define PG8_SCHED __builtin_amdgcn_sched_barrier(0)
;     ...
;             PG8_LDB(B0, 1, 0); PG8_LDB(B1, 1, 1); PG8_SCHED; PG8_LDA(At, 1, 0); PG8_STAGE(PG8_SA(0, 1), a2 + hstepA, voffA);
;             PG8_WAIT_V(8); PG8_WAIT_L(0); PG8_BAR; PG8_MMA(0, 0, At, B0); PG8_MMA(0, 1, At, B1); PG8_BAR; PG8_SCHED;
;             if constexpr (!HALFU) PG8_LDA(At, 1, 1); PG8_STAGE(PG8_SB(1, 0), b3, voffB); PG8_STAGE(PG8_SB(1, 1), b3 + hstep, voffB); PG8_STAGE(PG8_SA(1, 0), a3, voffA);
;             PG8_WAIT_V(8); PG8_WAIT_L(0); PG8_BAR; if constexpr (!HALFU) { PG8_MMA(1, 0, At, B0); PG8_MMA(1, 1, At, B1); } PG8_BAR; PG8_SCHED;
	s_mov_b32 m0, s33
	s_nop 0
	global_load_lds_dwordx4 v128, s[28:29]
	s_mov_b32 m0, s36
	s_nop 0
	global_load_lds_dwordx4 v130, s[28:29]
	s_add_i32 s56, 0, 0x18000
	s_add_i32 s57, 0, 0x1c000
	s_nop 0
	s_add_u32 s28, s28, 0x158000
	s_addc_u32 s29, s29, 0
	s_mov_b32 m0, s37
	s_nop 0
	global_load_lds_dwordx4 v128, s[28:29]
	s_mov_b32 m0, s38
	s_nop 0
	global_load_lds_dwordx4 v130, s[28:29]
	v_add_u32_e32 v12, s56, v136
	v_add_u32_e32 v16, s57, v136
	ds_read_b128 v[0:3], v12
	ds_read_b128 v[4:7], v12 offset:1024
	ds_read_b128 v[8:11], v12 offset:2048
	ds_read_b128 v[12:15], v12 offset:3072
	ds_read_b128 v[142:145], v16
	ds_read_b128 v[146:149], v16 offset:1024
	ds_read_b128 v[150:153], v16 offset:2048
	ds_read_b128 v[154:157], v16 offset:3072
	ds_read_b128 v[16:19], v139 offset:32768
	ds_read_b128 v[20:23], v139 offset:33792
	ds_read_b128 v[24:27], v139 offset:34816
	ds_read_b128 v[28:31], v139 offset:35840
	ds_read_b128 v[32:35], v139 offset:36864
	ds_read_b128 v[36:39], v139 offset:37888
	ds_read_b128 v[40:43], v139 offset:38912
	ds_read_b128 v[44:47], v139 offset:39936
	s_waitcnt vmcnt(8)
	s_waitcnt lgkmcnt(0)
	s_barrier
	s_setprio 1
	s_waitcnt lgkmcnt(0)
	v_mfma_scale_f32_16x16x128_f8f6f4 v[124:127], v[0:7], v[16:23], v[124:127], v140, v140 op_sel_hi:[0,0,0]
	v_mfma_scale_f32_16x16x128_f8f6f4 v[120:123], v[8:15], v[16:23], v[120:123], v140, v140 op_sel_hi:[0,0,0]
	v_mfma_scale_f32_16x16x128_f8f6f4 v[112:115], v[0:7], v[24:31], v[112:115], v140, v140 op_sel_hi:[0,0,0]
	v_mfma_scale_f32_16x16x128_f8f6f4 v[104:107], v[8:15], v[24:31], v[104:107], v140, v140 op_sel_hi:[0,0,0]
	v_mfma_scale_f32_16x16x128_f8f6f4 v[96:99], v[0:7], v[32:39], v[96:99], v140, v140 op_sel_hi:[0,0,0]
	v_mfma_scale_f32_16x16x128_f8f6f4 v[88:91], v[8:15], v[32:39], v[206:209], v140, v140 op_sel_hi:[0,0,0]
	v_mfma_scale_f32_16x16x128_f8f6f4 v[80:83], v[0:7], v[40:47], v[210:213], v140, v140 op_sel_hi:[0,0,0]
	v_mfma_scale_f32_16x16x128_f8f6f4 v[72:75], v[8:15], v[40:47], v[214:217], v140, v140 op_sel_hi:[0,0,0]
	s_setprio 0
	s_setprio 1
	v_mfma_scale_f32_16x16x128_f8f6f4 v[116:119], v[142:149], v[16:23], v[116:119], v140, v140 op_sel_hi:[0,0,0]
	v_mfma_scale_f32_16x16x128_f8f6f4 v[108:111], v[150:157], v[16:23], v[108:111], v140, v140 op_sel_hi:[0,0,0]
	v_mfma_scale_f32_16x16x128_f8f6f4 v[100:103], v[142:149], v[24:31], v[100:103], v140, v140 op_sel_hi:[0,0,0]
	v_mfma_scale_f32_16x16x128_f8f6f4 v[92:95], v[150:157], v[24:31], v[174:177], v140, v140 op_sel_hi:[0,0,0]
	v_mfma_scale_f32_16x16x128_f8f6f4 v[84:87], v[142:149], v[32:39], v[178:181], v140, v140 op_sel_hi:[0,0,0]
	v_mfma_scale_f32_16x16x128_f8f6f4 v[76:79], v[150:157], v[32:39], v[182:185], v140, v140 op_sel_hi:[0,0,0]
	v_mfma_scale_f32_16x16x128_f8f6f4 v[68:71], v[142:149], v[40:47], v[186:189], v140, v140 op_sel_hi:[0,0,0]
	v_mfma_scale_f32_16x16x128_f8f6f4 v[64:67], v[150:157], v[40:47], v[190:193], v140, v140 op_sel_hi:[0,0,0]
	s_setprio 0
	s_barrier
	s_add_u32 s28, s26, 0x80
	s_addc_u32 s29, s27, 0
	s_add_i32 s56, s56, s30
	s_mov_b32 m0, s56
	ds_read_b128 v[158:161], v139 offset:49152
	ds_read_b128 v[162:165], v139 offset:50176
	ds_read_b128 v[166:169], v139 offset:51200
	ds_read_b128 v[170:173], v139 offset:52224
	ds_read_b128 v[174:177], v139 offset:53248
	ds_read_b128 v[178:181], v139 offset:54272
	ds_read_b128 v[182:185], v139 offset:55296
	ds_read_b128 v[186:189], v139 offset:56320
	global_load_lds_dwordx4 v128, s[28:29]
	s_add_i32 m0, s56, 0x2000
	s_add_u32 s26, s26, 0x158080
	v_lshl_add_u64 v[16:17], s[28:29], 0, v[130:131]
	s_addc_u32 s27, s27, 0
	s_add_i32 s28, s57, s30
	global_load_lds_dwordx4 v[16:17], off
	s_mov_b32 m0, s28
	s_nop 0
	global_load_lds_dwordx4 v128, s[26:27]
	s_add_i32 m0, s28, 0x2000
	s_nop 0
	global_load_lds_dwordx4 v130, s[26:27]
	s_waitcnt vmcnt(4)
	s_waitcnt lgkmcnt(0)
	s_barrier
	s_setprio 1
	s_waitcnt lgkmcnt(0)
	v_mfma_scale_f32_16x16x128_f8f6f4 v[60:63], v[0:7], v[158:165], v[60:63], v140, v140 op_sel_hi:[0,0,0]
	v_mfma_scale_f32_16x16x128_f8f6f4 v[56:59], v[8:15], v[158:165], v[56:59], v140, v140 op_sel_hi:[0,0,0]
	v_mfma_scale_f32_16x16x128_f8f6f4 v[48:51], v[0:7], v[166:173], v[48:51], v140, v140 op_sel_hi:[0,0,0]
	v_mfma_scale_f32_16x16x128_f8f6f4 v[40:43], v[8:15], v[166:173], v[194:197], v140, v140 op_sel_hi:[0,0,0]
	v_mfma_scale_f32_16x16x128_f8f6f4 v[32:35], v[0:7], v[174:181], v[198:201], v140, v140 op_sel_hi:[0,0,0]
	v_mfma_scale_f32_16x16x128_f8f6f4 v[24:27], v[8:15], v[174:181], v[202:205], v140, v140 op_sel_hi:[0,0,0]
	v_mfma_scale_f32_16x16x128_f8f6f4 v[16:19], v[0:7], v[182:189], v[218:221], v140, v140 op_sel_hi:[0,0,0]
	v_mfma_scale_f32_16x16x128_f8f6f4 v[8:11], v[8:15], v[182:189], v[222:225], v140, v140 op_sel_hi:[0,0,0]
	s_setprio 0
	s_setprio 1
	v_mfma_scale_f32_16x16x128_f8f6f4 v[52:55], v[142:149], v[158:165], v[52:55], v140, v140 op_sel_hi:[0,0,0]
	v_mfma_scale_f32_16x16x128_f8f6f4 v[44:47], v[150:157], v[158:165], v[226:229], v140, v140 op_sel_hi:[0,0,0]
	v_mfma_scale_f32_16x16x128_f8f6f4 v[36:39], v[142:149], v[166:173], v[230:233], v140, v140 op_sel_hi:[0,0,0]
	v_mfma_scale_f32_16x16x128_f8f6f4 v[28:31], v[150:157], v[166:173], v[234:237], v140, v140 op_sel_hi:[0,0,0]
	v_mfma_scale_f32_16x16x128_f8f6f4 v[20:23], v[142:149], v[174:181], v[238:241], v140, v140 op_sel_hi:[0,0,0]
	v_mfma_scale_f32_16x16x128_f8f6f4 v[12:15], v[150:157], v[174:181], v[242:245], v140, v140 op_sel_hi:[0,0,0]
	v_mfma_scale_f32_16x16x128_f8f6f4 v[4:7], v[142:149], v[182:189], v[246:249], v140, v140 op_sel_hi:[0,0,0]
	v_mfma_scale_f32_16x16x128_f8f6f4 v[0:3], v[150:157], v[182:189], v[250:253], v140, v140 op_sel_hi:[0,0,0]
	s_setprio 0
	s_barrier
	s_add_i32 s55, s55, 2
	s_add_u32 s51, s51, 0x100
	s_addc_u32 s52, s52, 0
	s_add_u32 s53, s53, 0x100
	s_addc_u32 s54, s54, 0
	s_add_u32 s10, s10, 0x100
	s_addc_u32 s11, s11, 0
	s_cmpk_gt_u32 s55, 0x53
	s_cbranch_scc0 .LBB0_3640
	s_and_b64 vcc, exec, s[12:13]
	s_cbranch_vccz .LBB0_3643
	s_barrier
